# v15 with the mid-segment s_setprio 0/1 flip pair deleted between the two 16-MFMA blocks of every 8-phase K-loop stage (60 sites)
# speedup vs baseline: 1.0048x; 1.0048x over previous
.LBB0_285:
	ds_read_b128 v[154:157], v151
	ds_read_b128 v[158:161], v151 offset:1024
	ds_read_b128 v[164:167], v151 offset:2048
	ds_read_b128 v[168:171], v151 offset:3072
	ds_read_b128 v[172:175], v152
	ds_read_b128 v[176:179], v152 offset:1024
	ds_read_b128 v[180:183], v152 offset:2048
	ds_read_b128 v[184:187], v152 offset:3072
	s_add_u32 s36, s34, 0xfff80080
	s_addc_u32 s37, s35, -1
	s_cmp_eq_u32 s53, 28
	s_cselect_b32 s39, s16, s37
	s_cselect_b32 s38, s17, s36
	s_cselect_b32 s37, s18, s25
	s_cselect_b32 s36, s19, s23
	v_lshl_add_u64 v[146:147], s[34:35], 0, v[138:139]
	s_add_i32 m0, s31, 0xc000
	ds_read_b128 v[188:191], v153
	ds_read_b128 v[192:195], v153 offset:1024
	ds_read_b128 v[196:199], v153 offset:2048
	ds_read_b128 v[200:203], v153 offset:3072
	ds_read_b128 v[204:207], v153 offset:4096
	ds_read_b128 v[208:211], v153 offset:5120
	ds_read_b128 v[212:215], v153 offset:6144
	ds_read_b128 v[216:219], v153 offset:7168
	global_load_lds_dwordx4 v[146:147], off
	v_lshl_add_u64 v[146:147], s[34:35], 0, v[140:141]
	s_add_i32 m0, s31, 0xe000
	s_nop 0
	global_load_lds_dwordx4 v[146:147], off
	s_waitcnt vmcnt(8)
	s_waitcnt lgkmcnt(0)
	s_waitcnt lgkmcnt(0)
	v_mfma_f32_16x16x32_bf16 v[126:129], v[154:157], v[188:191], v[126:129]
	v_mfma_f32_16x16x32_bf16 v[122:125], v[164:167], v[188:191], v[122:125]
	v_mfma_f32_16x16x32_bf16 v[110:113], v[154:157], v[196:199], v[110:113]
	v_mfma_f32_16x16x32_bf16 v[106:109], v[164:167], v[196:199], v[106:109]
	s_barrier
	s_setprio 1
	v_mfma_f32_16x16x32_bf16 v[94:97], v[154:157], v[204:207], v[94:97]
	v_mfma_f32_16x16x32_bf16 v[90:93], v[164:167], v[204:207], v[90:93]
	v_mfma_f32_16x16x32_bf16 v[78:81], v[154:157], v[212:215], v[78:81]
	v_mfma_f32_16x16x32_bf16 v[74:77], v[164:167], v[212:215], v[74:77]
	v_mfma_f32_16x16x32_bf16 v[126:129], v[158:161], v[192:195], v[126:129]
	v_mfma_f32_16x16x32_bf16 v[122:125], v[168:171], v[192:195], v[122:125]
	v_mfma_f32_16x16x32_bf16 v[110:113], v[158:161], v[200:203], v[110:113]
	v_mfma_f32_16x16x32_bf16 v[106:109], v[168:171], v[200:203], v[106:109]
	v_mfma_f32_16x16x32_bf16 v[94:97], v[158:161], v[208:211], v[94:97]
	v_mfma_f32_16x16x32_bf16 v[90:93], v[168:171], v[208:211], v[90:93]
	v_mfma_f32_16x16x32_bf16 v[78:81], v[158:161], v[216:219], v[78:81]
	v_mfma_f32_16x16x32_bf16 v[74:77], v[168:171], v[216:219], v[74:77]
	v_mfma_f32_16x16x32_bf16 v[118:121], v[172:175], v[188:191], v[118:121]
	v_mfma_f32_16x16x32_bf16 v[114:117], v[180:183], v[188:191], v[114:117]
	v_mfma_f32_16x16x32_bf16 v[102:105], v[172:175], v[196:199], v[102:105]
	v_mfma_f32_16x16x32_bf16 v[98:101], v[180:183], v[196:199], v[98:101]
	v_mfma_f32_16x16x32_bf16 v[86:89], v[172:175], v[204:207], v[86:89]
	v_mfma_f32_16x16x32_bf16 v[82:85], v[180:183], v[204:207], v[82:85]
	v_mfma_f32_16x16x32_bf16 v[70:73], v[172:175], v[212:215], v[70:73]
	v_mfma_f32_16x16x32_bf16 v[66:69], v[180:183], v[212:215], v[66:69]
	v_mfma_f32_16x16x32_bf16 v[118:121], v[176:179], v[192:195], v[118:121]
	v_mfma_f32_16x16x32_bf16 v[114:117], v[184:187], v[192:195], v[114:117]
	v_mfma_f32_16x16x32_bf16 v[102:105], v[176:179], v[200:203], v[102:105]
	v_mfma_f32_16x16x32_bf16 v[98:101], v[184:187], v[200:203], v[98:101]
	v_mfma_f32_16x16x32_bf16 v[86:89], v[176:179], v[208:211], v[86:89]
	v_mfma_f32_16x16x32_bf16 v[82:85], v[184:187], v[208:211], v[82:85]
	v_mfma_f32_16x16x32_bf16 v[70:73], v[176:179], v[216:219], v[70:73]
	v_mfma_f32_16x16x32_bf16 v[66:69], v[184:187], v[216:219], v[66:69]
	s_setprio 0
	s_barrier
	s_add_i32 s54, s15, s44
	v_lshl_add_u64 v[146:147], s[36:37], 0, v[134:135]
	s_mov_b32 m0, s54
	ds_read_b128 v[188:191], v153 offset:16384
	ds_read_b128 v[192:195], v153 offset:17408
	ds_read_b128 v[196:199], v153 offset:18432
	ds_read_b128 v[200:203], v153 offset:19456
	ds_read_b128 v[204:207], v153 offset:20480
	ds_read_b128 v[208:211], v153 offset:21504
	ds_read_b128 v[212:215], v153 offset:22528
	ds_read_b128 v[216:219], v153 offset:23552
	global_load_lds_dwordx4 v[146:147], off
	s_add_i32 m0, s54, 0x2000
	s_add_u32 s54, s36, 0x80000
	v_lshl_add_u64 v[220:221], s[36:37], 0, v[130:131]
	s_addc_u32 s55, s37, 0
	s_add_i32 s56, s51, s44
	global_load_lds_dwordx4 v[220:221], off
	v_lshl_add_u64 v[222:223], s[54:55], 0, v[134:135]
	s_mov_b32 m0, s56
	v_lshl_add_u64 v[224:225], s[38:39], 0, v[132:133]
	global_load_lds_dwordx4 v[222:223], off
	v_lshl_add_u64 v[222:223], s[54:55], 0, v[130:131]
	s_add_i32 m0, s56, 0x2000
	s_nop 0
	global_load_lds_dwordx4 v[222:223], off
	v_lshl_add_u64 v[222:223], s[38:39], 0, v[136:137]
	s_mov_b32 m0, s31
	s_nop 0
	global_load_lds_dwordx4 v[222:223], off
	s_mov_b32 m0, s47
	s_nop 0
	global_load_lds_dwordx4 v[224:225], off
	s_waitcnt vmcnt(8)
	s_waitcnt lgkmcnt(0)
	s_waitcnt lgkmcnt(0)
	v_mfma_f32_16x16x32_bf16 v[62:65], v[154:157], v[188:191], v[62:65]
	v_mfma_f32_16x16x32_bf16 v[58:61], v[164:167], v[188:191], v[58:61]
	v_mfma_f32_16x16x32_bf16 v[46:49], v[154:157], v[196:199], v[46:49]
	v_mfma_f32_16x16x32_bf16 v[42:45], v[164:167], v[196:199], v[42:45]
	s_barrier
	s_setprio 1
	v_mfma_f32_16x16x32_bf16 v[30:33], v[154:157], v[204:207], v[30:33]
	v_mfma_f32_16x16x32_bf16 v[26:29], v[164:167], v[204:207], v[26:29]
	v_mfma_f32_16x16x32_bf16 v[14:17], v[154:157], v[212:215], v[14:17]
	v_mfma_f32_16x16x32_bf16 v[10:13], v[164:167], v[212:215], v[10:13]
	v_mfma_f32_16x16x32_bf16 v[62:65], v[158:161], v[192:195], v[62:65]
	v_mfma_f32_16x16x32_bf16 v[58:61], v[168:171], v[192:195], v[58:61]
	v_mfma_f32_16x16x32_bf16 v[46:49], v[158:161], v[200:203], v[46:49]
	v_mfma_f32_16x16x32_bf16 v[42:45], v[168:171], v[200:203], v[42:45]
	v_mfma_f32_16x16x32_bf16 v[30:33], v[158:161], v[208:211], v[30:33]
	v_mfma_f32_16x16x32_bf16 v[26:29], v[168:171], v[208:211], v[26:29]
	v_mfma_f32_16x16x32_bf16 v[14:17], v[158:161], v[216:219], v[14:17]
	v_mfma_f32_16x16x32_bf16 v[10:13], v[168:171], v[216:219], v[10:13]
	v_mfma_f32_16x16x32_bf16 v[54:57], v[172:175], v[188:191], v[54:57]
	v_mfma_f32_16x16x32_bf16 v[50:53], v[180:183], v[188:191], v[50:53]
	v_mfma_f32_16x16x32_bf16 v[38:41], v[172:175], v[196:199], v[38:41]
	v_mfma_f32_16x16x32_bf16 v[34:37], v[180:183], v[196:199], v[34:37]
	v_mfma_f32_16x16x32_bf16 v[22:25], v[172:175], v[204:207], v[22:25]
	v_mfma_f32_16x16x32_bf16 v[18:21], v[180:183], v[204:207], v[18:21]
	v_mfma_f32_16x16x32_bf16 v[6:9], v[172:175], v[212:215], v[6:9]
	v_mfma_f32_16x16x32_bf16 v[2:5], v[180:183], v[212:215], v[2:5]
	v_mfma_f32_16x16x32_bf16 v[54:57], v[176:179], v[192:195], v[54:57]
	v_mfma_f32_16x16x32_bf16 v[50:53], v[184:187], v[192:195], v[50:53]
	v_mfma_f32_16x16x32_bf16 v[38:41], v[176:179], v[200:203], v[38:41]
	v_mfma_f32_16x16x32_bf16 v[34:37], v[184:187], v[200:203], v[34:37]
	v_mfma_f32_16x16x32_bf16 v[22:25], v[176:179], v[208:211], v[22:25]
	v_mfma_f32_16x16x32_bf16 v[18:21], v[184:187], v[208:211], v[18:21]
	v_mfma_f32_16x16x32_bf16 v[6:9], v[176:179], v[216:219], v[6:9]
	v_mfma_f32_16x16x32_bf16 v[2:5], v[184:187], v[216:219], v[2:5]
	s_setprio 0
	s_barrier
	s_add_i32 s54, 0, 0x18000
	v_add_u32_e32 v163, s54, v149
	s_add_i32 s55, 0, 0x1c000
	ds_read_b128 v[154:157], v163
	ds_read_b128 v[158:161], v163 offset:1024
	ds_read_b128 v[164:167], v163 offset:2048
	ds_read_b128 v[168:171], v163 offset:3072
	v_add_u32_e32 v163, s55, v149
	ds_read_b128 v[172:175], v163
	ds_read_b128 v[176:179], v163 offset:1024
	ds_read_b128 v[180:183], v163 offset:2048
	ds_read_b128 v[184:187], v163 offset:3072
	s_add_u32 s38, s38, 0x80000
	s_addc_u32 s39, s39, 0
	s_mov_b32 m0, s48
	v_lshl_add_u64 v[226:227], s[38:39], 0, v[136:137]
	ds_read_b128 v[188:191], v153 offset:32768
	ds_read_b128 v[192:195], v153 offset:33792
	ds_read_b128 v[196:199], v153 offset:34816
	ds_read_b128 v[200:203], v153 offset:35840
	ds_read_b128 v[204:207], v153 offset:36864
	ds_read_b128 v[208:211], v153 offset:37888
	ds_read_b128 v[212:215], v153 offset:38912
	ds_read_b128 v[216:219], v153 offset:39936
	global_load_lds_dwordx4 v[226:227], off
	v_lshl_add_u64 v[226:227], s[38:39], 0, v[132:133]
	s_mov_b32 m0, s49
	s_nop 0
	global_load_lds_dwordx4 v[226:227], off
	s_waitcnt vmcnt(8)
	s_waitcnt lgkmcnt(0)
	s_waitcnt lgkmcnt(0)
	v_mfma_f32_16x16x32_bf16 v[126:129], v[154:157], v[188:191], v[126:129]
	v_mfma_f32_16x16x32_bf16 v[122:125], v[164:167], v[188:191], v[122:125]
	v_mfma_f32_16x16x32_bf16 v[110:113], v[154:157], v[196:199], v[110:113]
	v_mfma_f32_16x16x32_bf16 v[106:109], v[164:167], v[196:199], v[106:109]
	s_barrier
	s_setprio 1
	v_mfma_f32_16x16x32_bf16 v[94:97], v[154:157], v[204:207], v[94:97]
	v_mfma_f32_16x16x32_bf16 v[90:93], v[164:167], v[204:207], v[90:93]
	v_mfma_f32_16x16x32_bf16 v[78:81], v[154:157], v[212:215], v[78:81]
	v_mfma_f32_16x16x32_bf16 v[74:77], v[164:167], v[212:215], v[74:77]
	v_mfma_f32_16x16x32_bf16 v[126:129], v[158:161], v[192:195], v[126:129]
	v_mfma_f32_16x16x32_bf16 v[122:125], v[168:171], v[192:195], v[122:125]
	v_mfma_f32_16x16x32_bf16 v[110:113], v[158:161], v[200:203], v[110:113]
	v_mfma_f32_16x16x32_bf16 v[106:109], v[168:171], v[200:203], v[106:109]
	v_mfma_f32_16x16x32_bf16 v[94:97], v[158:161], v[208:211], v[94:97]
	v_mfma_f32_16x16x32_bf16 v[90:93], v[168:171], v[208:211], v[90:93]
	v_mfma_f32_16x16x32_bf16 v[78:81], v[158:161], v[216:219], v[78:81]
	v_mfma_f32_16x16x32_bf16 v[74:77], v[168:171], v[216:219], v[74:77]
	v_mfma_f32_16x16x32_bf16 v[118:121], v[172:175], v[188:191], v[118:121]
	v_mfma_f32_16x16x32_bf16 v[114:117], v[180:183], v[188:191], v[114:117]
	v_mfma_f32_16x16x32_bf16 v[102:105], v[172:175], v[196:199], v[102:105]
	v_mfma_f32_16x16x32_bf16 v[98:101], v[180:183], v[196:199], v[98:101]
	v_mfma_f32_16x16x32_bf16 v[86:89], v[172:175], v[204:207], v[86:89]
	v_mfma_f32_16x16x32_bf16 v[82:85], v[180:183], v[204:207], v[82:85]
	v_mfma_f32_16x16x32_bf16 v[70:73], v[172:175], v[212:215], v[70:73]
	v_mfma_f32_16x16x32_bf16 v[66:69], v[180:183], v[212:215], v[66:69]
	v_mfma_f32_16x16x32_bf16 v[118:121], v[176:179], v[192:195], v[118:121]
	v_mfma_f32_16x16x32_bf16 v[114:117], v[184:187], v[192:195], v[114:117]
	v_mfma_f32_16x16x32_bf16 v[102:105], v[176:179], v[200:203], v[102:105]
	v_mfma_f32_16x16x32_bf16 v[98:101], v[184:187], v[200:203], v[98:101]
	v_mfma_f32_16x16x32_bf16 v[86:89], v[176:179], v[208:211], v[86:89]
	v_mfma_f32_16x16x32_bf16 v[82:85], v[184:187], v[208:211], v[82:85]
	v_mfma_f32_16x16x32_bf16 v[70:73], v[176:179], v[216:219], v[70:73]
	v_mfma_f32_16x16x32_bf16 v[66:69], v[184:187], v[216:219], v[66:69]
	s_setprio 0
	s_barrier
	s_add_i32 s38, s54, s44
	v_lshl_add_u64 v[146:147], v[146:147], 0, s[10:11]
	s_mov_b32 m0, s38
	ds_read_b128 v[188:191], v153 offset:49152
	ds_read_b128 v[192:195], v153 offset:50176
	ds_read_b128 v[196:199], v153 offset:51200
	ds_read_b128 v[200:203], v153 offset:52224
	ds_read_b128 v[204:207], v153 offset:53248
	ds_read_b128 v[208:211], v153 offset:54272
	ds_read_b128 v[212:215], v153 offset:55296
	ds_read_b128 v[216:219], v153 offset:56320
	global_load_lds_dwordx4 v[146:147], off
	s_add_i32 m0, s38, 0x2000
	s_add_u32 s36, s36, 0x80080
	v_lshl_add_u64 v[146:147], v[220:221], 0, s[10:11]
	s_addc_u32 s37, s37, 0
	s_add_i32 s38, s55, s44
	global_load_lds_dwordx4 v[146:147], off
	v_lshl_add_u64 v[146:147], s[36:37], 0, v[134:135]
	s_mov_b32 m0, s38
	s_nop 0
	global_load_lds_dwordx4 v[146:147], off
	v_lshl_add_u64 v[146:147], s[36:37], 0, v[130:131]
	s_add_i32 m0, s38, 0x2000
	s_nop 0
	global_load_lds_dwordx4 v[146:147], off
	v_lshl_add_u64 v[146:147], v[222:223], 0, s[10:11]
	s_mov_b32 m0, s20
	s_nop 0
	global_load_lds_dwordx4 v[146:147], off
	v_lshl_add_u64 v[146:147], v[224:225], 0, s[10:11]
	s_mov_b32 m0, s21
	s_nop 0
	global_load_lds_dwordx4 v[146:147], off
	s_waitcnt vmcnt(8)
	s_waitcnt lgkmcnt(0)
	s_waitcnt lgkmcnt(0)
	v_mfma_f32_16x16x32_bf16 v[62:65], v[154:157], v[188:191], v[62:65]
	v_mfma_f32_16x16x32_bf16 v[58:61], v[164:167], v[188:191], v[58:61]
	v_mfma_f32_16x16x32_bf16 v[46:49], v[154:157], v[196:199], v[46:49]
	v_mfma_f32_16x16x32_bf16 v[42:45], v[164:167], v[196:199], v[42:45]
	s_barrier
	s_setprio 1
	v_mfma_f32_16x16x32_bf16 v[30:33], v[154:157], v[204:207], v[30:33]
	v_mfma_f32_16x16x32_bf16 v[26:29], v[164:167], v[204:207], v[26:29]
	v_mfma_f32_16x16x32_bf16 v[14:17], v[154:157], v[212:215], v[14:17]
	v_mfma_f32_16x16x32_bf16 v[10:13], v[164:167], v[212:215], v[10:13]
	v_mfma_f32_16x16x32_bf16 v[62:65], v[158:161], v[192:195], v[62:65]
	v_mfma_f32_16x16x32_bf16 v[58:61], v[168:171], v[192:195], v[58:61]
	v_mfma_f32_16x16x32_bf16 v[46:49], v[158:161], v[200:203], v[46:49]
	v_mfma_f32_16x16x32_bf16 v[42:45], v[168:171], v[200:203], v[42:45]
	v_mfma_f32_16x16x32_bf16 v[30:33], v[158:161], v[208:211], v[30:33]
	v_mfma_f32_16x16x32_bf16 v[26:29], v[168:171], v[208:211], v[26:29]
	v_mfma_f32_16x16x32_bf16 v[14:17], v[158:161], v[216:219], v[14:17]
	v_mfma_f32_16x16x32_bf16 v[10:13], v[168:171], v[216:219], v[10:13]
	v_mfma_f32_16x16x32_bf16 v[54:57], v[172:175], v[188:191], v[54:57]
	v_mfma_f32_16x16x32_bf16 v[50:53], v[180:183], v[188:191], v[50:53]
	v_mfma_f32_16x16x32_bf16 v[38:41], v[172:175], v[196:199], v[38:41]
	v_mfma_f32_16x16x32_bf16 v[34:37], v[180:183], v[196:199], v[34:37]
	v_mfma_f32_16x16x32_bf16 v[22:25], v[172:175], v[204:207], v[22:25]
	v_mfma_f32_16x16x32_bf16 v[18:21], v[180:183], v[204:207], v[18:21]
	v_mfma_f32_16x16x32_bf16 v[6:9], v[172:175], v[212:215], v[6:9]
	v_mfma_f32_16x16x32_bf16 v[2:5], v[180:183], v[212:215], v[2:5]
	v_mfma_f32_16x16x32_bf16 v[54:57], v[176:179], v[192:195], v[54:57]
	v_mfma_f32_16x16x32_bf16 v[50:53], v[184:187], v[192:195], v[50:53]
	v_mfma_f32_16x16x32_bf16 v[38:41], v[176:179], v[200:203], v[38:41]
	v_mfma_f32_16x16x32_bf16 v[34:37], v[184:187], v[200:203], v[34:37]
	v_mfma_f32_16x16x32_bf16 v[22:25], v[176:179], v[208:211], v[22:25]
	v_mfma_f32_16x16x32_bf16 v[18:21], v[184:187], v[208:211], v[18:21]
	v_mfma_f32_16x16x32_bf16 v[6:9], v[176:179], v[216:219], v[6:9]
	v_mfma_f32_16x16x32_bf16 v[2:5], v[184:187], v[216:219], v[2:5]
	s_setprio 0
	s_barrier
	s_add_i32 s53, s53, 2
	s_add_u32 s34, s34, 0x100
	s_addc_u32 s35, s35, 0
	s_add_u32 s23, s23, 0x100
	s_addc_u32 s25, s25, 0
	s_cmp_gt_u32 s53, 29
	s_cbranch_scc0 .LBB0_285
	s_and_b64 vcc, exec, s[12:13]
	s_cbranch_vccz .LBB0_288
	s_barrier

.LBB0_356:
	ds_read_b128 v[134:137], v213
	ds_read_b128 v[138:141], v213 offset:1024
	ds_read_b128 v[142:145], v213 offset:2048
	ds_read_b128 v[178:181], v213 offset:3072
	ds_read_b128 v[182:185], v214
	ds_read_b128 v[186:189], v214 offset:1024
	ds_read_b128 v[190:193], v214 offset:2048
	ds_read_b128 v[194:197], v214 offset:3072
	s_add_u32 s36, s34, 0x100
	s_addc_u32 s37, s35, 0
	s_add_u32 s16, s3, s34
	s_addc_u32 s17, s14, s35
	s_cmpk_eq_i32 s15, 0x54
	s_cselect_b32 s41, s27, s17
	s_cselect_b32 s17, 0, s36
	s_cselect_b32 s40, s26, s16
	s_cselect_b32 s16, 0, s37
	s_add_u32 s38, s8, s17
	s_addc_u32 s39, s9, s16
	s_mov_b32 m0, s63
	v_lshl_add_u64 v[244:245], v[130:131], 0, s[34:35]
	ds_read_b128 v[198:201], v215
	ds_read_b128 v[202:205], v215 offset:1024
	ds_read_b128 v[206:209], v215 offset:2048
	ds_read_b128 v[224:227], v215 offset:3072
	ds_read_b128 v[228:231], v215 offset:4096
	ds_read_b128 v[232:235], v215 offset:5120
	ds_read_b128 v[236:239], v215 offset:6144
	ds_read_b128 v[240:243], v215 offset:7168
	global_load_lds_dwordx4 v[244:245], off
	v_lshl_add_u64 v[244:245], v[132:133], 0, s[34:35]
	s_mov_b32 m0, s64
	s_nop 0
	global_load_lds_dwordx4 v[244:245], off
	s_waitcnt vmcnt(8)
	s_waitcnt lgkmcnt(0)
	s_waitcnt lgkmcnt(0)
	v_mfma_f32_16x16x32_bf16 v[86:89], v[134:137], v[198:201], v[86:89]
	v_mfma_f32_16x16x32_bf16 v[82:85], v[142:145], v[198:201], v[82:85]
	v_mfma_f32_16x16x32_bf16 v[110:113], v[134:137], v[206:209], v[110:113]
	v_mfma_f32_16x16x32_bf16 v[106:109], v[142:145], v[206:209], v[106:109]
	s_barrier
	s_setprio 1
	v_mfma_f32_16x16x32_bf16 v[118:121], v[134:137], v[228:231], v[118:121]
	v_mfma_f32_16x16x32_bf16 v[114:117], v[142:145], v[228:231], v[114:117]
	v_mfma_f32_16x16x32_bf16 v[126:129], v[134:137], v[236:239], v[126:129]
	v_mfma_f32_16x16x32_bf16 v[122:125], v[142:145], v[236:239], v[122:125]
	v_mfma_f32_16x16x32_bf16 v[86:89], v[138:141], v[202:205], v[86:89]
	v_mfma_f32_16x16x32_bf16 v[82:85], v[178:181], v[202:205], v[82:85]
	v_mfma_f32_16x16x32_bf16 v[110:113], v[138:141], v[224:227], v[110:113]
	v_mfma_f32_16x16x32_bf16 v[106:109], v[178:181], v[224:227], v[106:109]
	v_mfma_f32_16x16x32_bf16 v[118:121], v[138:141], v[232:235], v[118:121]
	v_mfma_f32_16x16x32_bf16 v[114:117], v[178:181], v[232:235], v[114:117]
	v_mfma_f32_16x16x32_bf16 v[126:129], v[138:141], v[240:243], v[126:129]
	v_mfma_f32_16x16x32_bf16 v[122:125], v[178:181], v[240:243], v[122:125]
	v_mfma_f32_16x16x32_bf16 v[26:29], v[182:185], v[198:201], v[26:29]
	v_mfma_f32_16x16x32_bf16 v[30:33], v[190:193], v[198:201], v[30:33]
	v_mfma_f32_16x16x32_bf16 v[42:45], v[182:185], v[206:209], v[42:45]
	v_mfma_f32_16x16x32_bf16 v[50:53], v[190:193], v[206:209], v[50:53]
	v_mfma_f32_16x16x32_bf16 v[66:69], v[182:185], v[228:231], v[66:69]
	v_mfma_f32_16x16x32_bf16 v[70:73], v[190:193], v[228:231], v[70:73]
	v_mfma_f32_16x16x32_bf16 v[90:93], v[182:185], v[236:239], v[90:93]
	v_mfma_f32_16x16x32_bf16 v[94:97], v[190:193], v[236:239], v[94:97]
	v_mfma_f32_16x16x32_bf16 v[26:29], v[186:189], v[202:205], v[26:29]
	v_mfma_f32_16x16x32_bf16 v[30:33], v[194:197], v[202:205], v[30:33]
	v_mfma_f32_16x16x32_bf16 v[42:45], v[186:189], v[224:227], v[42:45]
	v_mfma_f32_16x16x32_bf16 v[50:53], v[194:197], v[224:227], v[50:53]
	v_mfma_f32_16x16x32_bf16 v[66:69], v[186:189], v[232:235], v[66:69]
	v_mfma_f32_16x16x32_bf16 v[70:73], v[194:197], v[232:235], v[70:73]
	v_mfma_f32_16x16x32_bf16 v[90:93], v[186:189], v[240:243], v[90:93]
	v_mfma_f32_16x16x32_bf16 v[94:97], v[194:197], v[240:243], v[94:97]
	s_setprio 0
	s_barrier
	s_mov_b32 m0, s65
	v_lshl_add_u64 v[244:245], s[38:39], 0, v[150:151]
	s_add_u32 s16, s38, 0x160000
	ds_read_b128 v[198:201], v215 offset:16384
	ds_read_b128 v[202:205], v215 offset:17408
	ds_read_b128 v[206:209], v215 offset:18432
	ds_read_b128 v[224:227], v215 offset:19456
	ds_read_b128 v[228:231], v215 offset:20480
	ds_read_b128 v[232:235], v215 offset:21504
	ds_read_b128 v[236:239], v215 offset:22528
	ds_read_b128 v[240:243], v215 offset:23552
	global_load_lds_dwordx4 v[244:245], off
	v_lshl_add_u64 v[246:247], s[38:39], 0, v[146:147]
	s_mov_b32 m0, s66
	s_addc_u32 s17, s39, 0
	global_load_lds_dwordx4 v[246:247], off
	v_lshl_add_u64 v[248:249], s[16:17], 0, v[150:151]
	s_mov_b32 m0, s67
	v_lshl_add_u64 v[250:251], s[40:41], 0, v[148:149]
	global_load_lds_dwordx4 v[248:249], off
	v_lshl_add_u64 v[248:249], s[16:17], 0, v[146:147]
	s_mov_b32 m0, s68
	s_nop 0
	global_load_lds_dwordx4 v[248:249], off
	v_lshl_add_u64 v[248:249], s[40:41], 0, v[152:153]
	s_mov_b32 m0, s51
	s_nop 0
	global_load_lds_dwordx4 v[248:249], off
	s_mov_b32 m0, s52
	s_nop 0
	global_load_lds_dwordx4 v[250:251], off
	s_waitcnt vmcnt(8)
	s_waitcnt lgkmcnt(0)
	s_waitcnt lgkmcnt(0)
	v_mfma_f32_16x16x32_bf16 v[102:105], v[134:137], v[198:201], v[102:105]
	v_mfma_f32_16x16x32_bf16 v[98:101], v[142:145], v[198:201], v[98:101]
	v_mfma_f32_16x16x32_bf16 v[62:65], v[134:137], v[206:209], v[62:65]
	v_mfma_f32_16x16x32_bf16 v[58:61], v[142:145], v[206:209], v[58:61]
	s_barrier
	s_setprio 1
	v_mfma_f32_16x16x32_bf16 v[38:41], v[134:137], v[228:231], v[38:41]
	v_mfma_f32_16x16x32_bf16 v[34:37], v[142:145], v[228:231], v[34:37]
	v_mfma_f32_16x16x32_bf16 v[14:17], v[134:137], v[236:239], v[14:17]
	v_mfma_f32_16x16x32_bf16 v[10:13], v[142:145], v[236:239], v[10:13]
	v_mfma_f32_16x16x32_bf16 v[102:105], v[138:141], v[202:205], v[102:105]
	v_mfma_f32_16x16x32_bf16 v[98:101], v[178:181], v[202:205], v[98:101]
	v_mfma_f32_16x16x32_bf16 v[62:65], v[138:141], v[224:227], v[62:65]
	v_mfma_f32_16x16x32_bf16 v[58:61], v[178:181], v[224:227], v[58:61]
	v_mfma_f32_16x16x32_bf16 v[38:41], v[138:141], v[232:235], v[38:41]
	v_mfma_f32_16x16x32_bf16 v[34:37], v[178:181], v[232:235], v[34:37]
	v_mfma_f32_16x16x32_bf16 v[14:17], v[138:141], v[240:243], v[14:17]
	v_mfma_f32_16x16x32_bf16 v[10:13], v[178:181], v[240:243], v[10:13]
	v_mfma_f32_16x16x32_bf16 v[78:81], v[182:185], v[198:201], v[78:81]
	v_mfma_f32_16x16x32_bf16 v[74:77], v[190:193], v[198:201], v[74:77]
	v_mfma_f32_16x16x32_bf16 v[54:57], v[182:185], v[206:209], v[54:57]
	v_mfma_f32_16x16x32_bf16 v[46:49], v[190:193], v[206:209], v[46:49]
	v_mfma_f32_16x16x32_bf16 v[22:25], v[182:185], v[228:231], v[22:25]
	v_mfma_f32_16x16x32_bf16 v[18:21], v[190:193], v[228:231], v[18:21]
	v_mfma_f32_16x16x32_bf16 v[6:9], v[182:185], v[236:239], v[6:9]
	v_mfma_f32_16x16x32_bf16 v[2:5], v[190:193], v[236:239], v[2:5]
	v_mfma_f32_16x16x32_bf16 v[78:81], v[186:189], v[202:205], v[78:81]
	v_mfma_f32_16x16x32_bf16 v[74:77], v[194:197], v[202:205], v[74:77]
	v_mfma_f32_16x16x32_bf16 v[54:57], v[186:189], v[224:227], v[54:57]
	v_mfma_f32_16x16x32_bf16 v[46:49], v[194:197], v[224:227], v[46:49]
	v_mfma_f32_16x16x32_bf16 v[22:25], v[186:189], v[232:235], v[22:25]
	v_mfma_f32_16x16x32_bf16 v[18:21], v[194:197], v[232:235], v[18:21]
	v_mfma_f32_16x16x32_bf16 v[6:9], v[186:189], v[240:243], v[6:9]
	v_mfma_f32_16x16x32_bf16 v[2:5], v[194:197], v[240:243], v[2:5]
	s_setprio 0
	s_barrier
	ds_read_b128 v[134:137], v219
	ds_read_b128 v[138:141], v219 offset:1024
	ds_read_b128 v[142:145], v219 offset:2048
	ds_read_b128 v[178:181], v219 offset:3072
	ds_read_b128 v[182:185], v220
	ds_read_b128 v[186:189], v220 offset:1024
	ds_read_b128 v[190:193], v220 offset:2048
	ds_read_b128 v[194:197], v220 offset:3072
	s_add_u32 s16, s40, 0x160000
	s_addc_u32 s17, s41, 0
	s_mov_b32 m0, s53
	v_lshl_add_u64 v[252:253], s[16:17], 0, v[152:153]
	ds_read_b128 v[198:201], v215 offset:32768
	ds_read_b128 v[202:205], v215 offset:33792
	ds_read_b128 v[206:209], v215 offset:34816
	ds_read_b128 v[224:227], v215 offset:35840
	ds_read_b128 v[228:231], v215 offset:36864
	ds_read_b128 v[232:235], v215 offset:37888
	ds_read_b128 v[236:239], v215 offset:38912
	ds_read_b128 v[240:243], v215 offset:39936
	global_load_lds_dwordx4 v[252:253], off
	v_lshl_add_u64 v[252:253], s[16:17], 0, v[148:149]
	s_mov_b32 m0, s54
	s_nop 0
	global_load_lds_dwordx4 v[252:253], off
	s_waitcnt vmcnt(8)
	s_waitcnt lgkmcnt(0)
	s_waitcnt lgkmcnt(0)
	v_mfma_f32_16x16x32_bf16 v[86:89], v[134:137], v[198:201], v[86:89]
	v_mfma_f32_16x16x32_bf16 v[82:85], v[142:145], v[198:201], v[82:85]
	v_mfma_f32_16x16x32_bf16 v[110:113], v[134:137], v[206:209], v[110:113]
	v_mfma_f32_16x16x32_bf16 v[106:109], v[142:145], v[206:209], v[106:109]
	s_barrier
	s_setprio 1
	v_mfma_f32_16x16x32_bf16 v[118:121], v[134:137], v[228:231], v[118:121]
	v_mfma_f32_16x16x32_bf16 v[114:117], v[142:145], v[228:231], v[114:117]
	v_mfma_f32_16x16x32_bf16 v[126:129], v[134:137], v[236:239], v[126:129]
	v_mfma_f32_16x16x32_bf16 v[122:125], v[142:145], v[236:239], v[122:125]
	v_mfma_f32_16x16x32_bf16 v[86:89], v[138:141], v[202:205], v[86:89]
	v_mfma_f32_16x16x32_bf16 v[82:85], v[178:181], v[202:205], v[82:85]
	v_mfma_f32_16x16x32_bf16 v[110:113], v[138:141], v[224:227], v[110:113]
	v_mfma_f32_16x16x32_bf16 v[106:109], v[178:181], v[224:227], v[106:109]
	v_mfma_f32_16x16x32_bf16 v[118:121], v[138:141], v[232:235], v[118:121]
	v_mfma_f32_16x16x32_bf16 v[114:117], v[178:181], v[232:235], v[114:117]
	v_mfma_f32_16x16x32_bf16 v[126:129], v[138:141], v[240:243], v[126:129]
	v_mfma_f32_16x16x32_bf16 v[122:125], v[178:181], v[240:243], v[122:125]
	v_mfma_f32_16x16x32_bf16 v[26:29], v[182:185], v[198:201], v[26:29]
	v_mfma_f32_16x16x32_bf16 v[30:33], v[190:193], v[198:201], v[30:33]
	v_mfma_f32_16x16x32_bf16 v[42:45], v[182:185], v[206:209], v[42:45]
	v_mfma_f32_16x16x32_bf16 v[50:53], v[190:193], v[206:209], v[50:53]
	v_mfma_f32_16x16x32_bf16 v[66:69], v[182:185], v[228:231], v[66:69]
	v_mfma_f32_16x16x32_bf16 v[70:73], v[190:193], v[228:231], v[70:73]
	v_mfma_f32_16x16x32_bf16 v[90:93], v[182:185], v[236:239], v[90:93]
	v_mfma_f32_16x16x32_bf16 v[94:97], v[190:193], v[236:239], v[94:97]
	v_mfma_f32_16x16x32_bf16 v[26:29], v[186:189], v[202:205], v[26:29]
	v_mfma_f32_16x16x32_bf16 v[30:33], v[194:197], v[202:205], v[30:33]
	v_mfma_f32_16x16x32_bf16 v[42:45], v[186:189], v[224:227], v[42:45]
	v_mfma_f32_16x16x32_bf16 v[50:53], v[194:197], v[224:227], v[50:53]
	v_mfma_f32_16x16x32_bf16 v[66:69], v[186:189], v[232:235], v[66:69]
	v_mfma_f32_16x16x32_bf16 v[70:73], v[194:197], v[232:235], v[70:73]
	v_mfma_f32_16x16x32_bf16 v[90:93], v[186:189], v[240:243], v[90:93]
	v_mfma_f32_16x16x32_bf16 v[94:97], v[194:197], v[240:243], v[94:97]
	s_setprio 0
	s_barrier
	s_mov_b32 m0, s69
	v_lshl_add_u64 v[244:245], v[244:245], 0, s[22:23]
	s_add_u32 s16, s38, 0x160080
	ds_read_b128 v[198:201], v215 offset:49152
	ds_read_b128 v[202:205], v215 offset:50176
	ds_read_b128 v[206:209], v215 offset:51200
	ds_read_b128 v[224:227], v215 offset:52224
	ds_read_b128 v[228:231], v215 offset:53248
	ds_read_b128 v[232:235], v215 offset:54272
	ds_read_b128 v[236:239], v215 offset:55296
	ds_read_b128 v[240:243], v215 offset:56320
	global_load_lds_dwordx4 v[244:245], off
	v_lshl_add_u64 v[244:245], v[246:247], 0, s[22:23]
	s_mov_b32 m0, s73
	s_addc_u32 s17, s39, 0
	global_load_lds_dwordx4 v[244:245], off
	v_lshl_add_u64 v[244:245], s[16:17], 0, v[150:151]
	s_mov_b32 m0, s74
	s_nop 0
	global_load_lds_dwordx4 v[244:245], off
	v_lshl_add_u64 v[244:245], s[16:17], 0, v[146:147]
	s_mov_b32 m0, s75
	s_nop 0
	global_load_lds_dwordx4 v[244:245], off
	v_lshl_add_u64 v[244:245], v[248:249], 0, s[22:23]
	s_mov_b32 m0, s60
	s_nop 0
	global_load_lds_dwordx4 v[244:245], off
	v_lshl_add_u64 v[244:245], v[250:251], 0, s[22:23]
	s_mov_b32 m0, s61
	s_nop 0
	global_load_lds_dwordx4 v[244:245], off
	s_waitcnt vmcnt(8)
	s_waitcnt lgkmcnt(0)
	s_waitcnt lgkmcnt(0)
	v_mfma_f32_16x16x32_bf16 v[102:105], v[134:137], v[198:201], v[102:105]
	v_mfma_f32_16x16x32_bf16 v[98:101], v[142:145], v[198:201], v[98:101]
	v_mfma_f32_16x16x32_bf16 v[62:65], v[134:137], v[206:209], v[62:65]
	v_mfma_f32_16x16x32_bf16 v[58:61], v[142:145], v[206:209], v[58:61]
	s_barrier
	s_setprio 1
	v_mfma_f32_16x16x32_bf16 v[38:41], v[134:137], v[228:231], v[38:41]
	v_mfma_f32_16x16x32_bf16 v[34:37], v[142:145], v[228:231], v[34:37]
	v_mfma_f32_16x16x32_bf16 v[14:17], v[134:137], v[236:239], v[14:17]
	v_mfma_f32_16x16x32_bf16 v[10:13], v[142:145], v[236:239], v[10:13]
	v_mfma_f32_16x16x32_bf16 v[102:105], v[138:141], v[202:205], v[102:105]
	v_mfma_f32_16x16x32_bf16 v[98:101], v[178:181], v[202:205], v[98:101]
	v_mfma_f32_16x16x32_bf16 v[62:65], v[138:141], v[224:227], v[62:65]
	v_mfma_f32_16x16x32_bf16 v[58:61], v[178:181], v[224:227], v[58:61]
	v_mfma_f32_16x16x32_bf16 v[38:41], v[138:141], v[232:235], v[38:41]
	v_mfma_f32_16x16x32_bf16 v[34:37], v[178:181], v[232:235], v[34:37]
	v_mfma_f32_16x16x32_bf16 v[14:17], v[138:141], v[240:243], v[14:17]
	v_mfma_f32_16x16x32_bf16 v[10:13], v[178:181], v[240:243], v[10:13]
	v_mfma_f32_16x16x32_bf16 v[78:81], v[182:185], v[198:201], v[78:81]
	v_mfma_f32_16x16x32_bf16 v[74:77], v[190:193], v[198:201], v[74:77]
	v_mfma_f32_16x16x32_bf16 v[54:57], v[182:185], v[206:209], v[54:57]
	v_mfma_f32_16x16x32_bf16 v[46:49], v[190:193], v[206:209], v[46:49]
	v_mfma_f32_16x16x32_bf16 v[22:25], v[182:185], v[228:231], v[22:25]
	v_mfma_f32_16x16x32_bf16 v[18:21], v[190:193], v[228:231], v[18:21]
	v_mfma_f32_16x16x32_bf16 v[6:9], v[182:185], v[236:239], v[6:9]
	v_mfma_f32_16x16x32_bf16 v[2:5], v[190:193], v[236:239], v[2:5]
	v_mfma_f32_16x16x32_bf16 v[78:81], v[186:189], v[202:205], v[78:81]
	v_mfma_f32_16x16x32_bf16 v[74:77], v[194:197], v[202:205], v[74:77]
	v_mfma_f32_16x16x32_bf16 v[54:57], v[186:189], v[224:227], v[54:57]
	v_mfma_f32_16x16x32_bf16 v[46:49], v[194:197], v[224:227], v[46:49]
	v_mfma_f32_16x16x32_bf16 v[22:25], v[186:189], v[232:235], v[22:25]
	v_mfma_f32_16x16x32_bf16 v[18:21], v[194:197], v[232:235], v[18:21]
	v_mfma_f32_16x16x32_bf16 v[6:9], v[186:189], v[240:243], v[6:9]
	v_mfma_f32_16x16x32_bf16 v[2:5], v[194:197], v[240:243], v[2:5]
	s_setprio 0
	s_barrier
	s_add_i32 s15, s15, 2
	s_cmpk_gt_u32 s15, 0x55
	s_mov_b64 s[34:35], s[36:37]
	s_cbranch_scc0 .LBB0_356
	s_and_b64 vcc, exec, s[24:25]
	s_cbranch_vccz .LBB0_359
	s_barrier

.LBB0_466:
	ds_read_b128 v[130:133], v170
	ds_read_b128 v[134:137], v170 offset:1024
	ds_read_b128 v[164:167], v170 offset:2048
	ds_read_b128 v[174:177], v170 offset:3072
	ds_read_b128 v[178:181], v171
	ds_read_b128 v[182:185], v171 offset:1024
	ds_read_b128 v[186:189], v171 offset:2048
	ds_read_b128 v[190:193], v171 offset:3072
	s_add_u32 s19, s42, 0xfff80080
	s_addc_u32 s20, s43, -1
	s_cmp_eq_u32 s18, 28
	s_cselect_b32 s47, s3, s20
	s_cselect_b32 s46, s7, s19
	s_cselect_b32 s45, s14, s17
	s_cselect_b32 s44, s15, s16
	v_lshl_add_u64 v[168:169], s[42:43], 0, v[154:155]
	s_add_i32 m0, s41, 0xc000
	ds_read_b128 v[194:197], v172
	ds_read_b128 v[198:201], v172 offset:1024
	ds_read_b128 v[202:205], v172 offset:2048
	ds_read_b128 v[206:209], v172 offset:3072
	ds_read_b128 v[210:213], v172 offset:4096
	ds_read_b128 v[214:217], v172 offset:5120
	ds_read_b128 v[218:221], v172 offset:6144
	ds_read_b128 v[222:225], v172 offset:7168
	global_load_lds_dwordx4 v[168:169], off
	v_lshl_add_u64 v[168:169], s[42:43], 0, v[156:157]
	s_add_i32 m0, s41, 0xe000
	s_nop 0
	global_load_lds_dwordx4 v[168:169], off
	s_waitcnt vmcnt(8)
	s_waitcnt lgkmcnt(0)
	s_waitcnt lgkmcnt(0)
	v_mfma_f32_16x16x32_bf16 v[126:129], v[130:133], v[194:197], v[126:129]
	v_mfma_f32_16x16x32_bf16 v[122:125], v[164:167], v[194:197], v[122:125]
	v_mfma_f32_16x16x32_bf16 v[110:113], v[130:133], v[202:205], v[110:113]
	v_mfma_f32_16x16x32_bf16 v[106:109], v[164:167], v[202:205], v[106:109]
	s_barrier
	s_setprio 1
	v_mfma_f32_16x16x32_bf16 v[94:97], v[130:133], v[210:213], v[94:97]
	v_mfma_f32_16x16x32_bf16 v[90:93], v[164:167], v[210:213], v[90:93]
	v_mfma_f32_16x16x32_bf16 v[78:81], v[130:133], v[218:221], v[78:81]
	v_mfma_f32_16x16x32_bf16 v[74:77], v[164:167], v[218:221], v[74:77]
	v_mfma_f32_16x16x32_bf16 v[126:129], v[134:137], v[198:201], v[126:129]
	v_mfma_f32_16x16x32_bf16 v[122:125], v[174:177], v[198:201], v[122:125]
	v_mfma_f32_16x16x32_bf16 v[110:113], v[134:137], v[206:209], v[110:113]
	v_mfma_f32_16x16x32_bf16 v[106:109], v[174:177], v[206:209], v[106:109]
	v_mfma_f32_16x16x32_bf16 v[94:97], v[134:137], v[214:217], v[94:97]
	v_mfma_f32_16x16x32_bf16 v[90:93], v[174:177], v[214:217], v[90:93]
	v_mfma_f32_16x16x32_bf16 v[78:81], v[134:137], v[222:225], v[78:81]
	v_mfma_f32_16x16x32_bf16 v[74:77], v[174:177], v[222:225], v[74:77]
	v_mfma_f32_16x16x32_bf16 v[118:121], v[178:181], v[194:197], v[118:121]
	v_mfma_f32_16x16x32_bf16 v[114:117], v[186:189], v[194:197], v[114:117]
	v_mfma_f32_16x16x32_bf16 v[102:105], v[178:181], v[202:205], v[102:105]
	v_mfma_f32_16x16x32_bf16 v[98:101], v[186:189], v[202:205], v[98:101]
	v_mfma_f32_16x16x32_bf16 v[86:89], v[178:181], v[210:213], v[86:89]
	v_mfma_f32_16x16x32_bf16 v[82:85], v[186:189], v[210:213], v[82:85]
	v_mfma_f32_16x16x32_bf16 v[70:73], v[178:181], v[218:221], v[70:73]
	v_mfma_f32_16x16x32_bf16 v[66:69], v[186:189], v[218:221], v[66:69]
	v_mfma_f32_16x16x32_bf16 v[118:121], v[182:185], v[198:201], v[118:121]
	v_mfma_f32_16x16x32_bf16 v[114:117], v[190:193], v[198:201], v[114:117]
	v_mfma_f32_16x16x32_bf16 v[102:105], v[182:185], v[206:209], v[102:105]
	v_mfma_f32_16x16x32_bf16 v[98:101], v[190:193], v[206:209], v[98:101]
	v_mfma_f32_16x16x32_bf16 v[86:89], v[182:185], v[214:217], v[86:89]
	v_mfma_f32_16x16x32_bf16 v[82:85], v[190:193], v[214:217], v[82:85]
	v_mfma_f32_16x16x32_bf16 v[70:73], v[182:185], v[222:225], v[70:73]
	v_mfma_f32_16x16x32_bf16 v[66:69], v[190:193], v[222:225], v[66:69]
	s_setprio 0
	s_barrier
	s_add_i32 s19, s75, s52
	v_lshl_add_u64 v[168:169], s[44:45], 0, v[140:141]
	s_mov_b32 m0, s19
	ds_read_b128 v[194:197], v172 offset:16384
	ds_read_b128 v[198:201], v172 offset:17408
	ds_read_b128 v[202:205], v172 offset:18432
	ds_read_b128 v[206:209], v172 offset:19456
	ds_read_b128 v[210:213], v172 offset:20480
	ds_read_b128 v[214:217], v172 offset:21504
	ds_read_b128 v[218:221], v172 offset:22528
	ds_read_b128 v[222:225], v172 offset:23552
	global_load_lds_dwordx4 v[168:169], off
	s_add_i32 m0, s19, 0x2000
	s_add_u32 s20, s44, 0x80000
	v_lshl_add_u64 v[226:227], s[44:45], 0, v[144:145]
	s_addc_u32 s21, s45, 0
	s_add_i32 s19, s76, s52
	global_load_lds_dwordx4 v[226:227], off
	v_lshl_add_u64 v[228:229], s[20:21], 0, v[140:141]
	s_mov_b32 m0, s19
	v_lshl_add_u64 v[230:231], s[46:47], 0, v[142:143]
	global_load_lds_dwordx4 v[228:229], off
	v_lshl_add_u64 v[228:229], s[20:21], 0, v[144:145]
	s_add_i32 m0, s19, 0x2000
	s_nop 0
	global_load_lds_dwordx4 v[228:229], off
	v_lshl_add_u64 v[228:229], s[46:47], 0, v[138:139]
	s_mov_b32 m0, s41
	s_nop 0
	global_load_lds_dwordx4 v[228:229], off
	s_mov_b32 m0, s53
	s_nop 0
	global_load_lds_dwordx4 v[230:231], off
	s_waitcnt vmcnt(8)
	s_waitcnt lgkmcnt(0)
	s_waitcnt lgkmcnt(0)
	v_mfma_f32_16x16x32_bf16 v[62:65], v[130:133], v[194:197], v[62:65]
	v_mfma_f32_16x16x32_bf16 v[58:61], v[164:167], v[194:197], v[58:61]
	v_mfma_f32_16x16x32_bf16 v[46:49], v[130:133], v[202:205], v[46:49]
	v_mfma_f32_16x16x32_bf16 v[42:45], v[164:167], v[202:205], v[42:45]
	s_barrier
	s_setprio 1
	v_mfma_f32_16x16x32_bf16 v[30:33], v[130:133], v[210:213], v[30:33]
	v_mfma_f32_16x16x32_bf16 v[26:29], v[164:167], v[210:213], v[26:29]
	v_mfma_f32_16x16x32_bf16 v[14:17], v[130:133], v[218:221], v[14:17]
	v_mfma_f32_16x16x32_bf16 v[10:13], v[164:167], v[218:221], v[10:13]
	v_mfma_f32_16x16x32_bf16 v[62:65], v[134:137], v[198:201], v[62:65]
	v_mfma_f32_16x16x32_bf16 v[58:61], v[174:177], v[198:201], v[58:61]
	v_mfma_f32_16x16x32_bf16 v[46:49], v[134:137], v[206:209], v[46:49]
	v_mfma_f32_16x16x32_bf16 v[42:45], v[174:177], v[206:209], v[42:45]
	v_mfma_f32_16x16x32_bf16 v[30:33], v[134:137], v[214:217], v[30:33]
	v_mfma_f32_16x16x32_bf16 v[26:29], v[174:177], v[214:217], v[26:29]
	v_mfma_f32_16x16x32_bf16 v[14:17], v[134:137], v[222:225], v[14:17]
	v_mfma_f32_16x16x32_bf16 v[10:13], v[174:177], v[222:225], v[10:13]
	v_mfma_f32_16x16x32_bf16 v[54:57], v[178:181], v[194:197], v[54:57]
	v_mfma_f32_16x16x32_bf16 v[50:53], v[186:189], v[194:197], v[50:53]
	v_mfma_f32_16x16x32_bf16 v[38:41], v[178:181], v[202:205], v[38:41]
	v_mfma_f32_16x16x32_bf16 v[34:37], v[186:189], v[202:205], v[34:37]
	v_mfma_f32_16x16x32_bf16 v[22:25], v[178:181], v[210:213], v[22:25]
	v_mfma_f32_16x16x32_bf16 v[18:21], v[186:189], v[210:213], v[18:21]
	v_mfma_f32_16x16x32_bf16 v[6:9], v[178:181], v[218:221], v[6:9]
	v_mfma_f32_16x16x32_bf16 v[2:5], v[186:189], v[218:221], v[2:5]
	v_mfma_f32_16x16x32_bf16 v[54:57], v[182:185], v[198:201], v[54:57]
	v_mfma_f32_16x16x32_bf16 v[50:53], v[190:193], v[198:201], v[50:53]
	v_mfma_f32_16x16x32_bf16 v[38:41], v[182:185], v[206:209], v[38:41]
	v_mfma_f32_16x16x32_bf16 v[34:37], v[190:193], v[206:209], v[34:37]
	v_mfma_f32_16x16x32_bf16 v[22:25], v[182:185], v[214:217], v[22:25]
	v_mfma_f32_16x16x32_bf16 v[18:21], v[190:193], v[214:217], v[18:21]
	v_mfma_f32_16x16x32_bf16 v[6:9], v[182:185], v[222:225], v[6:9]
	v_mfma_f32_16x16x32_bf16 v[2:5], v[190:193], v[222:225], v[2:5]
	s_setprio 0
	s_barrier
	s_add_i32 s19, 0, 0x18000
	v_add_u32_e32 v146, s19, v163
	s_add_i32 s31, 0, 0x1c000
	ds_read_b128 v[130:133], v146
	ds_read_b128 v[134:137], v146 offset:1024
	ds_read_b128 v[164:167], v146 offset:2048
	ds_read_b128 v[174:177], v146 offset:3072
	v_add_u32_e32 v146, s31, v163
	ds_read_b128 v[178:181], v146
	ds_read_b128 v[182:185], v146 offset:1024
	ds_read_b128 v[186:189], v146 offset:2048
	ds_read_b128 v[190:193], v146 offset:3072
	s_add_u32 s20, s46, 0x80000
	s_addc_u32 s21, s47, 0
	s_mov_b32 m0, s54
	v_lshl_add_u64 v[232:233], s[20:21], 0, v[138:139]
	ds_read_b128 v[194:197], v172 offset:32768
	ds_read_b128 v[198:201], v172 offset:33792
	ds_read_b128 v[202:205], v172 offset:34816
	ds_read_b128 v[206:209], v172 offset:35840
	ds_read_b128 v[210:213], v172 offset:36864
	ds_read_b128 v[214:217], v172 offset:37888
	ds_read_b128 v[218:221], v172 offset:38912
	ds_read_b128 v[222:225], v172 offset:39936
	global_load_lds_dwordx4 v[232:233], off
	v_lshl_add_u64 v[232:233], s[20:21], 0, v[142:143]
	s_mov_b32 m0, s55
	s_nop 0
	global_load_lds_dwordx4 v[232:233], off
	s_waitcnt vmcnt(8)
	s_waitcnt lgkmcnt(0)
	s_waitcnt lgkmcnt(0)
	v_mfma_f32_16x16x32_bf16 v[126:129], v[130:133], v[194:197], v[126:129]
	v_mfma_f32_16x16x32_bf16 v[122:125], v[164:167], v[194:197], v[122:125]
	v_mfma_f32_16x16x32_bf16 v[110:113], v[130:133], v[202:205], v[110:113]
	v_mfma_f32_16x16x32_bf16 v[106:109], v[164:167], v[202:205], v[106:109]
	s_barrier
	s_setprio 1
	v_mfma_f32_16x16x32_bf16 v[94:97], v[130:133], v[210:213], v[94:97]
	v_mfma_f32_16x16x32_bf16 v[90:93], v[164:167], v[210:213], v[90:93]
	v_mfma_f32_16x16x32_bf16 v[78:81], v[130:133], v[218:221], v[78:81]
	v_mfma_f32_16x16x32_bf16 v[74:77], v[164:167], v[218:221], v[74:77]
	v_mfma_f32_16x16x32_bf16 v[126:129], v[134:137], v[198:201], v[126:129]
	v_mfma_f32_16x16x32_bf16 v[122:125], v[174:177], v[198:201], v[122:125]
	v_mfma_f32_16x16x32_bf16 v[110:113], v[134:137], v[206:209], v[110:113]
	v_mfma_f32_16x16x32_bf16 v[106:109], v[174:177], v[206:209], v[106:109]
	v_mfma_f32_16x16x32_bf16 v[94:97], v[134:137], v[214:217], v[94:97]
	v_mfma_f32_16x16x32_bf16 v[90:93], v[174:177], v[214:217], v[90:93]
	v_mfma_f32_16x16x32_bf16 v[78:81], v[134:137], v[222:225], v[78:81]
	v_mfma_f32_16x16x32_bf16 v[74:77], v[174:177], v[222:225], v[74:77]
	v_mfma_f32_16x16x32_bf16 v[118:121], v[178:181], v[194:197], v[118:121]
	v_mfma_f32_16x16x32_bf16 v[114:117], v[186:189], v[194:197], v[114:117]
	v_mfma_f32_16x16x32_bf16 v[102:105], v[178:181], v[202:205], v[102:105]
	v_mfma_f32_16x16x32_bf16 v[98:101], v[186:189], v[202:205], v[98:101]
	v_mfma_f32_16x16x32_bf16 v[86:89], v[178:181], v[210:213], v[86:89]
	v_mfma_f32_16x16x32_bf16 v[82:85], v[186:189], v[210:213], v[82:85]
	v_mfma_f32_16x16x32_bf16 v[70:73], v[178:181], v[218:221], v[70:73]
	v_mfma_f32_16x16x32_bf16 v[66:69], v[186:189], v[218:221], v[66:69]
	v_mfma_f32_16x16x32_bf16 v[118:121], v[182:185], v[198:201], v[118:121]
	v_mfma_f32_16x16x32_bf16 v[114:117], v[190:193], v[198:201], v[114:117]
	v_mfma_f32_16x16x32_bf16 v[102:105], v[182:185], v[206:209], v[102:105]
	v_mfma_f32_16x16x32_bf16 v[98:101], v[190:193], v[206:209], v[98:101]
	v_mfma_f32_16x16x32_bf16 v[86:89], v[182:185], v[214:217], v[86:89]
	v_mfma_f32_16x16x32_bf16 v[82:85], v[190:193], v[214:217], v[82:85]
	v_mfma_f32_16x16x32_bf16 v[70:73], v[182:185], v[222:225], v[70:73]
	v_mfma_f32_16x16x32_bf16 v[66:69], v[190:193], v[222:225], v[66:69]
	s_setprio 0
	s_barrier
	s_add_i32 s19, s19, s52
	v_lshl_add_u64 v[168:169], v[168:169], 0, s[10:11]
	s_mov_b32 m0, s19
	ds_read_b128 v[194:197], v172 offset:49152
	ds_read_b128 v[198:201], v172 offset:50176
	ds_read_b128 v[202:205], v172 offset:51200
	ds_read_b128 v[206:209], v172 offset:52224
	ds_read_b128 v[210:213], v172 offset:53248
	ds_read_b128 v[214:217], v172 offset:54272
	ds_read_b128 v[218:221], v172 offset:55296
	ds_read_b128 v[222:225], v172 offset:56320
	global_load_lds_dwordx4 v[168:169], off
	s_add_i32 m0, s19, 0x2000
	s_add_u32 s20, s44, 0x80080
	v_lshl_add_u64 v[168:169], v[226:227], 0, s[10:11]
	s_addc_u32 s21, s45, 0
	s_add_i32 s19, s31, s52
	global_load_lds_dwordx4 v[168:169], off
	v_lshl_add_u64 v[168:169], s[20:21], 0, v[140:141]
	s_mov_b32 m0, s19
	s_nop 0
	global_load_lds_dwordx4 v[168:169], off
	v_lshl_add_u64 v[168:169], s[20:21], 0, v[144:145]
	s_add_i32 m0, s19, 0x2000
	s_nop 0
	global_load_lds_dwordx4 v[168:169], off
	v_lshl_add_u64 v[168:169], v[228:229], 0, s[10:11]
	s_mov_b32 m0, s67
	s_nop 0
	global_load_lds_dwordx4 v[168:169], off
	v_lshl_add_u64 v[168:169], v[230:231], 0, s[10:11]
	s_mov_b32 m0, s68
	s_nop 0
	global_load_lds_dwordx4 v[168:169], off
	s_waitcnt vmcnt(8)
	s_waitcnt lgkmcnt(0)
	s_waitcnt lgkmcnt(0)
	v_mfma_f32_16x16x32_bf16 v[62:65], v[130:133], v[194:197], v[62:65]
	v_mfma_f32_16x16x32_bf16 v[58:61], v[164:167], v[194:197], v[58:61]
	v_mfma_f32_16x16x32_bf16 v[46:49], v[130:133], v[202:205], v[46:49]
	v_mfma_f32_16x16x32_bf16 v[42:45], v[164:167], v[202:205], v[42:45]
	s_barrier
	s_setprio 1
	v_mfma_f32_16x16x32_bf16 v[30:33], v[130:133], v[210:213], v[30:33]
	v_mfma_f32_16x16x32_bf16 v[26:29], v[164:167], v[210:213], v[26:29]
	v_mfma_f32_16x16x32_bf16 v[14:17], v[130:133], v[218:221], v[14:17]
	v_mfma_f32_16x16x32_bf16 v[10:13], v[164:167], v[218:221], v[10:13]
	v_mfma_f32_16x16x32_bf16 v[62:65], v[134:137], v[198:201], v[62:65]
	v_mfma_f32_16x16x32_bf16 v[58:61], v[174:177], v[198:201], v[58:61]
	v_mfma_f32_16x16x32_bf16 v[46:49], v[134:137], v[206:209], v[46:49]
	v_mfma_f32_16x16x32_bf16 v[42:45], v[174:177], v[206:209], v[42:45]
	v_mfma_f32_16x16x32_bf16 v[30:33], v[134:137], v[214:217], v[30:33]
	v_mfma_f32_16x16x32_bf16 v[26:29], v[174:177], v[214:217], v[26:29]
	v_mfma_f32_16x16x32_bf16 v[14:17], v[134:137], v[222:225], v[14:17]
	v_mfma_f32_16x16x32_bf16 v[10:13], v[174:177], v[222:225], v[10:13]
	v_mfma_f32_16x16x32_bf16 v[54:57], v[178:181], v[194:197], v[54:57]
	v_mfma_f32_16x16x32_bf16 v[50:53], v[186:189], v[194:197], v[50:53]
	v_mfma_f32_16x16x32_bf16 v[38:41], v[178:181], v[202:205], v[38:41]
	v_mfma_f32_16x16x32_bf16 v[34:37], v[186:189], v[202:205], v[34:37]
	v_mfma_f32_16x16x32_bf16 v[22:25], v[178:181], v[210:213], v[22:25]
	v_mfma_f32_16x16x32_bf16 v[18:21], v[186:189], v[210:213], v[18:21]
	v_mfma_f32_16x16x32_bf16 v[6:9], v[178:181], v[218:221], v[6:9]
	v_mfma_f32_16x16x32_bf16 v[2:5], v[186:189], v[218:221], v[2:5]
	v_mfma_f32_16x16x32_bf16 v[54:57], v[182:185], v[198:201], v[54:57]
	v_mfma_f32_16x16x32_bf16 v[50:53], v[190:193], v[198:201], v[50:53]
	v_mfma_f32_16x16x32_bf16 v[38:41], v[182:185], v[206:209], v[38:41]
	v_mfma_f32_16x16x32_bf16 v[34:37], v[190:193], v[206:209], v[34:37]
	v_mfma_f32_16x16x32_bf16 v[22:25], v[182:185], v[214:217], v[22:25]
	v_mfma_f32_16x16x32_bf16 v[18:21], v[190:193], v[214:217], v[18:21]
	v_mfma_f32_16x16x32_bf16 v[6:9], v[182:185], v[222:225], v[6:9]
	v_mfma_f32_16x16x32_bf16 v[2:5], v[190:193], v[222:225], v[2:5]
	s_setprio 0
	s_barrier
	s_add_i32 s18, s18, 2
	s_add_u32 s42, s42, 0x100
	s_addc_u32 s43, s43, 0
	s_add_u32 s16, s16, 0x100
	s_addc_u32 s17, s17, 0
	s_cmp_gt_u32 s18, 29
	s_cbranch_scc0 .LBB0_466
	s_and_b64 vcc, exec, s[12:13]
	s_cbranch_vccz .LBB0_469
	s_barrier

.LBB0_699:
	ds_read_b128 v[134:137], v214
	ds_read_b128 v[138:141], v214 offset:1024
	ds_read_b128 v[142:145], v214 offset:2048
	ds_read_b128 v[178:181], v214 offset:3072
	ds_read_b128 v[182:185], v215
	ds_read_b128 v[186:189], v215 offset:1024
	ds_read_b128 v[190:193], v215 offset:2048
	ds_read_b128 v[194:197], v215 offset:3072
	s_add_u32 s40, s38, 0x100
	s_addc_u32 s41, s39, 0
	s_add_u32 s18, s15, s38
	s_addc_u32 s19, s16, s39
	s_cmp_eq_u32 s17, 60
	s_cselect_b32 s45, s3, s19
	s_cselect_b32 s19, 0, s40
	s_cselect_b32 s44, s14, s18
	s_cselect_b32 s18, 0, s41
	s_add_u32 s42, s10, s19
	s_addc_u32 s43, s11, s18
	s_mov_b32 m0, s66
	v_lshl_add_u64 v[244:245], v[130:131], 0, s[38:39]
	ds_read_b128 v[198:201], v216
	ds_read_b128 v[202:205], v216 offset:1024
	ds_read_b128 v[206:209], v216 offset:2048
	ds_read_b128 v[224:227], v216 offset:3072
	ds_read_b128 v[228:231], v216 offset:4096
	ds_read_b128 v[232:235], v216 offset:5120
	ds_read_b128 v[236:239], v216 offset:6144
	ds_read_b128 v[240:243], v216 offset:7168
	global_load_lds_dwordx4 v[244:245], off
	v_lshl_add_u64 v[244:245], v[132:133], 0, s[38:39]
	s_mov_b32 m0, s67
	s_nop 0
	global_load_lds_dwordx4 v[244:245], off
	s_waitcnt vmcnt(8)
	s_waitcnt lgkmcnt(0)
	s_waitcnt lgkmcnt(0)
	v_mfma_f32_16x16x32_bf16 v[82:85], v[134:137], v[198:201], v[82:85]
	v_mfma_f32_16x16x32_bf16 v[78:81], v[142:145], v[198:201], v[78:81]
	v_mfma_f32_16x16x32_bf16 v[110:113], v[134:137], v[206:209], v[110:113]
	v_mfma_f32_16x16x32_bf16 v[106:109], v[142:145], v[206:209], v[106:109]
	s_barrier
	s_setprio 1
	v_mfma_f32_16x16x32_bf16 v[118:121], v[134:137], v[228:231], v[118:121]
	v_mfma_f32_16x16x32_bf16 v[114:117], v[142:145], v[228:231], v[114:117]
	v_mfma_f32_16x16x32_bf16 v[126:129], v[134:137], v[236:239], v[126:129]
	v_mfma_f32_16x16x32_bf16 v[122:125], v[142:145], v[236:239], v[122:125]
	v_mfma_f32_16x16x32_bf16 v[82:85], v[138:141], v[202:205], v[82:85]
	v_mfma_f32_16x16x32_bf16 v[78:81], v[178:181], v[202:205], v[78:81]
	v_mfma_f32_16x16x32_bf16 v[110:113], v[138:141], v[224:227], v[110:113]
	v_mfma_f32_16x16x32_bf16 v[106:109], v[178:181], v[224:227], v[106:109]
	v_mfma_f32_16x16x32_bf16 v[118:121], v[138:141], v[232:235], v[118:121]
	v_mfma_f32_16x16x32_bf16 v[114:117], v[178:181], v[232:235], v[114:117]
	v_mfma_f32_16x16x32_bf16 v[126:129], v[138:141], v[240:243], v[126:129]
	v_mfma_f32_16x16x32_bf16 v[122:125], v[178:181], v[240:243], v[122:125]
	v_mfma_f32_16x16x32_bf16 v[22:25], v[182:185], v[198:201], v[22:25]
	v_mfma_f32_16x16x32_bf16 v[26:29], v[190:193], v[198:201], v[26:29]
	v_mfma_f32_16x16x32_bf16 v[42:45], v[182:185], v[206:209], v[42:45]
	v_mfma_f32_16x16x32_bf16 v[46:49], v[190:193], v[206:209], v[46:49]
	v_mfma_f32_16x16x32_bf16 v[62:65], v[182:185], v[228:231], v[62:65]
	v_mfma_f32_16x16x32_bf16 v[70:73], v[190:193], v[228:231], v[70:73]
	v_mfma_f32_16x16x32_bf16 v[90:93], v[182:185], v[236:239], v[90:93]
	v_mfma_f32_16x16x32_bf16 v[94:97], v[190:193], v[236:239], v[94:97]
	v_mfma_f32_16x16x32_bf16 v[22:25], v[186:189], v[202:205], v[22:25]
	v_mfma_f32_16x16x32_bf16 v[26:29], v[194:197], v[202:205], v[26:29]
	v_mfma_f32_16x16x32_bf16 v[42:45], v[186:189], v[224:227], v[42:45]
	v_mfma_f32_16x16x32_bf16 v[46:49], v[194:197], v[224:227], v[46:49]
	v_mfma_f32_16x16x32_bf16 v[62:65], v[186:189], v[232:235], v[62:65]
	v_mfma_f32_16x16x32_bf16 v[70:73], v[194:197], v[232:235], v[70:73]
	v_mfma_f32_16x16x32_bf16 v[90:93], v[186:189], v[240:243], v[90:93]
	v_mfma_f32_16x16x32_bf16 v[94:97], v[194:197], v[240:243], v[94:97]
	s_setprio 0
	s_barrier
	s_mov_b32 m0, s68
	v_lshl_add_u64 v[244:245], s[42:43], 0, v[150:151]
	s_add_u32 s18, s42, 0x100000
	ds_read_b128 v[198:201], v216 offset:16384
	ds_read_b128 v[202:205], v216 offset:17408
	ds_read_b128 v[206:209], v216 offset:18432
	ds_read_b128 v[224:227], v216 offset:19456
	ds_read_b128 v[228:231], v216 offset:20480
	ds_read_b128 v[232:235], v216 offset:21504
	ds_read_b128 v[236:239], v216 offset:22528
	ds_read_b128 v[240:243], v216 offset:23552
	global_load_lds_dwordx4 v[244:245], off
	v_lshl_add_u64 v[246:247], s[42:43], 0, v[146:147]
	s_mov_b32 m0, s69
	s_addc_u32 s19, s43, 0
	global_load_lds_dwordx4 v[246:247], off
	v_lshl_add_u64 v[248:249], s[18:19], 0, v[150:151]
	s_mov_b32 m0, s73
	v_lshl_add_u64 v[250:251], s[44:45], 0, v[148:149]
	global_load_lds_dwordx4 v[248:249], off
	v_lshl_add_u64 v[248:249], s[18:19], 0, v[146:147]
	s_mov_b32 m0, s74
	s_nop 0
	global_load_lds_dwordx4 v[248:249], off
	v_lshl_add_u64 v[248:249], s[44:45], 0, v[152:153]
	s_mov_b32 m0, s9
	s_nop 0
	global_load_lds_dwordx4 v[248:249], off
	s_mov_b32 m0, s55
	s_nop 0
	global_load_lds_dwordx4 v[250:251], off
	s_waitcnt vmcnt(8)
	s_waitcnt lgkmcnt(0)
	s_waitcnt lgkmcnt(0)
	v_mfma_f32_16x16x32_bf16 v[102:105], v[134:137], v[198:201], v[102:105]
	v_mfma_f32_16x16x32_bf16 v[98:101], v[142:145], v[198:201], v[98:101]
	v_mfma_f32_16x16x32_bf16 v[66:69], v[134:137], v[206:209], v[66:69]
	v_mfma_f32_16x16x32_bf16 v[58:61], v[142:145], v[206:209], v[58:61]
	s_barrier
	s_setprio 1
	v_mfma_f32_16x16x32_bf16 v[38:41], v[134:137], v[228:231], v[38:41]
	v_mfma_f32_16x16x32_bf16 v[34:37], v[142:145], v[228:231], v[34:37]
	v_mfma_f32_16x16x32_bf16 v[14:17], v[134:137], v[236:239], v[14:17]
	v_mfma_f32_16x16x32_bf16 v[10:13], v[142:145], v[236:239], v[10:13]
	v_mfma_f32_16x16x32_bf16 v[102:105], v[138:141], v[202:205], v[102:105]
	v_mfma_f32_16x16x32_bf16 v[98:101], v[178:181], v[202:205], v[98:101]
	v_mfma_f32_16x16x32_bf16 v[66:69], v[138:141], v[224:227], v[66:69]
	v_mfma_f32_16x16x32_bf16 v[58:61], v[178:181], v[224:227], v[58:61]
	v_mfma_f32_16x16x32_bf16 v[38:41], v[138:141], v[232:235], v[38:41]
	v_mfma_f32_16x16x32_bf16 v[34:37], v[178:181], v[232:235], v[34:37]
	v_mfma_f32_16x16x32_bf16 v[14:17], v[138:141], v[240:243], v[14:17]
	v_mfma_f32_16x16x32_bf16 v[10:13], v[178:181], v[240:243], v[10:13]
	v_mfma_f32_16x16x32_bf16 v[86:89], v[182:185], v[198:201], v[86:89]
	v_mfma_f32_16x16x32_bf16 v[74:77], v[190:193], v[198:201], v[74:77]
	v_mfma_f32_16x16x32_bf16 v[54:57], v[182:185], v[206:209], v[54:57]
	v_mfma_f32_16x16x32_bf16 v[50:53], v[190:193], v[206:209], v[50:53]
	v_mfma_f32_16x16x32_bf16 v[30:33], v[182:185], v[228:231], v[30:33]
	v_mfma_f32_16x16x32_bf16 v[18:21], v[190:193], v[228:231], v[18:21]
	v_mfma_f32_16x16x32_bf16 v[6:9], v[182:185], v[236:239], v[6:9]
	v_mfma_f32_16x16x32_bf16 v[2:5], v[190:193], v[236:239], v[2:5]
	v_mfma_f32_16x16x32_bf16 v[86:89], v[186:189], v[202:205], v[86:89]
	v_mfma_f32_16x16x32_bf16 v[74:77], v[194:197], v[202:205], v[74:77]
	v_mfma_f32_16x16x32_bf16 v[54:57], v[186:189], v[224:227], v[54:57]
	v_mfma_f32_16x16x32_bf16 v[50:53], v[194:197], v[224:227], v[50:53]
	v_mfma_f32_16x16x32_bf16 v[30:33], v[186:189], v[232:235], v[30:33]
	v_mfma_f32_16x16x32_bf16 v[18:21], v[194:197], v[232:235], v[18:21]
	v_mfma_f32_16x16x32_bf16 v[6:9], v[186:189], v[240:243], v[6:9]
	v_mfma_f32_16x16x32_bf16 v[2:5], v[194:197], v[240:243], v[2:5]
	s_setprio 0
	s_barrier
	s_add_i32 s20, 0, 0x1c000
	v_add_u32_e32 v194, s20, v212
	ds_read_b128 v[134:137], v220
	ds_read_b128 v[138:141], v220 offset:1024
	ds_read_b128 v[142:145], v220 offset:2048
	ds_read_b128 v[178:181], v220 offset:3072
	ds_read_b128 v[182:185], v194
	ds_read_b128 v[186:189], v194 offset:1024
	ds_read_b128 v[190:193], v194 offset:2048
	ds_read_b128 v[194:197], v194 offset:3072
	s_add_u32 s18, s44, 0x100000
	s_addc_u32 s19, s45, 0
	s_mov_b32 m0, s56
	v_lshl_add_u64 v[252:253], s[18:19], 0, v[152:153]
	ds_read_b128 v[198:201], v216 offset:32768
	ds_read_b128 v[202:205], v216 offset:33792
	ds_read_b128 v[206:209], v216 offset:34816
	ds_read_b128 v[224:227], v216 offset:35840
	ds_read_b128 v[228:231], v216 offset:36864
	ds_read_b128 v[232:235], v216 offset:37888
	ds_read_b128 v[236:239], v216 offset:38912
	ds_read_b128 v[240:243], v216 offset:39936
	global_load_lds_dwordx4 v[252:253], off
	v_lshl_add_u64 v[252:253], s[18:19], 0, v[148:149]
	s_mov_b32 m0, s57
	s_nop 0
	global_load_lds_dwordx4 v[252:253], off
	s_waitcnt vmcnt(8)
	s_waitcnt lgkmcnt(0)
	s_waitcnt lgkmcnt(0)
	v_mfma_f32_16x16x32_bf16 v[82:85], v[134:137], v[198:201], v[82:85]
	v_mfma_f32_16x16x32_bf16 v[78:81], v[142:145], v[198:201], v[78:81]
	v_mfma_f32_16x16x32_bf16 v[110:113], v[134:137], v[206:209], v[110:113]
	v_mfma_f32_16x16x32_bf16 v[106:109], v[142:145], v[206:209], v[106:109]
	s_barrier
	s_setprio 1
	v_mfma_f32_16x16x32_bf16 v[118:121], v[134:137], v[228:231], v[118:121]
	v_mfma_f32_16x16x32_bf16 v[114:117], v[142:145], v[228:231], v[114:117]
	v_mfma_f32_16x16x32_bf16 v[126:129], v[134:137], v[236:239], v[126:129]
	v_mfma_f32_16x16x32_bf16 v[122:125], v[142:145], v[236:239], v[122:125]
	v_mfma_f32_16x16x32_bf16 v[82:85], v[138:141], v[202:205], v[82:85]
	v_mfma_f32_16x16x32_bf16 v[78:81], v[178:181], v[202:205], v[78:81]
	v_mfma_f32_16x16x32_bf16 v[110:113], v[138:141], v[224:227], v[110:113]
	v_mfma_f32_16x16x32_bf16 v[106:109], v[178:181], v[224:227], v[106:109]
	v_mfma_f32_16x16x32_bf16 v[118:121], v[138:141], v[232:235], v[118:121]
	v_mfma_f32_16x16x32_bf16 v[114:117], v[178:181], v[232:235], v[114:117]
	v_mfma_f32_16x16x32_bf16 v[126:129], v[138:141], v[240:243], v[126:129]
	v_mfma_f32_16x16x32_bf16 v[122:125], v[178:181], v[240:243], v[122:125]
	v_mfma_f32_16x16x32_bf16 v[22:25], v[182:185], v[198:201], v[22:25]
	v_mfma_f32_16x16x32_bf16 v[26:29], v[190:193], v[198:201], v[26:29]
	v_mfma_f32_16x16x32_bf16 v[42:45], v[182:185], v[206:209], v[42:45]
	v_mfma_f32_16x16x32_bf16 v[46:49], v[190:193], v[206:209], v[46:49]
	v_mfma_f32_16x16x32_bf16 v[62:65], v[182:185], v[228:231], v[62:65]
	v_mfma_f32_16x16x32_bf16 v[70:73], v[190:193], v[228:231], v[70:73]
	v_mfma_f32_16x16x32_bf16 v[90:93], v[182:185], v[236:239], v[90:93]
	v_mfma_f32_16x16x32_bf16 v[94:97], v[190:193], v[236:239], v[94:97]
	v_mfma_f32_16x16x32_bf16 v[22:25], v[186:189], v[202:205], v[22:25]
	v_mfma_f32_16x16x32_bf16 v[26:29], v[194:197], v[202:205], v[26:29]
	v_mfma_f32_16x16x32_bf16 v[42:45], v[186:189], v[224:227], v[42:45]
	v_mfma_f32_16x16x32_bf16 v[46:49], v[194:197], v[224:227], v[46:49]
	v_mfma_f32_16x16x32_bf16 v[62:65], v[186:189], v[232:235], v[62:65]
	v_mfma_f32_16x16x32_bf16 v[70:73], v[194:197], v[232:235], v[70:73]
	v_mfma_f32_16x16x32_bf16 v[90:93], v[186:189], v[240:243], v[90:93]
	v_mfma_f32_16x16x32_bf16 v[94:97], v[194:197], v[240:243], v[94:97]
	s_setprio 0
	s_barrier
	s_add_i32 s18, s75, s54
	v_lshl_add_u64 v[244:245], v[244:245], 0, s[26:27]
	s_mov_b32 m0, s18
	ds_read_b128 v[198:201], v216 offset:49152
	ds_read_b128 v[202:205], v216 offset:50176
	ds_read_b128 v[206:209], v216 offset:51200
	ds_read_b128 v[224:227], v216 offset:52224
	ds_read_b128 v[228:231], v216 offset:53248
	ds_read_b128 v[232:235], v216 offset:54272
	ds_read_b128 v[236:239], v216 offset:55296
	ds_read_b128 v[240:243], v216 offset:56320
	global_load_lds_dwordx4 v[244:245], off
	s_add_i32 m0, s18, 0x2000
	s_add_u32 s18, s42, 0x100080
	v_lshl_add_u64 v[244:245], v[246:247], 0, s[26:27]
	s_addc_u32 s19, s43, 0
	s_add_i32 s20, s20, s54
	global_load_lds_dwordx4 v[244:245], off
	v_lshl_add_u64 v[244:245], s[18:19], 0, v[150:151]
	s_mov_b32 m0, s20
	s_nop 0
	global_load_lds_dwordx4 v[244:245], off
	v_lshl_add_u64 v[244:245], s[18:19], 0, v[146:147]
	s_add_i32 m0, s20, 0x2000
	s_nop 0
	global_load_lds_dwordx4 v[244:245], off
	v_lshl_add_u64 v[244:245], v[248:249], 0, s[26:27]
	s_mov_b32 m0, s63
	s_nop 0
	global_load_lds_dwordx4 v[244:245], off
	v_lshl_add_u64 v[244:245], v[250:251], 0, s[26:27]
	s_mov_b32 m0, s64
	s_nop 0
	global_load_lds_dwordx4 v[244:245], off
	s_waitcnt vmcnt(8)
	s_waitcnt lgkmcnt(0)
	s_waitcnt lgkmcnt(0)
	v_mfma_f32_16x16x32_bf16 v[102:105], v[134:137], v[198:201], v[102:105]
	v_mfma_f32_16x16x32_bf16 v[98:101], v[142:145], v[198:201], v[98:101]
	v_mfma_f32_16x16x32_bf16 v[66:69], v[134:137], v[206:209], v[66:69]
	v_mfma_f32_16x16x32_bf16 v[58:61], v[142:145], v[206:209], v[58:61]
	s_barrier
	s_setprio 1
	v_mfma_f32_16x16x32_bf16 v[38:41], v[134:137], v[228:231], v[38:41]
	v_mfma_f32_16x16x32_bf16 v[34:37], v[142:145], v[228:231], v[34:37]
	v_mfma_f32_16x16x32_bf16 v[14:17], v[134:137], v[236:239], v[14:17]
	v_mfma_f32_16x16x32_bf16 v[10:13], v[142:145], v[236:239], v[10:13]
	v_mfma_f32_16x16x32_bf16 v[102:105], v[138:141], v[202:205], v[102:105]
	v_mfma_f32_16x16x32_bf16 v[98:101], v[178:181], v[202:205], v[98:101]
	v_mfma_f32_16x16x32_bf16 v[66:69], v[138:141], v[224:227], v[66:69]
	v_mfma_f32_16x16x32_bf16 v[58:61], v[178:181], v[224:227], v[58:61]
	v_mfma_f32_16x16x32_bf16 v[38:41], v[138:141], v[232:235], v[38:41]
	v_mfma_f32_16x16x32_bf16 v[34:37], v[178:181], v[232:235], v[34:37]
	v_mfma_f32_16x16x32_bf16 v[14:17], v[138:141], v[240:243], v[14:17]
	v_mfma_f32_16x16x32_bf16 v[10:13], v[178:181], v[240:243], v[10:13]
	v_mfma_f32_16x16x32_bf16 v[86:89], v[182:185], v[198:201], v[86:89]
	v_mfma_f32_16x16x32_bf16 v[74:77], v[190:193], v[198:201], v[74:77]
	v_mfma_f32_16x16x32_bf16 v[54:57], v[182:185], v[206:209], v[54:57]
	v_mfma_f32_16x16x32_bf16 v[50:53], v[190:193], v[206:209], v[50:53]
	v_mfma_f32_16x16x32_bf16 v[30:33], v[182:185], v[228:231], v[30:33]
	v_mfma_f32_16x16x32_bf16 v[18:21], v[190:193], v[228:231], v[18:21]
	v_mfma_f32_16x16x32_bf16 v[6:9], v[182:185], v[236:239], v[6:9]
	v_mfma_f32_16x16x32_bf16 v[2:5], v[190:193], v[236:239], v[2:5]
	v_mfma_f32_16x16x32_bf16 v[86:89], v[186:189], v[202:205], v[86:89]
	v_mfma_f32_16x16x32_bf16 v[74:77], v[194:197], v[202:205], v[74:77]
	v_mfma_f32_16x16x32_bf16 v[54:57], v[186:189], v[224:227], v[54:57]
	v_mfma_f32_16x16x32_bf16 v[50:53], v[194:197], v[224:227], v[50:53]
	v_mfma_f32_16x16x32_bf16 v[30:33], v[186:189], v[232:235], v[30:33]
	v_mfma_f32_16x16x32_bf16 v[18:21], v[194:197], v[232:235], v[18:21]
	v_mfma_f32_16x16x32_bf16 v[6:9], v[186:189], v[240:243], v[6:9]
	v_mfma_f32_16x16x32_bf16 v[2:5], v[194:197], v[240:243], v[2:5]
	s_setprio 0
	s_barrier
	s_add_i32 s17, s17, 2
	s_cmp_gt_u32 s17, 61
	s_mov_b64 s[38:39], s[40:41]
	s_cbranch_scc0 .LBB0_699
	s_and_b64 vcc, exec, s[28:29]
	s_cbranch_vccz .LBB0_702
	s_barrier

.LBB0_877:
	ds_read_b128 v[130:133], v220
	ds_read_b128 v[134:137], v220 offset:1024
	ds_read_b128 v[138:141], v220 offset:2048
	ds_read_b128 v[142:145], v220 offset:3072
	ds_read_b128 v[184:187], v224
	ds_read_b128 v[188:191], v224 offset:1024
	ds_read_b128 v[192:195], v224 offset:2048
	ds_read_b128 v[196:199], v224 offset:3072
	s_add_u32 s14, s36, 0xffea0080
	s_addc_u32 s15, s37, -1
	s_cmpk_eq_i32 s3, 0x54
	s_cselect_b32 s43, s29, s15
	s_cselect_b32 s42, s28, s14
	s_cselect_b32 s41, s9, s39
	s_cselect_b32 s40, s8, s38
	s_mov_b32 m0, s50
	v_lshl_add_u64 v[244:245], s[36:37], 0, v[178:179]
	ds_read_b128 v[200:203], v221
	ds_read_b128 v[204:207], v221 offset:1024
	ds_read_b128 v[208:211], v221 offset:2048
	ds_read_b128 v[212:215], v221 offset:3072
	ds_read_b128 v[228:231], v221 offset:4096
	ds_read_b128 v[232:235], v221 offset:5120
	ds_read_b128 v[236:239], v221 offset:6144
	ds_read_b128 v[240:243], v221 offset:7168
	global_load_lds_dwordx4 v[244:245], off
	v_lshl_add_u64 v[244:245], s[36:37], 0, v[180:181]
	s_mov_b32 m0, s51
	s_nop 0
	global_load_lds_dwordx4 v[244:245], off
	s_waitcnt vmcnt(8)
	s_waitcnt lgkmcnt(0)
	s_waitcnt lgkmcnt(0)
	v_mfma_f32_16x16x32_bf16 v[30:33], v[130:133], v[200:203], v[30:33]
	v_mfma_f32_16x16x32_bf16 v[26:29], v[138:141], v[200:203], v[26:29]
	v_mfma_f32_16x16x32_bf16 v[46:49], v[130:133], v[208:211], v[46:49]
	v_mfma_f32_16x16x32_bf16 v[42:45], v[138:141], v[208:211], v[42:45]
	s_barrier
	s_setprio 1
	v_mfma_f32_16x16x32_bf16 v[62:65], v[130:133], v[228:231], v[62:65]
	v_mfma_f32_16x16x32_bf16 v[58:61], v[138:141], v[228:231], v[58:61]
	v_mfma_f32_16x16x32_bf16 v[94:97], v[130:133], v[236:239], v[94:97]
	v_mfma_f32_16x16x32_bf16 v[90:93], v[138:141], v[236:239], v[90:93]
	v_mfma_f32_16x16x32_bf16 v[30:33], v[134:137], v[204:207], v[30:33]
	v_mfma_f32_16x16x32_bf16 v[26:29], v[142:145], v[204:207], v[26:29]
	v_mfma_f32_16x16x32_bf16 v[46:49], v[134:137], v[212:215], v[46:49]
	v_mfma_f32_16x16x32_bf16 v[42:45], v[142:145], v[212:215], v[42:45]
	v_mfma_f32_16x16x32_bf16 v[62:65], v[134:137], v[232:235], v[62:65]
	v_mfma_f32_16x16x32_bf16 v[58:61], v[142:145], v[232:235], v[58:61]
	v_mfma_f32_16x16x32_bf16 v[94:97], v[134:137], v[240:243], v[94:97]
	v_mfma_f32_16x16x32_bf16 v[90:93], v[142:145], v[240:243], v[90:93]
	v_mfma_f32_16x16x32_bf16 v[2:5], v[184:187], v[200:203], v[2:5]
	v_mfma_f32_16x16x32_bf16 v[6:9], v[192:195], v[200:203], v[6:9]
	v_mfma_f32_16x16x32_bf16 v[10:13], v[184:187], v[208:211], v[10:13]
	v_mfma_f32_16x16x32_bf16 v[14:17], v[192:195], v[208:211], v[14:17]
	v_mfma_f32_16x16x32_bf16 v[18:21], v[184:187], v[228:231], v[18:21]
	v_mfma_f32_16x16x32_bf16 v[22:25], v[192:195], v[228:231], v[22:25]
	v_mfma_f32_16x16x32_bf16 v[34:37], v[184:187], v[236:239], v[34:37]
	v_mfma_f32_16x16x32_bf16 v[38:41], v[192:195], v[236:239], v[38:41]
	v_mfma_f32_16x16x32_bf16 v[2:5], v[188:191], v[204:207], v[2:5]
	v_mfma_f32_16x16x32_bf16 v[6:9], v[196:199], v[204:207], v[6:9]
	v_mfma_f32_16x16x32_bf16 v[10:13], v[188:191], v[212:215], v[10:13]
	v_mfma_f32_16x16x32_bf16 v[14:17], v[196:199], v[212:215], v[14:17]
	v_mfma_f32_16x16x32_bf16 v[18:21], v[188:191], v[232:235], v[18:21]
	v_mfma_f32_16x16x32_bf16 v[22:25], v[196:199], v[232:235], v[22:25]
	v_mfma_f32_16x16x32_bf16 v[34:37], v[188:191], v[240:243], v[34:37]
	v_mfma_f32_16x16x32_bf16 v[38:41], v[196:199], v[240:243], v[38:41]
	s_setprio 0
	s_barrier
	s_mov_b32 m0, s52
	v_lshl_add_u64 v[244:245], s[40:41], 0, v[150:151]
	s_add_u32 s14, s40, 0x160000
	ds_read_b128 v[200:203], v221 offset:16384
	ds_read_b128 v[204:207], v221 offset:17408
	ds_read_b128 v[208:211], v221 offset:18432
	ds_read_b128 v[212:215], v221 offset:19456
	ds_read_b128 v[228:231], v221 offset:20480
	ds_read_b128 v[232:235], v221 offset:21504
	ds_read_b128 v[236:239], v221 offset:22528
	ds_read_b128 v[240:243], v221 offset:23552
	global_load_lds_dwordx4 v[244:245], off
	v_lshl_add_u64 v[246:247], s[40:41], 0, v[146:147]
	s_mov_b32 m0, s53
	s_addc_u32 s15, s41, 0
	global_load_lds_dwordx4 v[246:247], off
	v_lshl_add_u64 v[248:249], s[14:15], 0, v[150:151]
	s_mov_b32 m0, s54
	v_lshl_add_u64 v[250:251], s[42:43], 0, v[148:149]
	global_load_lds_dwordx4 v[248:249], off
	v_lshl_add_u64 v[248:249], s[14:15], 0, v[146:147]
	s_mov_b32 m0, s55
	s_nop 0
	global_load_lds_dwordx4 v[248:249], off
	v_lshl_add_u64 v[248:249], s[42:43], 0, v[152:153]
	s_mov_b32 m0, s61
	s_nop 0
	global_load_lds_dwordx4 v[248:249], off
	s_mov_b32 m0, s62
	s_nop 0
	global_load_lds_dwordx4 v[250:251], off
	s_waitcnt vmcnt(8)
	s_waitcnt lgkmcnt(0)
	s_waitcnt lgkmcnt(0)
	v_mfma_f32_16x16x32_bf16 v[114:117], v[130:133], v[200:203], v[114:117]
	v_mfma_f32_16x16x32_bf16 v[110:113], v[138:141], v[200:203], v[110:113]
	v_mfma_f32_16x16x32_bf16 v[126:129], v[130:133], v[208:211], v[126:129]
	v_mfma_f32_16x16x32_bf16 v[122:125], v[138:141], v[208:211], v[122:125]
	s_barrier
	s_setprio 1
	v_mfma_f32_16x16x32_bf16 v[118:121], v[130:133], v[228:231], v[118:121]
	v_mfma_f32_16x16x32_bf16 v[106:109], v[138:141], v[228:231], v[106:109]
	v_mfma_f32_16x16x32_bf16 v[78:81], v[130:133], v[236:239], v[78:81]
	v_mfma_f32_16x16x32_bf16 v[74:77], v[138:141], v[236:239], v[74:77]
	v_mfma_f32_16x16x32_bf16 v[114:117], v[134:137], v[204:207], v[114:117]
	v_mfma_f32_16x16x32_bf16 v[110:113], v[142:145], v[204:207], v[110:113]
	v_mfma_f32_16x16x32_bf16 v[126:129], v[134:137], v[212:215], v[126:129]
	v_mfma_f32_16x16x32_bf16 v[122:125], v[142:145], v[212:215], v[122:125]
	v_mfma_f32_16x16x32_bf16 v[118:121], v[134:137], v[232:235], v[118:121]
	v_mfma_f32_16x16x32_bf16 v[106:109], v[142:145], v[232:235], v[106:109]
	v_mfma_f32_16x16x32_bf16 v[78:81], v[134:137], v[240:243], v[78:81]
	v_mfma_f32_16x16x32_bf16 v[74:77], v[142:145], v[240:243], v[74:77]
	v_mfma_f32_16x16x32_bf16 v[50:53], v[184:187], v[200:203], v[50:53]
	v_mfma_f32_16x16x32_bf16 v[54:57], v[192:195], v[200:203], v[54:57]
	v_mfma_f32_16x16x32_bf16 v[82:85], v[184:187], v[208:211], v[82:85]
	v_mfma_f32_16x16x32_bf16 v[86:89], v[192:195], v[208:211], v[86:89]
	v_mfma_f32_16x16x32_bf16 v[102:105], v[184:187], v[228:231], v[102:105]
	v_mfma_f32_16x16x32_bf16 v[98:101], v[192:195], v[228:231], v[98:101]
	v_mfma_f32_16x16x32_bf16 v[70:73], v[184:187], v[236:239], v[70:73]
	v_mfma_f32_16x16x32_bf16 v[66:69], v[192:195], v[236:239], v[66:69]
	v_mfma_f32_16x16x32_bf16 v[50:53], v[188:191], v[204:207], v[50:53]
	v_mfma_f32_16x16x32_bf16 v[54:57], v[196:199], v[204:207], v[54:57]
	v_mfma_f32_16x16x32_bf16 v[82:85], v[188:191], v[212:215], v[82:85]
	v_mfma_f32_16x16x32_bf16 v[86:89], v[196:199], v[212:215], v[86:89]
	v_mfma_f32_16x16x32_bf16 v[102:105], v[188:191], v[232:235], v[102:105]
	v_mfma_f32_16x16x32_bf16 v[98:101], v[196:199], v[232:235], v[98:101]
	v_mfma_f32_16x16x32_bf16 v[70:73], v[188:191], v[240:243], v[70:73]
	v_mfma_f32_16x16x32_bf16 v[66:69], v[196:199], v[240:243], v[66:69]
	s_setprio 0
	s_barrier
	v_add_u32_e32 v196, s74, v218
	ds_read_b128 v[130:133], v225
	ds_read_b128 v[134:137], v225 offset:1024
	ds_read_b128 v[138:141], v225 offset:2048
	ds_read_b128 v[142:145], v225 offset:3072
	ds_read_b128 v[184:187], v196
	ds_read_b128 v[188:191], v196 offset:1024
	ds_read_b128 v[192:195], v196 offset:2048
	ds_read_b128 v[196:199], v196 offset:3072
	s_add_u32 s14, s42, 0x160000
	s_addc_u32 s15, s43, 0
	s_mov_b32 m0, s63
	v_lshl_add_u64 v[252:253], s[14:15], 0, v[152:153]
	ds_read_b128 v[200:203], v221 offset:32768
	ds_read_b128 v[204:207], v221 offset:33792
	ds_read_b128 v[208:211], v221 offset:34816
	ds_read_b128 v[212:215], v221 offset:35840
	ds_read_b128 v[228:231], v221 offset:36864
	ds_read_b128 v[232:235], v221 offset:37888
	ds_read_b128 v[236:239], v221 offset:38912
	ds_read_b128 v[240:243], v221 offset:39936
	global_load_lds_dwordx4 v[252:253], off
	v_lshl_add_u64 v[252:253], s[14:15], 0, v[148:149]
	s_mov_b32 m0, s64
	s_nop 0
	global_load_lds_dwordx4 v[252:253], off
	s_waitcnt vmcnt(8)
	s_waitcnt lgkmcnt(0)
	s_waitcnt lgkmcnt(0)
	v_mfma_f32_16x16x32_bf16 v[30:33], v[130:133], v[200:203], v[30:33]
	v_mfma_f32_16x16x32_bf16 v[26:29], v[138:141], v[200:203], v[26:29]
	v_mfma_f32_16x16x32_bf16 v[46:49], v[130:133], v[208:211], v[46:49]
	v_mfma_f32_16x16x32_bf16 v[42:45], v[138:141], v[208:211], v[42:45]
	s_barrier
	s_setprio 1
	v_mfma_f32_16x16x32_bf16 v[62:65], v[130:133], v[228:231], v[62:65]
	v_mfma_f32_16x16x32_bf16 v[58:61], v[138:141], v[228:231], v[58:61]
	v_mfma_f32_16x16x32_bf16 v[94:97], v[130:133], v[236:239], v[94:97]
	v_mfma_f32_16x16x32_bf16 v[90:93], v[138:141], v[236:239], v[90:93]
	v_mfma_f32_16x16x32_bf16 v[30:33], v[134:137], v[204:207], v[30:33]
	v_mfma_f32_16x16x32_bf16 v[26:29], v[142:145], v[204:207], v[26:29]
	v_mfma_f32_16x16x32_bf16 v[46:49], v[134:137], v[212:215], v[46:49]
	v_mfma_f32_16x16x32_bf16 v[42:45], v[142:145], v[212:215], v[42:45]
	v_mfma_f32_16x16x32_bf16 v[62:65], v[134:137], v[232:235], v[62:65]
	v_mfma_f32_16x16x32_bf16 v[58:61], v[142:145], v[232:235], v[58:61]
	v_mfma_f32_16x16x32_bf16 v[94:97], v[134:137], v[240:243], v[94:97]
	v_mfma_f32_16x16x32_bf16 v[90:93], v[142:145], v[240:243], v[90:93]
	v_mfma_f32_16x16x32_bf16 v[2:5], v[184:187], v[200:203], v[2:5]
	v_mfma_f32_16x16x32_bf16 v[6:9], v[192:195], v[200:203], v[6:9]
	v_mfma_f32_16x16x32_bf16 v[10:13], v[184:187], v[208:211], v[10:13]
	v_mfma_f32_16x16x32_bf16 v[14:17], v[192:195], v[208:211], v[14:17]
	v_mfma_f32_16x16x32_bf16 v[18:21], v[184:187], v[228:231], v[18:21]
	v_mfma_f32_16x16x32_bf16 v[22:25], v[192:195], v[228:231], v[22:25]
	v_mfma_f32_16x16x32_bf16 v[34:37], v[184:187], v[236:239], v[34:37]
	v_mfma_f32_16x16x32_bf16 v[38:41], v[192:195], v[236:239], v[38:41]
	v_mfma_f32_16x16x32_bf16 v[2:5], v[188:191], v[204:207], v[2:5]
	v_mfma_f32_16x16x32_bf16 v[6:9], v[196:199], v[204:207], v[6:9]
	v_mfma_f32_16x16x32_bf16 v[10:13], v[188:191], v[212:215], v[10:13]
	v_mfma_f32_16x16x32_bf16 v[14:17], v[196:199], v[212:215], v[14:17]
	v_mfma_f32_16x16x32_bf16 v[18:21], v[188:191], v[232:235], v[18:21]
	v_mfma_f32_16x16x32_bf16 v[22:25], v[196:199], v[232:235], v[22:25]
	v_mfma_f32_16x16x32_bf16 v[34:37], v[188:191], v[240:243], v[34:37]
	v_mfma_f32_16x16x32_bf16 v[38:41], v[196:199], v[240:243], v[38:41]
	s_setprio 0
	s_barrier
	s_mov_b32 m0, s75
	v_lshl_add_u64 v[244:245], v[244:245], 0, s[22:23]
	s_add_u32 s14, s40, 0x160080
	ds_read_b128 v[200:203], v221 offset:49152
	ds_read_b128 v[204:207], v221 offset:50176
	ds_read_b128 v[208:211], v221 offset:51200
	ds_read_b128 v[212:215], v221 offset:52224
	ds_read_b128 v[228:231], v221 offset:53248
	ds_read_b128 v[232:235], v221 offset:54272
	ds_read_b128 v[236:239], v221 offset:55296
	ds_read_b128 v[240:243], v221 offset:56320
	global_load_lds_dwordx4 v[244:245], off
	v_lshl_add_u64 v[244:245], v[246:247], 0, s[22:23]
	s_mov_b32 m0, s76
	s_addc_u32 s15, s41, 0
	global_load_lds_dwordx4 v[244:245], off
	v_lshl_add_u64 v[244:245], s[14:15], 0, v[150:151]
	s_mov_b32 m0, s77
	s_nop 0
	global_load_lds_dwordx4 v[244:245], off
	v_lshl_add_u64 v[244:245], s[14:15], 0, v[146:147]
	s_mov_b32 m0, s78
	s_nop 0
	global_load_lds_dwordx4 v[244:245], off
	v_lshl_add_u64 v[244:245], v[248:249], 0, s[22:23]
	s_mov_b32 m0, s68
	s_nop 0
	global_load_lds_dwordx4 v[244:245], off
	v_lshl_add_u64 v[244:245], v[250:251], 0, s[22:23]
	s_mov_b32 m0, s69
	s_nop 0
	global_load_lds_dwordx4 v[244:245], off
	s_waitcnt vmcnt(8)
	s_waitcnt lgkmcnt(0)
	s_waitcnt lgkmcnt(0)
	v_mfma_f32_16x16x32_bf16 v[114:117], v[130:133], v[200:203], v[114:117]
	v_mfma_f32_16x16x32_bf16 v[110:113], v[138:141], v[200:203], v[110:113]
	v_mfma_f32_16x16x32_bf16 v[126:129], v[130:133], v[208:211], v[126:129]
	v_mfma_f32_16x16x32_bf16 v[122:125], v[138:141], v[208:211], v[122:125]
	s_barrier
	s_setprio 1
	v_mfma_f32_16x16x32_bf16 v[118:121], v[130:133], v[228:231], v[118:121]
	v_mfma_f32_16x16x32_bf16 v[106:109], v[138:141], v[228:231], v[106:109]
	v_mfma_f32_16x16x32_bf16 v[78:81], v[130:133], v[236:239], v[78:81]
	v_mfma_f32_16x16x32_bf16 v[74:77], v[138:141], v[236:239], v[74:77]
	v_mfma_f32_16x16x32_bf16 v[114:117], v[134:137], v[204:207], v[114:117]
	v_mfma_f32_16x16x32_bf16 v[110:113], v[142:145], v[204:207], v[110:113]
	v_mfma_f32_16x16x32_bf16 v[126:129], v[134:137], v[212:215], v[126:129]
	v_mfma_f32_16x16x32_bf16 v[122:125], v[142:145], v[212:215], v[122:125]
	v_mfma_f32_16x16x32_bf16 v[118:121], v[134:137], v[232:235], v[118:121]
	v_mfma_f32_16x16x32_bf16 v[106:109], v[142:145], v[232:235], v[106:109]
	v_mfma_f32_16x16x32_bf16 v[78:81], v[134:137], v[240:243], v[78:81]
	v_mfma_f32_16x16x32_bf16 v[74:77], v[142:145], v[240:243], v[74:77]
	v_mfma_f32_16x16x32_bf16 v[50:53], v[184:187], v[200:203], v[50:53]
	v_mfma_f32_16x16x32_bf16 v[54:57], v[192:195], v[200:203], v[54:57]
	v_mfma_f32_16x16x32_bf16 v[82:85], v[184:187], v[208:211], v[82:85]
	v_mfma_f32_16x16x32_bf16 v[86:89], v[192:195], v[208:211], v[86:89]
	v_mfma_f32_16x16x32_bf16 v[102:105], v[184:187], v[228:231], v[102:105]
	v_mfma_f32_16x16x32_bf16 v[98:101], v[192:195], v[228:231], v[98:101]
	v_mfma_f32_16x16x32_bf16 v[70:73], v[184:187], v[236:239], v[70:73]
	v_mfma_f32_16x16x32_bf16 v[66:69], v[192:195], v[236:239], v[66:69]
	v_mfma_f32_16x16x32_bf16 v[50:53], v[188:191], v[204:207], v[50:53]
	v_mfma_f32_16x16x32_bf16 v[54:57], v[196:199], v[204:207], v[54:57]
	v_mfma_f32_16x16x32_bf16 v[82:85], v[188:191], v[212:215], v[82:85]
	v_mfma_f32_16x16x32_bf16 v[86:89], v[196:199], v[212:215], v[86:89]
	v_mfma_f32_16x16x32_bf16 v[102:105], v[188:191], v[232:235], v[102:105]
	v_mfma_f32_16x16x32_bf16 v[98:101], v[196:199], v[232:235], v[98:101]
	v_mfma_f32_16x16x32_bf16 v[70:73], v[188:191], v[240:243], v[70:73]
	v_mfma_f32_16x16x32_bf16 v[66:69], v[196:199], v[240:243], v[66:69]
	s_setprio 0
	s_barrier
	s_add_i32 s3, s3, 2
	s_add_u32 s36, s36, 0x100
	s_addc_u32 s37, s37, 0
	s_add_u32 s38, s38, 0x100
	s_addc_u32 s39, s39, 0
	s_cmpk_gt_u32 s3, 0x55
	s_cbranch_scc0 .LBB0_877
	s_and_b64 vcc, exec, s[24:25]
	s_cbranch_vccz .LBB0_880
	s_barrier

.LBB0_986:
	ds_read_b128 v[130:133], v172
	ds_read_b128 v[134:137], v172 offset:1024
	ds_read_b128 v[138:141], v172 offset:2048
	ds_read_b128 v[142:145], v172 offset:3072
	ds_read_b128 v[166:169], v173
	ds_read_b128 v[176:179], v173 offset:1024
	ds_read_b128 v[180:183], v173 offset:2048
	ds_read_b128 v[184:187], v173 offset:3072
	s_add_u32 s20, s52, 0xfff80080
	s_addc_u32 s21, s53, -1
	s_cmp_eq_u32 s19, 28
	s_cselect_b32 s57, s3, s21
	s_cselect_b32 s56, s14, s20
	s_cselect_b32 s55, s15, s18
	s_cselect_b32 s54, s16, s17
	v_lshl_add_u64 v[220:221], s[52:53], 0, v[156:157]
	s_add_i32 m0, s65, 0xc000
	ds_read_b128 v[188:191], v174
	ds_read_b128 v[192:195], v174 offset:1024
	ds_read_b128 v[196:199], v174 offset:2048
	ds_read_b128 v[200:203], v174 offset:3072
	ds_read_b128 v[204:207], v174 offset:4096
	ds_read_b128 v[208:211], v174 offset:5120
	ds_read_b128 v[212:215], v174 offset:6144
	ds_read_b128 v[216:219], v174 offset:7168
	global_load_lds_dwordx4 v[220:221], off
	v_lshl_add_u64 v[220:221], s[52:53], 0, v[158:159]
	s_add_i32 m0, s65, 0xe000
	s_nop 0
	global_load_lds_dwordx4 v[220:221], off
	s_waitcnt vmcnt(8)
	s_waitcnt lgkmcnt(0)
	s_waitcnt lgkmcnt(0)
	v_mfma_f32_16x16x32_bf16 v[126:129], v[130:133], v[188:191], v[126:129]
	v_mfma_f32_16x16x32_bf16 v[122:125], v[138:141], v[188:191], v[122:125]
	v_mfma_f32_16x16x32_bf16 v[110:113], v[130:133], v[196:199], v[110:113]
	v_mfma_f32_16x16x32_bf16 v[106:109], v[138:141], v[196:199], v[106:109]
	s_barrier
	s_setprio 1
	v_mfma_f32_16x16x32_bf16 v[94:97], v[130:133], v[204:207], v[94:97]
	v_mfma_f32_16x16x32_bf16 v[90:93], v[138:141], v[204:207], v[90:93]
	v_mfma_f32_16x16x32_bf16 v[78:81], v[130:133], v[212:215], v[78:81]
	v_mfma_f32_16x16x32_bf16 v[74:77], v[138:141], v[212:215], v[74:77]
	v_mfma_f32_16x16x32_bf16 v[126:129], v[134:137], v[192:195], v[126:129]
	v_mfma_f32_16x16x32_bf16 v[122:125], v[142:145], v[192:195], v[122:125]
	v_mfma_f32_16x16x32_bf16 v[110:113], v[134:137], v[200:203], v[110:113]
	v_mfma_f32_16x16x32_bf16 v[106:109], v[142:145], v[200:203], v[106:109]
	v_mfma_f32_16x16x32_bf16 v[94:97], v[134:137], v[208:211], v[94:97]
	v_mfma_f32_16x16x32_bf16 v[90:93], v[142:145], v[208:211], v[90:93]
	v_mfma_f32_16x16x32_bf16 v[78:81], v[134:137], v[216:219], v[78:81]
	v_mfma_f32_16x16x32_bf16 v[74:77], v[142:145], v[216:219], v[74:77]
	v_mfma_f32_16x16x32_bf16 v[118:121], v[166:169], v[188:191], v[118:121]
	v_mfma_f32_16x16x32_bf16 v[114:117], v[180:183], v[188:191], v[114:117]
	v_mfma_f32_16x16x32_bf16 v[102:105], v[166:169], v[196:199], v[102:105]
	v_mfma_f32_16x16x32_bf16 v[98:101], v[180:183], v[196:199], v[98:101]
	v_mfma_f32_16x16x32_bf16 v[86:89], v[166:169], v[204:207], v[86:89]
	v_mfma_f32_16x16x32_bf16 v[82:85], v[180:183], v[204:207], v[82:85]
	v_mfma_f32_16x16x32_bf16 v[70:73], v[166:169], v[212:215], v[70:73]
	v_mfma_f32_16x16x32_bf16 v[66:69], v[180:183], v[212:215], v[66:69]
	v_mfma_f32_16x16x32_bf16 v[118:121], v[176:179], v[192:195], v[118:121]
	v_mfma_f32_16x16x32_bf16 v[114:117], v[184:187], v[192:195], v[114:117]
	v_mfma_f32_16x16x32_bf16 v[102:105], v[176:179], v[200:203], v[102:105]
	v_mfma_f32_16x16x32_bf16 v[98:101], v[184:187], v[200:203], v[98:101]
	v_mfma_f32_16x16x32_bf16 v[86:89], v[176:179], v[208:211], v[86:89]
	v_mfma_f32_16x16x32_bf16 v[82:85], v[184:187], v[208:211], v[82:85]
	v_mfma_f32_16x16x32_bf16 v[70:73], v[176:179], v[216:219], v[70:73]
	v_mfma_f32_16x16x32_bf16 v[66:69], v[184:187], v[216:219], v[66:69]
	s_setprio 0
	s_barrier
	s_add_i32 s20, s77, s64
	v_lshl_add_u64 v[220:221], s[54:55], 0, v[146:147]
	s_mov_b32 m0, s20
	ds_read_b128 v[188:191], v174 offset:16384
	ds_read_b128 v[192:195], v174 offset:17408
	ds_read_b128 v[196:199], v174 offset:18432
	ds_read_b128 v[200:203], v174 offset:19456
	ds_read_b128 v[204:207], v174 offset:20480
	ds_read_b128 v[208:211], v174 offset:21504
	ds_read_b128 v[212:215], v174 offset:22528
	ds_read_b128 v[216:219], v174 offset:23552
	global_load_lds_dwordx4 v[220:221], off
	s_add_i32 m0, s20, 0x2000
	s_add_u32 s20, s54, 0x80000
	v_lshl_add_u64 v[222:223], s[54:55], 0, v[148:149]
	s_addc_u32 s21, s55, 0
	s_add_i32 s43, s78, s64
	global_load_lds_dwordx4 v[222:223], off
	v_lshl_add_u64 v[224:225], s[20:21], 0, v[146:147]
	s_mov_b32 m0, s43
	v_lshl_add_u64 v[226:227], s[56:57], 0, v[148:149]
	global_load_lds_dwordx4 v[224:225], off
	v_lshl_add_u64 v[224:225], s[20:21], 0, v[148:149]
	s_add_i32 m0, s43, 0x2000
	s_nop 0
	global_load_lds_dwordx4 v[224:225], off
	v_lshl_add_u64 v[224:225], s[56:57], 0, v[146:147]
	s_mov_b32 m0, s65
	s_nop 0
	global_load_lds_dwordx4 v[224:225], off
	s_mov_b32 m0, s66
	s_nop 0
	global_load_lds_dwordx4 v[226:227], off
	s_waitcnt vmcnt(8)
	s_waitcnt lgkmcnt(0)
	s_waitcnt lgkmcnt(0)
	v_mfma_f32_16x16x32_bf16 v[62:65], v[130:133], v[188:191], v[62:65]
	v_mfma_f32_16x16x32_bf16 v[58:61], v[138:141], v[188:191], v[58:61]
	v_mfma_f32_16x16x32_bf16 v[46:49], v[130:133], v[196:199], v[46:49]
	v_mfma_f32_16x16x32_bf16 v[42:45], v[138:141], v[196:199], v[42:45]
	s_barrier
	s_setprio 1
	v_mfma_f32_16x16x32_bf16 v[30:33], v[130:133], v[204:207], v[30:33]
	v_mfma_f32_16x16x32_bf16 v[26:29], v[138:141], v[204:207], v[26:29]
	v_mfma_f32_16x16x32_bf16 v[14:17], v[130:133], v[212:215], v[14:17]
	v_mfma_f32_16x16x32_bf16 v[10:13], v[138:141], v[212:215], v[10:13]
	v_mfma_f32_16x16x32_bf16 v[62:65], v[134:137], v[192:195], v[62:65]
	v_mfma_f32_16x16x32_bf16 v[58:61], v[142:145], v[192:195], v[58:61]
	v_mfma_f32_16x16x32_bf16 v[46:49], v[134:137], v[200:203], v[46:49]
	v_mfma_f32_16x16x32_bf16 v[42:45], v[142:145], v[200:203], v[42:45]
	v_mfma_f32_16x16x32_bf16 v[30:33], v[134:137], v[208:211], v[30:33]
	v_mfma_f32_16x16x32_bf16 v[26:29], v[142:145], v[208:211], v[26:29]
	v_mfma_f32_16x16x32_bf16 v[14:17], v[134:137], v[216:219], v[14:17]
	v_mfma_f32_16x16x32_bf16 v[10:13], v[142:145], v[216:219], v[10:13]
	v_mfma_f32_16x16x32_bf16 v[54:57], v[166:169], v[188:191], v[54:57]
	v_mfma_f32_16x16x32_bf16 v[50:53], v[180:183], v[188:191], v[50:53]
	v_mfma_f32_16x16x32_bf16 v[38:41], v[166:169], v[196:199], v[38:41]
	v_mfma_f32_16x16x32_bf16 v[34:37], v[180:183], v[196:199], v[34:37]
	v_mfma_f32_16x16x32_bf16 v[22:25], v[166:169], v[204:207], v[22:25]
	v_mfma_f32_16x16x32_bf16 v[18:21], v[180:183], v[204:207], v[18:21]
	v_mfma_f32_16x16x32_bf16 v[6:9], v[166:169], v[212:215], v[6:9]
	v_mfma_f32_16x16x32_bf16 v[2:5], v[180:183], v[212:215], v[2:5]
	v_mfma_f32_16x16x32_bf16 v[54:57], v[176:179], v[192:195], v[54:57]
	v_mfma_f32_16x16x32_bf16 v[50:53], v[184:187], v[192:195], v[50:53]
	v_mfma_f32_16x16x32_bf16 v[38:41], v[176:179], v[200:203], v[38:41]
	v_mfma_f32_16x16x32_bf16 v[34:37], v[184:187], v[200:203], v[34:37]
	v_mfma_f32_16x16x32_bf16 v[22:25], v[176:179], v[208:211], v[22:25]
	v_mfma_f32_16x16x32_bf16 v[18:21], v[184:187], v[208:211], v[18:21]
	v_mfma_f32_16x16x32_bf16 v[6:9], v[176:179], v[216:219], v[6:9]
	v_mfma_f32_16x16x32_bf16 v[2:5], v[184:187], v[216:219], v[2:5]
	s_setprio 0
	s_barrier
	s_add_i32 s43, 0, 0x18000
	s_add_i32 s45, 0, 0x1c000
	v_add_u32_e32 v142, s43, v170
	v_add_u32_e32 v184, s45, v170
	ds_read_b128 v[130:133], v142
	ds_read_b128 v[134:137], v142 offset:1024
	ds_read_b128 v[138:141], v142 offset:2048
	ds_read_b128 v[142:145], v142 offset:3072
	ds_read_b128 v[166:169], v184
	ds_read_b128 v[176:179], v184 offset:1024
	ds_read_b128 v[180:183], v184 offset:2048
	ds_read_b128 v[184:187], v184 offset:3072
	s_add_u32 s20, s56, 0x80000
	s_addc_u32 s21, s57, 0
	s_mov_b32 m0, s67
	v_lshl_add_u64 v[228:229], s[20:21], 0, v[146:147]
	ds_read_b128 v[188:191], v174 offset:32768
	ds_read_b128 v[192:195], v174 offset:33792
	ds_read_b128 v[196:199], v174 offset:34816
	ds_read_b128 v[200:203], v174 offset:35840
	ds_read_b128 v[204:207], v174 offset:36864
	ds_read_b128 v[208:211], v174 offset:37888
	ds_read_b128 v[212:215], v174 offset:38912
	ds_read_b128 v[216:219], v174 offset:39936
	global_load_lds_dwordx4 v[228:229], off
	v_lshl_add_u64 v[228:229], s[20:21], 0, v[148:149]
	s_mov_b32 m0, s68
	s_nop 0
	global_load_lds_dwordx4 v[228:229], off
	s_waitcnt vmcnt(8)
	s_waitcnt lgkmcnt(0)
	s_waitcnt lgkmcnt(0)
	v_mfma_f32_16x16x32_bf16 v[126:129], v[130:133], v[188:191], v[126:129]
	v_mfma_f32_16x16x32_bf16 v[122:125], v[138:141], v[188:191], v[122:125]
	v_mfma_f32_16x16x32_bf16 v[110:113], v[130:133], v[196:199], v[110:113]
	v_mfma_f32_16x16x32_bf16 v[106:109], v[138:141], v[196:199], v[106:109]
	s_barrier
	s_setprio 1
	v_mfma_f32_16x16x32_bf16 v[94:97], v[130:133], v[204:207], v[94:97]
	v_mfma_f32_16x16x32_bf16 v[90:93], v[138:141], v[204:207], v[90:93]
	v_mfma_f32_16x16x32_bf16 v[78:81], v[130:133], v[212:215], v[78:81]
	v_mfma_f32_16x16x32_bf16 v[74:77], v[138:141], v[212:215], v[74:77]
	v_mfma_f32_16x16x32_bf16 v[126:129], v[134:137], v[192:195], v[126:129]
	v_mfma_f32_16x16x32_bf16 v[122:125], v[142:145], v[192:195], v[122:125]
	v_mfma_f32_16x16x32_bf16 v[110:113], v[134:137], v[200:203], v[110:113]
	v_mfma_f32_16x16x32_bf16 v[106:109], v[142:145], v[200:203], v[106:109]
	v_mfma_f32_16x16x32_bf16 v[94:97], v[134:137], v[208:211], v[94:97]
	v_mfma_f32_16x16x32_bf16 v[90:93], v[142:145], v[208:211], v[90:93]
	v_mfma_f32_16x16x32_bf16 v[78:81], v[134:137], v[216:219], v[78:81]
	v_mfma_f32_16x16x32_bf16 v[74:77], v[142:145], v[216:219], v[74:77]
	v_mfma_f32_16x16x32_bf16 v[118:121], v[166:169], v[188:191], v[118:121]
	v_mfma_f32_16x16x32_bf16 v[114:117], v[180:183], v[188:191], v[114:117]
	v_mfma_f32_16x16x32_bf16 v[102:105], v[166:169], v[196:199], v[102:105]
	v_mfma_f32_16x16x32_bf16 v[98:101], v[180:183], v[196:199], v[98:101]
	v_mfma_f32_16x16x32_bf16 v[86:89], v[166:169], v[204:207], v[86:89]
	v_mfma_f32_16x16x32_bf16 v[82:85], v[180:183], v[204:207], v[82:85]
	v_mfma_f32_16x16x32_bf16 v[70:73], v[166:169], v[212:215], v[70:73]
	v_mfma_f32_16x16x32_bf16 v[66:69], v[180:183], v[212:215], v[66:69]
	v_mfma_f32_16x16x32_bf16 v[118:121], v[176:179], v[192:195], v[118:121]
	v_mfma_f32_16x16x32_bf16 v[114:117], v[184:187], v[192:195], v[114:117]
	v_mfma_f32_16x16x32_bf16 v[102:105], v[176:179], v[200:203], v[102:105]
	v_mfma_f32_16x16x32_bf16 v[98:101], v[184:187], v[200:203], v[98:101]
	v_mfma_f32_16x16x32_bf16 v[86:89], v[176:179], v[208:211], v[86:89]
	v_mfma_f32_16x16x32_bf16 v[82:85], v[184:187], v[208:211], v[82:85]
	v_mfma_f32_16x16x32_bf16 v[70:73], v[176:179], v[216:219], v[70:73]
	v_mfma_f32_16x16x32_bf16 v[66:69], v[184:187], v[216:219], v[66:69]
	s_setprio 0
	s_barrier
	s_add_i32 s20, s43, s64
	v_lshl_add_u64 v[220:221], v[220:221], 0, s[26:27]
	s_mov_b32 m0, s20
	ds_read_b128 v[188:191], v174 offset:49152
	ds_read_b128 v[192:195], v174 offset:50176
	ds_read_b128 v[196:199], v174 offset:51200
	ds_read_b128 v[200:203], v174 offset:52224
	ds_read_b128 v[204:207], v174 offset:53248
	ds_read_b128 v[208:211], v174 offset:54272
	ds_read_b128 v[212:215], v174 offset:55296
	ds_read_b128 v[216:219], v174 offset:56320
	global_load_lds_dwordx4 v[220:221], off
	s_add_i32 m0, s20, 0x2000
	s_add_u32 s20, s54, 0x80080
	v_lshl_add_u64 v[220:221], v[222:223], 0, s[26:27]
	s_addc_u32 s21, s55, 0
	s_add_i32 s43, s45, s64
	global_load_lds_dwordx4 v[220:221], off
	v_lshl_add_u64 v[220:221], s[20:21], 0, v[146:147]
	s_mov_b32 m0, s43
	s_nop 0
	global_load_lds_dwordx4 v[220:221], off
	v_lshl_add_u64 v[220:221], s[20:21], 0, v[148:149]
	s_add_i32 m0, s43, 0x2000
	s_nop 0
	global_load_lds_dwordx4 v[220:221], off
	v_lshl_add_u64 v[220:221], v[224:225], 0, s[26:27]
	s_mov_b32 m0, s73
	s_nop 0
	global_load_lds_dwordx4 v[220:221], off
	v_lshl_add_u64 v[220:221], v[226:227], 0, s[26:27]
	s_mov_b32 m0, s74
	s_nop 0
	global_load_lds_dwordx4 v[220:221], off
	s_waitcnt vmcnt(8)
	s_waitcnt lgkmcnt(0)
	s_waitcnt lgkmcnt(0)
	v_mfma_f32_16x16x32_bf16 v[62:65], v[130:133], v[188:191], v[62:65]
	v_mfma_f32_16x16x32_bf16 v[58:61], v[138:141], v[188:191], v[58:61]
	v_mfma_f32_16x16x32_bf16 v[46:49], v[130:133], v[196:199], v[46:49]
	v_mfma_f32_16x16x32_bf16 v[42:45], v[138:141], v[196:199], v[42:45]
	s_barrier
	s_setprio 1
	v_mfma_f32_16x16x32_bf16 v[30:33], v[130:133], v[204:207], v[30:33]
	v_mfma_f32_16x16x32_bf16 v[26:29], v[138:141], v[204:207], v[26:29]
	v_mfma_f32_16x16x32_bf16 v[14:17], v[130:133], v[212:215], v[14:17]
	v_mfma_f32_16x16x32_bf16 v[10:13], v[138:141], v[212:215], v[10:13]
	v_mfma_f32_16x16x32_bf16 v[62:65], v[134:137], v[192:195], v[62:65]
	v_mfma_f32_16x16x32_bf16 v[58:61], v[142:145], v[192:195], v[58:61]
	v_mfma_f32_16x16x32_bf16 v[46:49], v[134:137], v[200:203], v[46:49]
	v_mfma_f32_16x16x32_bf16 v[42:45], v[142:145], v[200:203], v[42:45]
	v_mfma_f32_16x16x32_bf16 v[30:33], v[134:137], v[208:211], v[30:33]
	v_mfma_f32_16x16x32_bf16 v[26:29], v[142:145], v[208:211], v[26:29]
	v_mfma_f32_16x16x32_bf16 v[14:17], v[134:137], v[216:219], v[14:17]
	v_mfma_f32_16x16x32_bf16 v[10:13], v[142:145], v[216:219], v[10:13]
	v_mfma_f32_16x16x32_bf16 v[54:57], v[166:169], v[188:191], v[54:57]
	v_mfma_f32_16x16x32_bf16 v[50:53], v[180:183], v[188:191], v[50:53]
	v_mfma_f32_16x16x32_bf16 v[38:41], v[166:169], v[196:199], v[38:41]
	v_mfma_f32_16x16x32_bf16 v[34:37], v[180:183], v[196:199], v[34:37]
	v_mfma_f32_16x16x32_bf16 v[22:25], v[166:169], v[204:207], v[22:25]
	v_mfma_f32_16x16x32_bf16 v[18:21], v[180:183], v[204:207], v[18:21]
	v_mfma_f32_16x16x32_bf16 v[6:9], v[166:169], v[212:215], v[6:9]
	v_mfma_f32_16x16x32_bf16 v[2:5], v[180:183], v[212:215], v[2:5]
	v_mfma_f32_16x16x32_bf16 v[54:57], v[176:179], v[192:195], v[54:57]
	v_mfma_f32_16x16x32_bf16 v[50:53], v[184:187], v[192:195], v[50:53]
	v_mfma_f32_16x16x32_bf16 v[38:41], v[176:179], v[200:203], v[38:41]
	v_mfma_f32_16x16x32_bf16 v[34:37], v[184:187], v[200:203], v[34:37]
	v_mfma_f32_16x16x32_bf16 v[22:25], v[176:179], v[208:211], v[22:25]
	v_mfma_f32_16x16x32_bf16 v[18:21], v[184:187], v[208:211], v[18:21]
	v_mfma_f32_16x16x32_bf16 v[6:9], v[176:179], v[216:219], v[6:9]
	v_mfma_f32_16x16x32_bf16 v[2:5], v[184:187], v[216:219], v[2:5]
	s_setprio 0
	s_barrier
	s_add_i32 s19, s19, 2
	s_add_u32 s52, s52, 0x100
	s_addc_u32 s53, s53, 0
	s_add_u32 s17, s17, 0x100
	s_addc_u32 s18, s18, 0
	s_cmp_gt_u32 s19, 29
	s_cbranch_scc0 .LBB0_986
	s_and_b64 vcc, exec, s[28:29]
	s_cbranch_vccnz .LBB0_991
	v_lshl_add_u32 v166, s50, 8, v163
	s_cmp_gt_i32 s10, 1
	s_mov_b64 s[50:51], -1
	s_cbranch_scc1 .LBB0_992

.LBB0_1213:
	ds_read_b128 v[130:133], v189
	ds_read_b128 v[134:137], v189 offset:1024
	ds_read_b128 v[138:141], v189 offset:2048
	ds_read_b128 v[142:145], v189 offset:3072
	ds_read_b128 v[164:167], v190
	ds_read_b128 v[168:171], v190 offset:1024
	ds_read_b128 v[172:175], v190 offset:2048
	ds_read_b128 v[194:197], v190 offset:3072
	s_add_u32 s20, s52, 0xfff80080
	s_addc_u32 s21, s53, -1
	s_cmp_eq_u32 s19, 28
	s_cselect_b32 s57, s3, s21
	s_cselect_b32 s56, s14, s20
	s_cselect_b32 s55, s15, s18
	s_cselect_b32 s54, s16, s17
	v_lshl_add_u64 v[230:231], s[52:53], 0, v[154:155]
	s_add_i32 m0, s65, 0xc000
	ds_read_b128 v[198:201], v191
	ds_read_b128 v[202:205], v191 offset:1024
	ds_read_b128 v[206:209], v191 offset:2048
	ds_read_b128 v[210:213], v191 offset:3072
	ds_read_b128 v[214:217], v191 offset:4096
	ds_read_b128 v[218:221], v191 offset:5120
	ds_read_b128 v[222:225], v191 offset:6144
	ds_read_b128 v[226:229], v191 offset:7168
	global_load_lds_dwordx4 v[230:231], off
	v_lshl_add_u64 v[230:231], s[52:53], 0, v[156:157]
	s_add_i32 m0, s65, 0xe000
	s_nop 0
	global_load_lds_dwordx4 v[230:231], off
	s_waitcnt vmcnt(8)
	s_waitcnt lgkmcnt(0)
	s_waitcnt lgkmcnt(0)
	v_mfma_f32_16x16x32_bf16 v[126:129], v[130:133], v[198:201], v[126:129]
	v_mfma_f32_16x16x32_bf16 v[122:125], v[138:141], v[198:201], v[122:125]
	v_mfma_f32_16x16x32_bf16 v[110:113], v[130:133], v[206:209], v[110:113]
	v_mfma_f32_16x16x32_bf16 v[106:109], v[138:141], v[206:209], v[106:109]
	s_barrier
	s_setprio 1
	v_mfma_f32_16x16x32_bf16 v[94:97], v[130:133], v[214:217], v[94:97]
	v_mfma_f32_16x16x32_bf16 v[90:93], v[138:141], v[214:217], v[90:93]
	v_mfma_f32_16x16x32_bf16 v[78:81], v[130:133], v[222:225], v[78:81]
	v_mfma_f32_16x16x32_bf16 v[74:77], v[138:141], v[222:225], v[74:77]
	v_mfma_f32_16x16x32_bf16 v[126:129], v[134:137], v[202:205], v[126:129]
	v_mfma_f32_16x16x32_bf16 v[122:125], v[142:145], v[202:205], v[122:125]
	v_mfma_f32_16x16x32_bf16 v[110:113], v[134:137], v[210:213], v[110:113]
	v_mfma_f32_16x16x32_bf16 v[106:109], v[142:145], v[210:213], v[106:109]
	v_mfma_f32_16x16x32_bf16 v[94:97], v[134:137], v[218:221], v[94:97]
	v_mfma_f32_16x16x32_bf16 v[90:93], v[142:145], v[218:221], v[90:93]
	v_mfma_f32_16x16x32_bf16 v[78:81], v[134:137], v[226:229], v[78:81]
	v_mfma_f32_16x16x32_bf16 v[74:77], v[142:145], v[226:229], v[74:77]
	v_mfma_f32_16x16x32_bf16 v[118:121], v[164:167], v[198:201], v[118:121]
	v_mfma_f32_16x16x32_bf16 v[114:117], v[172:175], v[198:201], v[114:117]
	v_mfma_f32_16x16x32_bf16 v[102:105], v[164:167], v[206:209], v[102:105]
	v_mfma_f32_16x16x32_bf16 v[98:101], v[172:175], v[206:209], v[98:101]
	v_mfma_f32_16x16x32_bf16 v[86:89], v[164:167], v[214:217], v[86:89]
	v_mfma_f32_16x16x32_bf16 v[82:85], v[172:175], v[214:217], v[82:85]
	v_mfma_f32_16x16x32_bf16 v[70:73], v[164:167], v[222:225], v[70:73]
	v_mfma_f32_16x16x32_bf16 v[66:69], v[172:175], v[222:225], v[66:69]
	v_mfma_f32_16x16x32_bf16 v[118:121], v[168:171], v[202:205], v[118:121]
	v_mfma_f32_16x16x32_bf16 v[114:117], v[194:197], v[202:205], v[114:117]
	v_mfma_f32_16x16x32_bf16 v[102:105], v[168:171], v[210:213], v[102:105]
	v_mfma_f32_16x16x32_bf16 v[98:101], v[194:197], v[210:213], v[98:101]
	v_mfma_f32_16x16x32_bf16 v[86:89], v[168:171], v[218:221], v[86:89]
	v_mfma_f32_16x16x32_bf16 v[82:85], v[194:197], v[218:221], v[82:85]
	v_mfma_f32_16x16x32_bf16 v[70:73], v[168:171], v[226:229], v[70:73]
	v_mfma_f32_16x16x32_bf16 v[66:69], v[194:197], v[226:229], v[66:69]
	s_setprio 0
	s_barrier
	s_add_i32 s20, s77, s64
	v_lshl_add_u64 v[230:231], s[54:55], 0, v[146:147]
	s_mov_b32 m0, s20
	ds_read_b128 v[198:201], v191 offset:16384
	ds_read_b128 v[202:205], v191 offset:17408
	ds_read_b128 v[206:209], v191 offset:18432
	ds_read_b128 v[210:213], v191 offset:19456
	ds_read_b128 v[214:217], v191 offset:20480
	ds_read_b128 v[218:221], v191 offset:21504
	ds_read_b128 v[222:225], v191 offset:22528
	ds_read_b128 v[226:229], v191 offset:23552
	global_load_lds_dwordx4 v[230:231], off
	s_add_i32 m0, s20, 0x2000
	s_add_u32 s20, s54, 0x80000
	v_lshl_add_u64 v[232:233], s[54:55], 0, v[148:149]
	s_addc_u32 s21, s55, 0
	s_add_i32 s43, s78, s64
	global_load_lds_dwordx4 v[232:233], off
	v_lshl_add_u64 v[234:235], s[20:21], 0, v[146:147]
	s_mov_b32 m0, s43
	v_lshl_add_u64 v[236:237], s[56:57], 0, v[148:149]
	global_load_lds_dwordx4 v[234:235], off
	v_lshl_add_u64 v[234:235], s[20:21], 0, v[148:149]
	s_add_i32 m0, s43, 0x2000
	s_nop 0
	global_load_lds_dwordx4 v[234:235], off
	v_lshl_add_u64 v[234:235], s[56:57], 0, v[146:147]
	s_mov_b32 m0, s65
	s_nop 0
	global_load_lds_dwordx4 v[234:235], off
	s_mov_b32 m0, s66
	s_nop 0
	global_load_lds_dwordx4 v[236:237], off
	s_waitcnt vmcnt(8)
	s_waitcnt lgkmcnt(0)
	s_waitcnt lgkmcnt(0)
	v_mfma_f32_16x16x32_bf16 v[62:65], v[130:133], v[198:201], v[62:65]
	v_mfma_f32_16x16x32_bf16 v[58:61], v[138:141], v[198:201], v[58:61]
	v_mfma_f32_16x16x32_bf16 v[46:49], v[130:133], v[206:209], v[46:49]
	v_mfma_f32_16x16x32_bf16 v[42:45], v[138:141], v[206:209], v[42:45]
	s_barrier
	s_setprio 1
	v_mfma_f32_16x16x32_bf16 v[30:33], v[130:133], v[214:217], v[30:33]
	v_mfma_f32_16x16x32_bf16 v[26:29], v[138:141], v[214:217], v[26:29]
	v_mfma_f32_16x16x32_bf16 v[14:17], v[130:133], v[222:225], v[14:17]
	v_mfma_f32_16x16x32_bf16 v[10:13], v[138:141], v[222:225], v[10:13]
	v_mfma_f32_16x16x32_bf16 v[62:65], v[134:137], v[202:205], v[62:65]
	v_mfma_f32_16x16x32_bf16 v[58:61], v[142:145], v[202:205], v[58:61]
	v_mfma_f32_16x16x32_bf16 v[46:49], v[134:137], v[210:213], v[46:49]
	v_mfma_f32_16x16x32_bf16 v[42:45], v[142:145], v[210:213], v[42:45]
	v_mfma_f32_16x16x32_bf16 v[30:33], v[134:137], v[218:221], v[30:33]
	v_mfma_f32_16x16x32_bf16 v[26:29], v[142:145], v[218:221], v[26:29]
	v_mfma_f32_16x16x32_bf16 v[14:17], v[134:137], v[226:229], v[14:17]
	v_mfma_f32_16x16x32_bf16 v[10:13], v[142:145], v[226:229], v[10:13]
	v_mfma_f32_16x16x32_bf16 v[54:57], v[164:167], v[198:201], v[54:57]
	v_mfma_f32_16x16x32_bf16 v[50:53], v[172:175], v[198:201], v[50:53]
	v_mfma_f32_16x16x32_bf16 v[38:41], v[164:167], v[206:209], v[38:41]
	v_mfma_f32_16x16x32_bf16 v[34:37], v[172:175], v[206:209], v[34:37]
	v_mfma_f32_16x16x32_bf16 v[22:25], v[164:167], v[214:217], v[22:25]
	v_mfma_f32_16x16x32_bf16 v[18:21], v[172:175], v[214:217], v[18:21]
	v_mfma_f32_16x16x32_bf16 v[6:9], v[164:167], v[222:225], v[6:9]
	v_mfma_f32_16x16x32_bf16 v[2:5], v[172:175], v[222:225], v[2:5]
	v_mfma_f32_16x16x32_bf16 v[54:57], v[168:171], v[202:205], v[54:57]
	v_mfma_f32_16x16x32_bf16 v[50:53], v[194:197], v[202:205], v[50:53]
	v_mfma_f32_16x16x32_bf16 v[38:41], v[168:171], v[210:213], v[38:41]
	v_mfma_f32_16x16x32_bf16 v[34:37], v[194:197], v[210:213], v[34:37]
	v_mfma_f32_16x16x32_bf16 v[22:25], v[168:171], v[218:221], v[22:25]
	v_mfma_f32_16x16x32_bf16 v[18:21], v[194:197], v[218:221], v[18:21]
	v_mfma_f32_16x16x32_bf16 v[6:9], v[168:171], v[226:229], v[6:9]
	v_mfma_f32_16x16x32_bf16 v[2:5], v[194:197], v[226:229], v[2:5]
	s_setprio 0
	s_barrier
	s_add_i32 s43, 0, 0x18000
	s_add_i32 s45, 0, 0x1c000
	v_add_u32_e32 v142, s43, v187
	v_add_u32_e32 v193, s45, v187
	ds_read_b128 v[130:133], v142
	ds_read_b128 v[134:137], v142 offset:1024
	ds_read_b128 v[138:141], v142 offset:2048
	ds_read_b128 v[142:145], v142 offset:3072
	ds_read_b128 v[164:167], v193
	ds_read_b128 v[168:171], v193 offset:1024
	ds_read_b128 v[172:175], v193 offset:2048
	ds_read_b128 v[194:197], v193 offset:3072
	s_add_u32 s20, s56, 0x80000
	s_addc_u32 s21, s57, 0
	s_mov_b32 m0, s67
	v_lshl_add_u64 v[238:239], s[20:21], 0, v[146:147]
	ds_read_b128 v[198:201], v191 offset:32768
	ds_read_b128 v[202:205], v191 offset:33792
	ds_read_b128 v[206:209], v191 offset:34816
	ds_read_b128 v[210:213], v191 offset:35840
	ds_read_b128 v[214:217], v191 offset:36864
	ds_read_b128 v[218:221], v191 offset:37888
	ds_read_b128 v[222:225], v191 offset:38912
	ds_read_b128 v[226:229], v191 offset:39936
	global_load_lds_dwordx4 v[238:239], off
	v_lshl_add_u64 v[238:239], s[20:21], 0, v[148:149]
	s_mov_b32 m0, s68
	s_nop 0
	global_load_lds_dwordx4 v[238:239], off
	s_waitcnt vmcnt(8)
	s_waitcnt lgkmcnt(0)
	s_waitcnt lgkmcnt(0)
	v_mfma_f32_16x16x32_bf16 v[126:129], v[130:133], v[198:201], v[126:129]
	v_mfma_f32_16x16x32_bf16 v[122:125], v[138:141], v[198:201], v[122:125]
	v_mfma_f32_16x16x32_bf16 v[110:113], v[130:133], v[206:209], v[110:113]
	v_mfma_f32_16x16x32_bf16 v[106:109], v[138:141], v[206:209], v[106:109]
	s_barrier
	s_setprio 1
	v_mfma_f32_16x16x32_bf16 v[94:97], v[130:133], v[214:217], v[94:97]
	v_mfma_f32_16x16x32_bf16 v[90:93], v[138:141], v[214:217], v[90:93]
	v_mfma_f32_16x16x32_bf16 v[78:81], v[130:133], v[222:225], v[78:81]
	v_mfma_f32_16x16x32_bf16 v[74:77], v[138:141], v[222:225], v[74:77]
	v_mfma_f32_16x16x32_bf16 v[126:129], v[134:137], v[202:205], v[126:129]
	v_mfma_f32_16x16x32_bf16 v[122:125], v[142:145], v[202:205], v[122:125]
	v_mfma_f32_16x16x32_bf16 v[110:113], v[134:137], v[210:213], v[110:113]
	v_mfma_f32_16x16x32_bf16 v[106:109], v[142:145], v[210:213], v[106:109]
	v_mfma_f32_16x16x32_bf16 v[94:97], v[134:137], v[218:221], v[94:97]
	v_mfma_f32_16x16x32_bf16 v[90:93], v[142:145], v[218:221], v[90:93]
	v_mfma_f32_16x16x32_bf16 v[78:81], v[134:137], v[226:229], v[78:81]
	v_mfma_f32_16x16x32_bf16 v[74:77], v[142:145], v[226:229], v[74:77]
	v_mfma_f32_16x16x32_bf16 v[118:121], v[164:167], v[198:201], v[118:121]
	v_mfma_f32_16x16x32_bf16 v[114:117], v[172:175], v[198:201], v[114:117]
	v_mfma_f32_16x16x32_bf16 v[102:105], v[164:167], v[206:209], v[102:105]
	v_mfma_f32_16x16x32_bf16 v[98:101], v[172:175], v[206:209], v[98:101]
	v_mfma_f32_16x16x32_bf16 v[86:89], v[164:167], v[214:217], v[86:89]
	v_mfma_f32_16x16x32_bf16 v[82:85], v[172:175], v[214:217], v[82:85]
	v_mfma_f32_16x16x32_bf16 v[70:73], v[164:167], v[222:225], v[70:73]
	v_mfma_f32_16x16x32_bf16 v[66:69], v[172:175], v[222:225], v[66:69]
	v_mfma_f32_16x16x32_bf16 v[118:121], v[168:171], v[202:205], v[118:121]
	v_mfma_f32_16x16x32_bf16 v[114:117], v[194:197], v[202:205], v[114:117]
	v_mfma_f32_16x16x32_bf16 v[102:105], v[168:171], v[210:213], v[102:105]
	v_mfma_f32_16x16x32_bf16 v[98:101], v[194:197], v[210:213], v[98:101]
	v_mfma_f32_16x16x32_bf16 v[86:89], v[168:171], v[218:221], v[86:89]
	v_mfma_f32_16x16x32_bf16 v[82:85], v[194:197], v[218:221], v[82:85]
	v_mfma_f32_16x16x32_bf16 v[70:73], v[168:171], v[226:229], v[70:73]
	v_mfma_f32_16x16x32_bf16 v[66:69], v[194:197], v[226:229], v[66:69]
	s_setprio 0
	s_barrier
	s_add_i32 s20, s43, s64
	v_lshl_add_u64 v[230:231], v[230:231], 0, s[26:27]
	s_mov_b32 m0, s20
	ds_read_b128 v[198:201], v191 offset:49152
	ds_read_b128 v[202:205], v191 offset:50176
	ds_read_b128 v[206:209], v191 offset:51200
	ds_read_b128 v[210:213], v191 offset:52224
	ds_read_b128 v[214:217], v191 offset:53248
	ds_read_b128 v[218:221], v191 offset:54272
	ds_read_b128 v[222:225], v191 offset:55296
	ds_read_b128 v[226:229], v191 offset:56320
	global_load_lds_dwordx4 v[230:231], off
	s_add_i32 m0, s20, 0x2000
	s_add_u32 s20, s54, 0x80080
	v_lshl_add_u64 v[230:231], v[232:233], 0, s[26:27]
	s_addc_u32 s21, s55, 0
	s_add_i32 s43, s45, s64
	global_load_lds_dwordx4 v[230:231], off
	v_lshl_add_u64 v[230:231], s[20:21], 0, v[146:147]
	s_mov_b32 m0, s43
	s_nop 0
	global_load_lds_dwordx4 v[230:231], off
	v_lshl_add_u64 v[230:231], s[20:21], 0, v[148:149]
	s_add_i32 m0, s43, 0x2000
	s_nop 0
	global_load_lds_dwordx4 v[230:231], off
	v_lshl_add_u64 v[230:231], v[234:235], 0, s[26:27]
	s_mov_b32 m0, s73
	s_nop 0
	global_load_lds_dwordx4 v[230:231], off
	v_lshl_add_u64 v[230:231], v[236:237], 0, s[26:27]
	s_mov_b32 m0, s74
	s_nop 0
	global_load_lds_dwordx4 v[230:231], off
	s_waitcnt vmcnt(8)
	s_waitcnt lgkmcnt(0)
	s_waitcnt lgkmcnt(0)
	v_mfma_f32_16x16x32_bf16 v[62:65], v[130:133], v[198:201], v[62:65]
	v_mfma_f32_16x16x32_bf16 v[58:61], v[138:141], v[198:201], v[58:61]
	v_mfma_f32_16x16x32_bf16 v[46:49], v[130:133], v[206:209], v[46:49]
	v_mfma_f32_16x16x32_bf16 v[42:45], v[138:141], v[206:209], v[42:45]
	s_barrier
	s_setprio 1
	v_mfma_f32_16x16x32_bf16 v[30:33], v[130:133], v[214:217], v[30:33]
	v_mfma_f32_16x16x32_bf16 v[26:29], v[138:141], v[214:217], v[26:29]
	v_mfma_f32_16x16x32_bf16 v[14:17], v[130:133], v[222:225], v[14:17]
	v_mfma_f32_16x16x32_bf16 v[10:13], v[138:141], v[222:225], v[10:13]
	v_mfma_f32_16x16x32_bf16 v[62:65], v[134:137], v[202:205], v[62:65]
	v_mfma_f32_16x16x32_bf16 v[58:61], v[142:145], v[202:205], v[58:61]
	v_mfma_f32_16x16x32_bf16 v[46:49], v[134:137], v[210:213], v[46:49]
	v_mfma_f32_16x16x32_bf16 v[42:45], v[142:145], v[210:213], v[42:45]
	v_mfma_f32_16x16x32_bf16 v[30:33], v[134:137], v[218:221], v[30:33]
	v_mfma_f32_16x16x32_bf16 v[26:29], v[142:145], v[218:221], v[26:29]
	v_mfma_f32_16x16x32_bf16 v[14:17], v[134:137], v[226:229], v[14:17]
	v_mfma_f32_16x16x32_bf16 v[10:13], v[142:145], v[226:229], v[10:13]
	v_mfma_f32_16x16x32_bf16 v[54:57], v[164:167], v[198:201], v[54:57]
	v_mfma_f32_16x16x32_bf16 v[50:53], v[172:175], v[198:201], v[50:53]
	v_mfma_f32_16x16x32_bf16 v[38:41], v[164:167], v[206:209], v[38:41]
	v_mfma_f32_16x16x32_bf16 v[34:37], v[172:175], v[206:209], v[34:37]
	v_mfma_f32_16x16x32_bf16 v[22:25], v[164:167], v[214:217], v[22:25]
	v_mfma_f32_16x16x32_bf16 v[18:21], v[172:175], v[214:217], v[18:21]
	v_mfma_f32_16x16x32_bf16 v[6:9], v[164:167], v[222:225], v[6:9]
	v_mfma_f32_16x16x32_bf16 v[2:5], v[172:175], v[222:225], v[2:5]
	v_mfma_f32_16x16x32_bf16 v[54:57], v[168:171], v[202:205], v[54:57]
	v_mfma_f32_16x16x32_bf16 v[50:53], v[194:197], v[202:205], v[50:53]
	v_mfma_f32_16x16x32_bf16 v[38:41], v[168:171], v[210:213], v[38:41]
	v_mfma_f32_16x16x32_bf16 v[34:37], v[194:197], v[210:213], v[34:37]
	v_mfma_f32_16x16x32_bf16 v[22:25], v[168:171], v[218:221], v[22:25]
	v_mfma_f32_16x16x32_bf16 v[18:21], v[194:197], v[218:221], v[18:21]
	v_mfma_f32_16x16x32_bf16 v[6:9], v[168:171], v[226:229], v[6:9]
	v_mfma_f32_16x16x32_bf16 v[2:5], v[194:197], v[226:229], v[2:5]
	s_setprio 0
	s_barrier
	s_add_i32 s19, s19, 2
	s_add_u32 s52, s52, 0x100
	s_addc_u32 s53, s53, 0
	s_add_u32 s17, s17, 0x100
	s_addc_u32 s18, s18, 0
	s_cmp_gt_u32 s19, 29
	s_cbranch_scc0 .LBB0_1213
	s_and_b64 vcc, exec, s[28:29]
	s_cbranch_vccnz .LBB0_1218
	v_lshl_add_u32 v164, s50, 8, v186
	s_cmp_gt_i32 s10, 1
	s_mov_b64 s[50:51], -1
	s_cbranch_scc1 .LBB0_1219

.LBB0_1264:
	ds_read_b128 v[142:145], v163
	ds_read_b128 v[146:149], v163 offset:1024
	ds_read_b128 v[150:153], v163 offset:2048
	ds_read_b128 v[154:157], v163 offset:3072
	ds_read_b128 v[170:173], v166
	ds_read_b128 v[174:177], v166 offset:1024
	ds_read_b128 v[178:181], v166 offset:2048
	ds_read_b128 v[182:185], v166 offset:3072
	s_add_u32 s44, s42, 0xfffe0080
	s_addc_u32 s45, s43, -1
	s_cmp_eq_u32 s29, 4
	s_cselect_b32 s47, s3, s45
	s_cselect_b32 s46, s16, s44
	s_cselect_b32 s45, s17, s27
	s_cselect_b32 s44, s18, s19
	v_lshl_add_u64 v[218:219], s[42:43], 0, v[138:139]
	s_add_i32 m0, s39, 0xc000
	ds_read_b128 v[186:189], v167
	ds_read_b128 v[190:193], v167 offset:1024
	ds_read_b128 v[194:197], v167 offset:2048
	ds_read_b128 v[198:201], v167 offset:3072
	ds_read_b128 v[202:205], v167 offset:4096
	ds_read_b128 v[206:209], v167 offset:5120
	ds_read_b128 v[210:213], v167 offset:6144
	ds_read_b128 v[214:217], v167 offset:7168
	global_load_lds_dwordx4 v[218:219], off
	v_lshl_add_u64 v[218:219], s[42:43], 0, v[140:141]
	s_add_i32 m0, s39, 0xe000
	s_nop 0
	global_load_lds_dwordx4 v[218:219], off
	s_waitcnt vmcnt(8)
	s_waitcnt lgkmcnt(0)
	s_waitcnt lgkmcnt(0)
	v_mfma_f32_16x16x32_bf16 v[126:129], v[142:145], v[186:189], v[126:129]
	v_mfma_f32_16x16x32_bf16 v[122:125], v[150:153], v[186:189], v[122:125]
	v_mfma_f32_16x16x32_bf16 v[118:121], v[142:145], v[194:197], v[118:121]
	v_mfma_f32_16x16x32_bf16 v[110:113], v[150:153], v[194:197], v[110:113]
	s_barrier
	s_setprio 1
	v_mfma_f32_16x16x32_bf16 v[102:105], v[142:145], v[202:205], v[102:105]
	v_mfma_f32_16x16x32_bf16 v[94:97], v[150:153], v[202:205], v[94:97]
	v_mfma_f32_16x16x32_bf16 v[86:89], v[142:145], v[210:213], v[86:89]
	v_mfma_f32_16x16x32_bf16 v[78:81], v[150:153], v[210:213], v[78:81]
	v_mfma_f32_16x16x32_bf16 v[126:129], v[146:149], v[190:193], v[126:129]
	v_mfma_f32_16x16x32_bf16 v[122:125], v[154:157], v[190:193], v[122:125]
	v_mfma_f32_16x16x32_bf16 v[118:121], v[146:149], v[198:201], v[118:121]
	v_mfma_f32_16x16x32_bf16 v[110:113], v[154:157], v[198:201], v[110:113]
	v_mfma_f32_16x16x32_bf16 v[102:105], v[146:149], v[206:209], v[102:105]
	v_mfma_f32_16x16x32_bf16 v[94:97], v[154:157], v[206:209], v[94:97]
	v_mfma_f32_16x16x32_bf16 v[86:89], v[146:149], v[214:217], v[86:89]
	v_mfma_f32_16x16x32_bf16 v[78:81], v[154:157], v[214:217], v[78:81]
	v_mfma_f32_16x16x32_bf16 v[114:117], v[170:173], v[186:189], v[114:117]
	v_mfma_f32_16x16x32_bf16 v[106:109], v[178:181], v[186:189], v[106:109]
	v_mfma_f32_16x16x32_bf16 v[98:101], v[170:173], v[194:197], v[98:101]
	v_mfma_f32_16x16x32_bf16 v[90:93], v[178:181], v[194:197], v[90:93]
	v_mfma_f32_16x16x32_bf16 v[82:85], v[170:173], v[202:205], v[82:85]
	v_mfma_f32_16x16x32_bf16 v[74:77], v[178:181], v[202:205], v[74:77]
	v_mfma_f32_16x16x32_bf16 v[70:73], v[170:173], v[210:213], v[70:73]
	v_mfma_f32_16x16x32_bf16 v[66:69], v[178:181], v[210:213], v[66:69]
	v_mfma_f32_16x16x32_bf16 v[114:117], v[174:177], v[190:193], v[114:117]
	v_mfma_f32_16x16x32_bf16 v[106:109], v[182:185], v[190:193], v[106:109]
	v_mfma_f32_16x16x32_bf16 v[98:101], v[174:177], v[198:201], v[98:101]
	v_mfma_f32_16x16x32_bf16 v[90:93], v[182:185], v[198:201], v[90:93]
	v_mfma_f32_16x16x32_bf16 v[82:85], v[174:177], v[206:209], v[82:85]
	v_mfma_f32_16x16x32_bf16 v[74:77], v[182:185], v[206:209], v[74:77]
	v_mfma_f32_16x16x32_bf16 v[70:73], v[174:177], v[214:217], v[70:73]
	v_mfma_f32_16x16x32_bf16 v[66:69], v[182:185], v[214:217], v[66:69]
	s_setprio 0
	s_barrier
	s_add_i32 s62, s60, s54
	v_lshl_add_u64 v[218:219], s[44:45], 0, v[132:133]
	s_mov_b32 m0, s62
	ds_read_b128 v[186:189], v167 offset:16384
	ds_read_b128 v[190:193], v167 offset:17408
	ds_read_b128 v[194:197], v167 offset:18432
	ds_read_b128 v[198:201], v167 offset:19456
	ds_read_b128 v[202:205], v167 offset:20480
	ds_read_b128 v[206:209], v167 offset:21504
	ds_read_b128 v[210:213], v167 offset:22528
	ds_read_b128 v[214:217], v167 offset:23552
	global_load_lds_dwordx4 v[218:219], off
	s_add_i32 m0, s62, 0x2000
	s_add_u32 s62, s44, 0x20000
	v_lshl_add_u64 v[220:221], s[44:45], 0, v[136:137]
	s_addc_u32 s63, s45, 0
	s_add_i32 s64, s61, s54
	global_load_lds_dwordx4 v[220:221], off
	v_lshl_add_u64 v[222:223], s[62:63], 0, v[132:133]
	s_mov_b32 m0, s64
	v_lshl_add_u64 v[224:225], s[46:47], 0, v[134:135]
	global_load_lds_dwordx4 v[222:223], off
	v_lshl_add_u64 v[222:223], s[62:63], 0, v[136:137]
	s_add_i32 m0, s64, 0x2000
	s_nop 0
	global_load_lds_dwordx4 v[222:223], off
	v_lshl_add_u64 v[222:223], s[46:47], 0, v[130:131]
	s_mov_b32 m0, s39
	s_nop 0
	global_load_lds_dwordx4 v[222:223], off
	s_mov_b32 m0, s41
	s_nop 0
	global_load_lds_dwordx4 v[224:225], off
	s_waitcnt vmcnt(8)
	s_waitcnt lgkmcnt(0)
	s_waitcnt lgkmcnt(0)
	v_mfma_f32_16x16x32_bf16 v[62:65], v[142:145], v[186:189], v[62:65]
	v_mfma_f32_16x16x32_bf16 v[58:61], v[150:153], v[186:189], v[58:61]
	v_mfma_f32_16x16x32_bf16 v[54:57], v[142:145], v[194:197], v[54:57]
	v_mfma_f32_16x16x32_bf16 v[46:49], v[150:153], v[194:197], v[46:49]
	s_barrier
	s_setprio 1
	v_mfma_f32_16x16x32_bf16 v[38:41], v[142:145], v[202:205], v[38:41]
	v_mfma_f32_16x16x32_bf16 v[30:33], v[150:153], v[202:205], v[30:33]
	v_mfma_f32_16x16x32_bf16 v[22:25], v[142:145], v[210:213], v[22:25]
	v_mfma_f32_16x16x32_bf16 v[14:17], v[150:153], v[210:213], v[14:17]
	v_mfma_f32_16x16x32_bf16 v[62:65], v[146:149], v[190:193], v[62:65]
	v_mfma_f32_16x16x32_bf16 v[58:61], v[154:157], v[190:193], v[58:61]
	v_mfma_f32_16x16x32_bf16 v[54:57], v[146:149], v[198:201], v[54:57]
	v_mfma_f32_16x16x32_bf16 v[46:49], v[154:157], v[198:201], v[46:49]
	v_mfma_f32_16x16x32_bf16 v[38:41], v[146:149], v[206:209], v[38:41]
	v_mfma_f32_16x16x32_bf16 v[30:33], v[154:157], v[206:209], v[30:33]
	v_mfma_f32_16x16x32_bf16 v[22:25], v[146:149], v[214:217], v[22:25]
	v_mfma_f32_16x16x32_bf16 v[14:17], v[154:157], v[214:217], v[14:17]
	v_mfma_f32_16x16x32_bf16 v[50:53], v[170:173], v[186:189], v[50:53]
	v_mfma_f32_16x16x32_bf16 v[42:45], v[178:181], v[186:189], v[42:45]
	v_mfma_f32_16x16x32_bf16 v[34:37], v[170:173], v[194:197], v[34:37]
	v_mfma_f32_16x16x32_bf16 v[26:29], v[178:181], v[194:197], v[26:29]
	v_mfma_f32_16x16x32_bf16 v[18:21], v[170:173], v[202:205], v[18:21]
	v_mfma_f32_16x16x32_bf16 v[10:13], v[178:181], v[202:205], v[10:13]
	v_mfma_f32_16x16x32_bf16 v[6:9], v[170:173], v[210:213], v[6:9]
	v_mfma_f32_16x16x32_bf16 v[2:5], v[178:181], v[210:213], v[2:5]
	v_mfma_f32_16x16x32_bf16 v[50:53], v[174:177], v[190:193], v[50:53]
	v_mfma_f32_16x16x32_bf16 v[42:45], v[182:185], v[190:193], v[42:45]
	v_mfma_f32_16x16x32_bf16 v[34:37], v[174:177], v[198:201], v[34:37]
	v_mfma_f32_16x16x32_bf16 v[26:29], v[182:185], v[198:201], v[26:29]
	v_mfma_f32_16x16x32_bf16 v[18:21], v[174:177], v[206:209], v[18:21]
	v_mfma_f32_16x16x32_bf16 v[10:13], v[182:185], v[206:209], v[10:13]
	v_mfma_f32_16x16x32_bf16 v[6:9], v[174:177], v[214:217], v[6:9]
	v_mfma_f32_16x16x32_bf16 v[2:5], v[182:185], v[214:217], v[2:5]
	s_setprio 0
	s_barrier
	s_add_i32 s62, 0, 0x18000
	s_add_i32 s63, 0, 0x1c000
	v_add_u32_e32 v154, s62, v161
	v_add_u32_e32 v158, s63, v161
	ds_read_b128 v[142:145], v154
	ds_read_b128 v[146:149], v154 offset:1024
	ds_read_b128 v[150:153], v154 offset:2048
	ds_read_b128 v[154:157], v154 offset:3072
	ds_read_b128 v[170:173], v158
	ds_read_b128 v[174:177], v158 offset:1024
	ds_read_b128 v[178:181], v158 offset:2048
	ds_read_b128 v[182:185], v158 offset:3072
	s_add_u32 s46, s46, 0x20000
	s_addc_u32 s47, s47, 0
	s_mov_b32 m0, s55
	v_lshl_add_u64 v[226:227], s[46:47], 0, v[130:131]
	ds_read_b128 v[186:189], v167 offset:32768
	ds_read_b128 v[190:193], v167 offset:33792
	ds_read_b128 v[194:197], v167 offset:34816
	ds_read_b128 v[198:201], v167 offset:35840
	ds_read_b128 v[202:205], v167 offset:36864
	ds_read_b128 v[206:209], v167 offset:37888
	ds_read_b128 v[210:213], v167 offset:38912
	ds_read_b128 v[214:217], v167 offset:39936
	global_load_lds_dwordx4 v[226:227], off
	v_lshl_add_u64 v[226:227], s[46:47], 0, v[134:135]
	s_mov_b32 m0, s56
	s_nop 0
	global_load_lds_dwordx4 v[226:227], off
	s_waitcnt vmcnt(8)
	s_waitcnt lgkmcnt(0)
	s_waitcnt lgkmcnt(0)
	v_mfma_f32_16x16x32_bf16 v[126:129], v[142:145], v[186:189], v[126:129]
	v_mfma_f32_16x16x32_bf16 v[122:125], v[150:153], v[186:189], v[122:125]
	v_mfma_f32_16x16x32_bf16 v[118:121], v[142:145], v[194:197], v[118:121]
	v_mfma_f32_16x16x32_bf16 v[110:113], v[150:153], v[194:197], v[110:113]
	s_barrier
	s_setprio 1
	v_mfma_f32_16x16x32_bf16 v[102:105], v[142:145], v[202:205], v[102:105]
	v_mfma_f32_16x16x32_bf16 v[94:97], v[150:153], v[202:205], v[94:97]
	v_mfma_f32_16x16x32_bf16 v[86:89], v[142:145], v[210:213], v[86:89]
	v_mfma_f32_16x16x32_bf16 v[78:81], v[150:153], v[210:213], v[78:81]
	v_mfma_f32_16x16x32_bf16 v[126:129], v[146:149], v[190:193], v[126:129]
	v_mfma_f32_16x16x32_bf16 v[122:125], v[154:157], v[190:193], v[122:125]
	v_mfma_f32_16x16x32_bf16 v[118:121], v[146:149], v[198:201], v[118:121]
	v_mfma_f32_16x16x32_bf16 v[110:113], v[154:157], v[198:201], v[110:113]
	v_mfma_f32_16x16x32_bf16 v[102:105], v[146:149], v[206:209], v[102:105]
	v_mfma_f32_16x16x32_bf16 v[94:97], v[154:157], v[206:209], v[94:97]
	v_mfma_f32_16x16x32_bf16 v[86:89], v[146:149], v[214:217], v[86:89]
	v_mfma_f32_16x16x32_bf16 v[78:81], v[154:157], v[214:217], v[78:81]
	v_mfma_f32_16x16x32_bf16 v[114:117], v[170:173], v[186:189], v[114:117]
	v_mfma_f32_16x16x32_bf16 v[106:109], v[178:181], v[186:189], v[106:109]
	v_mfma_f32_16x16x32_bf16 v[98:101], v[170:173], v[194:197], v[98:101]
	v_mfma_f32_16x16x32_bf16 v[90:93], v[178:181], v[194:197], v[90:93]
	v_mfma_f32_16x16x32_bf16 v[82:85], v[170:173], v[202:205], v[82:85]
	v_mfma_f32_16x16x32_bf16 v[74:77], v[178:181], v[202:205], v[74:77]
	v_mfma_f32_16x16x32_bf16 v[70:73], v[170:173], v[210:213], v[70:73]
	v_mfma_f32_16x16x32_bf16 v[66:69], v[178:181], v[210:213], v[66:69]
	v_mfma_f32_16x16x32_bf16 v[114:117], v[174:177], v[190:193], v[114:117]
	v_mfma_f32_16x16x32_bf16 v[106:109], v[182:185], v[190:193], v[106:109]
	v_mfma_f32_16x16x32_bf16 v[98:101], v[174:177], v[198:201], v[98:101]
	v_mfma_f32_16x16x32_bf16 v[90:93], v[182:185], v[198:201], v[90:93]
	v_mfma_f32_16x16x32_bf16 v[82:85], v[174:177], v[206:209], v[82:85]
	v_mfma_f32_16x16x32_bf16 v[74:77], v[182:185], v[206:209], v[74:77]
	v_mfma_f32_16x16x32_bf16 v[70:73], v[174:177], v[214:217], v[70:73]
	v_mfma_f32_16x16x32_bf16 v[66:69], v[182:185], v[214:217], v[66:69]
	s_setprio 0
	s_barrier
	s_add_i32 s46, s62, s54
	v_lshl_add_u64 v[218:219], v[218:219], 0, s[22:23]
	s_mov_b32 m0, s46
	ds_read_b128 v[186:189], v167 offset:49152
	ds_read_b128 v[190:193], v167 offset:50176
	ds_read_b128 v[194:197], v167 offset:51200
	ds_read_b128 v[198:201], v167 offset:52224
	ds_read_b128 v[202:205], v167 offset:53248
	ds_read_b128 v[206:209], v167 offset:54272
	ds_read_b128 v[210:213], v167 offset:55296
	ds_read_b128 v[214:217], v167 offset:56320
	global_load_lds_dwordx4 v[218:219], off
	s_add_i32 m0, s46, 0x2000
	s_add_u32 s44, s44, 0x20080
	v_lshl_add_u64 v[218:219], v[220:221], 0, s[22:23]
	s_addc_u32 s45, s45, 0
	s_add_i32 s46, s63, s54
	global_load_lds_dwordx4 v[218:219], off
	v_lshl_add_u64 v[218:219], s[44:45], 0, v[132:133]
	s_mov_b32 m0, s46
	s_nop 0
	global_load_lds_dwordx4 v[218:219], off
	v_lshl_add_u64 v[218:219], s[44:45], 0, v[136:137]
	s_add_i32 m0, s46, 0x2000
	s_nop 0
	global_load_lds_dwordx4 v[218:219], off
	v_lshl_add_u64 v[218:219], v[222:223], 0, s[22:23]
	s_mov_b32 m0, s14
	s_nop 0
	global_load_lds_dwordx4 v[218:219], off
	v_lshl_add_u64 v[218:219], v[224:225], 0, s[22:23]
	s_mov_b32 m0, s15
	s_nop 0
	global_load_lds_dwordx4 v[218:219], off
	s_waitcnt vmcnt(8)
	s_waitcnt lgkmcnt(0)
	s_waitcnt lgkmcnt(0)
	v_mfma_f32_16x16x32_bf16 v[62:65], v[142:145], v[186:189], v[62:65]
	v_mfma_f32_16x16x32_bf16 v[58:61], v[150:153], v[186:189], v[58:61]
	v_mfma_f32_16x16x32_bf16 v[54:57], v[142:145], v[194:197], v[54:57]
	v_mfma_f32_16x16x32_bf16 v[46:49], v[150:153], v[194:197], v[46:49]
	s_barrier
	s_setprio 1
	v_mfma_f32_16x16x32_bf16 v[38:41], v[142:145], v[202:205], v[38:41]
	v_mfma_f32_16x16x32_bf16 v[30:33], v[150:153], v[202:205], v[30:33]
	v_mfma_f32_16x16x32_bf16 v[22:25], v[142:145], v[210:213], v[22:25]
	v_mfma_f32_16x16x32_bf16 v[14:17], v[150:153], v[210:213], v[14:17]
	v_mfma_f32_16x16x32_bf16 v[62:65], v[146:149], v[190:193], v[62:65]
	v_mfma_f32_16x16x32_bf16 v[58:61], v[154:157], v[190:193], v[58:61]
	v_mfma_f32_16x16x32_bf16 v[54:57], v[146:149], v[198:201], v[54:57]
	v_mfma_f32_16x16x32_bf16 v[46:49], v[154:157], v[198:201], v[46:49]
	v_mfma_f32_16x16x32_bf16 v[38:41], v[146:149], v[206:209], v[38:41]
	v_mfma_f32_16x16x32_bf16 v[30:33], v[154:157], v[206:209], v[30:33]
	v_mfma_f32_16x16x32_bf16 v[22:25], v[146:149], v[214:217], v[22:25]
	v_mfma_f32_16x16x32_bf16 v[14:17], v[154:157], v[214:217], v[14:17]
	v_mfma_f32_16x16x32_bf16 v[50:53], v[170:173], v[186:189], v[50:53]
	v_mfma_f32_16x16x32_bf16 v[42:45], v[178:181], v[186:189], v[42:45]
	v_mfma_f32_16x16x32_bf16 v[34:37], v[170:173], v[194:197], v[34:37]
	v_mfma_f32_16x16x32_bf16 v[26:29], v[178:181], v[194:197], v[26:29]
	v_mfma_f32_16x16x32_bf16 v[18:21], v[170:173], v[202:205], v[18:21]
	v_mfma_f32_16x16x32_bf16 v[10:13], v[178:181], v[202:205], v[10:13]
	v_mfma_f32_16x16x32_bf16 v[6:9], v[170:173], v[210:213], v[6:9]
	v_mfma_f32_16x16x32_bf16 v[2:5], v[178:181], v[210:213], v[2:5]
	v_mfma_f32_16x16x32_bf16 v[50:53], v[174:177], v[190:193], v[50:53]
	v_mfma_f32_16x16x32_bf16 v[42:45], v[182:185], v[190:193], v[42:45]
	v_mfma_f32_16x16x32_bf16 v[34:37], v[174:177], v[198:201], v[34:37]
	v_mfma_f32_16x16x32_bf16 v[26:29], v[182:185], v[198:201], v[26:29]
	v_mfma_f32_16x16x32_bf16 v[18:21], v[174:177], v[206:209], v[18:21]
	v_mfma_f32_16x16x32_bf16 v[10:13], v[182:185], v[206:209], v[10:13]
	v_mfma_f32_16x16x32_bf16 v[6:9], v[174:177], v[214:217], v[6:9]
	v_mfma_f32_16x16x32_bf16 v[2:5], v[182:185], v[214:217], v[2:5]
	s_setprio 0
	s_barrier
	s_add_i32 s29, s29, 2
	s_add_u32 s42, s42, 0x100
	s_addc_u32 s43, s43, 0
	s_add_u32 s19, s19, 0x100
	s_addc_u32 s27, s27, 0
	s_cmp_gt_u32 s29, 5
	s_cbranch_scc0 .LBB0_1264
	s_and_b64 vcc, exec, s[24:25]
	s_cbranch_vccz .LBB0_1267
	s_barrier

.LBB0_1336:
	ds_read_b128 v[154:157], v175
	ds_read_b128 v[158:161], v175 offset:1024
	ds_read_b128 v[164:167], v175 offset:2048
	ds_read_b128 v[168:171], v175 offset:3072
	ds_read_b128 v[180:183], v176
	ds_read_b128 v[184:187], v176 offset:1024
	ds_read_b128 v[188:191], v176 offset:2048
	ds_read_b128 v[192:195], v176 offset:3072
	s_add_u32 s20, s36, 0xfffe0080
	s_addc_u32 s21, s37, -1
	s_cmp_eq_u32 s19, 4
	s_cselect_b32 s41, s3, s21
	s_cselect_b32 s40, s14, s20
	s_cselect_b32 s39, s15, s18
	s_cselect_b32 s38, s16, s17
	v_lshl_add_u64 v[228:229], s[36:37], 0, v[144:145]
	s_add_i32 m0, s49, 0xc000
	ds_read_b128 v[196:199], v177
	ds_read_b128 v[200:203], v177 offset:1024
	ds_read_b128 v[204:207], v177 offset:2048
	ds_read_b128 v[208:211], v177 offset:3072
	ds_read_b128 v[212:215], v177 offset:4096
	ds_read_b128 v[216:219], v177 offset:5120
	ds_read_b128 v[220:223], v177 offset:6144
	ds_read_b128 v[224:227], v177 offset:7168
	global_load_lds_dwordx4 v[228:229], off
	v_lshl_add_u64 v[228:229], s[36:37], 0, v[146:147]
	s_add_i32 m0, s49, 0xe000
	s_nop 0
	global_load_lds_dwordx4 v[228:229], off
	s_waitcnt vmcnt(8)
	s_waitcnt lgkmcnt(0)
	s_waitcnt lgkmcnt(0)
	v_mfma_f32_16x16x32_bf16 v[126:129], v[154:157], v[196:199], v[126:129]
	v_mfma_f32_16x16x32_bf16 v[122:125], v[164:167], v[196:199], v[122:125]
	v_mfma_f32_16x16x32_bf16 v[118:121], v[154:157], v[204:207], v[118:121]
	v_mfma_f32_16x16x32_bf16 v[110:113], v[164:167], v[204:207], v[110:113]
	s_barrier
	s_setprio 1
	v_mfma_f32_16x16x32_bf16 v[102:105], v[154:157], v[212:215], v[102:105]
	v_mfma_f32_16x16x32_bf16 v[94:97], v[164:167], v[212:215], v[94:97]
	v_mfma_f32_16x16x32_bf16 v[86:89], v[154:157], v[220:223], v[86:89]
	v_mfma_f32_16x16x32_bf16 v[78:81], v[164:167], v[220:223], v[78:81]
	v_mfma_f32_16x16x32_bf16 v[126:129], v[158:161], v[200:203], v[126:129]
	v_mfma_f32_16x16x32_bf16 v[122:125], v[168:171], v[200:203], v[122:125]
	v_mfma_f32_16x16x32_bf16 v[118:121], v[158:161], v[208:211], v[118:121]
	v_mfma_f32_16x16x32_bf16 v[110:113], v[168:171], v[208:211], v[110:113]
	v_mfma_f32_16x16x32_bf16 v[102:105], v[158:161], v[216:219], v[102:105]
	v_mfma_f32_16x16x32_bf16 v[94:97], v[168:171], v[216:219], v[94:97]
	v_mfma_f32_16x16x32_bf16 v[86:89], v[158:161], v[224:227], v[86:89]
	v_mfma_f32_16x16x32_bf16 v[78:81], v[168:171], v[224:227], v[78:81]
	v_mfma_f32_16x16x32_bf16 v[114:117], v[180:183], v[196:199], v[114:117]
	v_mfma_f32_16x16x32_bf16 v[106:109], v[188:191], v[196:199], v[106:109]
	v_mfma_f32_16x16x32_bf16 v[98:101], v[180:183], v[204:207], v[98:101]
	v_mfma_f32_16x16x32_bf16 v[90:93], v[188:191], v[204:207], v[90:93]
	v_mfma_f32_16x16x32_bf16 v[82:85], v[180:183], v[212:215], v[82:85]
	v_mfma_f32_16x16x32_bf16 v[74:77], v[188:191], v[212:215], v[74:77]
	v_mfma_f32_16x16x32_bf16 v[70:73], v[180:183], v[220:223], v[70:73]
	v_mfma_f32_16x16x32_bf16 v[66:69], v[188:191], v[220:223], v[66:69]
	v_mfma_f32_16x16x32_bf16 v[114:117], v[184:187], v[200:203], v[114:117]
	v_mfma_f32_16x16x32_bf16 v[106:109], v[192:195], v[200:203], v[106:109]
	v_mfma_f32_16x16x32_bf16 v[98:101], v[184:187], v[208:211], v[98:101]
	v_mfma_f32_16x16x32_bf16 v[90:93], v[192:195], v[208:211], v[90:93]
	v_mfma_f32_16x16x32_bf16 v[82:85], v[184:187], v[216:219], v[82:85]
	v_mfma_f32_16x16x32_bf16 v[74:77], v[192:195], v[216:219], v[74:77]
	v_mfma_f32_16x16x32_bf16 v[70:73], v[184:187], v[224:227], v[70:73]
	v_mfma_f32_16x16x32_bf16 v[66:69], v[192:195], v[224:227], v[66:69]
	s_setprio 0
	s_barrier
	s_add_i32 s20, s57, s46
	v_lshl_add_u64 v[228:229], s[38:39], 0, v[134:135]
	s_mov_b32 m0, s20
	ds_read_b128 v[196:199], v177 offset:16384
	ds_read_b128 v[200:203], v177 offset:17408
	ds_read_b128 v[204:207], v177 offset:18432
	ds_read_b128 v[208:211], v177 offset:19456
	ds_read_b128 v[212:215], v177 offset:20480
	ds_read_b128 v[216:219], v177 offset:21504
	ds_read_b128 v[220:223], v177 offset:22528
	ds_read_b128 v[224:227], v177 offset:23552
	global_load_lds_dwordx4 v[228:229], off
	s_add_i32 m0, s20, 0x2000
	s_add_u32 s20, s38, 0x20000
	v_lshl_add_u64 v[230:231], s[38:39], 0, v[130:131]
	s_addc_u32 s21, s39, 0
	s_add_i32 s27, s60, s46
	global_load_lds_dwordx4 v[230:231], off
	v_lshl_add_u64 v[232:233], s[20:21], 0, v[134:135]
	s_mov_b32 m0, s27
	v_lshl_add_u64 v[234:235], s[40:41], 0, v[132:133]
	global_load_lds_dwordx4 v[232:233], off
	v_lshl_add_u64 v[232:233], s[20:21], 0, v[130:131]
	s_add_i32 m0, s27, 0x2000
	s_nop 0
	global_load_lds_dwordx4 v[232:233], off
	v_lshl_add_u64 v[232:233], s[40:41], 0, v[136:137]
	s_mov_b32 m0, s49
	s_nop 0
	global_load_lds_dwordx4 v[232:233], off
	s_mov_b32 m0, s50
	s_nop 0
	global_load_lds_dwordx4 v[234:235], off
	s_waitcnt vmcnt(8)
	s_waitcnt lgkmcnt(0)
	s_waitcnt lgkmcnt(0)
	v_mfma_f32_16x16x32_bf16 v[62:65], v[154:157], v[196:199], v[62:65]
	v_mfma_f32_16x16x32_bf16 v[58:61], v[164:167], v[196:199], v[58:61]
	v_mfma_f32_16x16x32_bf16 v[54:57], v[154:157], v[204:207], v[54:57]
	v_mfma_f32_16x16x32_bf16 v[46:49], v[164:167], v[204:207], v[46:49]
	s_barrier
	s_setprio 1
	v_mfma_f32_16x16x32_bf16 v[38:41], v[154:157], v[212:215], v[38:41]
	v_mfma_f32_16x16x32_bf16 v[30:33], v[164:167], v[212:215], v[30:33]
	v_mfma_f32_16x16x32_bf16 v[22:25], v[154:157], v[220:223], v[22:25]
	v_mfma_f32_16x16x32_bf16 v[14:17], v[164:167], v[220:223], v[14:17]
	v_mfma_f32_16x16x32_bf16 v[62:65], v[158:161], v[200:203], v[62:65]
	v_mfma_f32_16x16x32_bf16 v[58:61], v[168:171], v[200:203], v[58:61]
	v_mfma_f32_16x16x32_bf16 v[54:57], v[158:161], v[208:211], v[54:57]
	v_mfma_f32_16x16x32_bf16 v[46:49], v[168:171], v[208:211], v[46:49]
	v_mfma_f32_16x16x32_bf16 v[38:41], v[158:161], v[216:219], v[38:41]
	v_mfma_f32_16x16x32_bf16 v[30:33], v[168:171], v[216:219], v[30:33]
	v_mfma_f32_16x16x32_bf16 v[22:25], v[158:161], v[224:227], v[22:25]
	v_mfma_f32_16x16x32_bf16 v[14:17], v[168:171], v[224:227], v[14:17]
	v_mfma_f32_16x16x32_bf16 v[50:53], v[180:183], v[196:199], v[50:53]
	v_mfma_f32_16x16x32_bf16 v[42:45], v[188:191], v[196:199], v[42:45]
	v_mfma_f32_16x16x32_bf16 v[34:37], v[180:183], v[204:207], v[34:37]
	v_mfma_f32_16x16x32_bf16 v[26:29], v[188:191], v[204:207], v[26:29]
	v_mfma_f32_16x16x32_bf16 v[18:21], v[180:183], v[212:215], v[18:21]
	v_mfma_f32_16x16x32_bf16 v[10:13], v[188:191], v[212:215], v[10:13]
	v_mfma_f32_16x16x32_bf16 v[6:9], v[180:183], v[220:223], v[6:9]
	v_mfma_f32_16x16x32_bf16 v[2:5], v[188:191], v[220:223], v[2:5]
	v_mfma_f32_16x16x32_bf16 v[50:53], v[184:187], v[200:203], v[50:53]
	v_mfma_f32_16x16x32_bf16 v[42:45], v[192:195], v[200:203], v[42:45]
	v_mfma_f32_16x16x32_bf16 v[34:37], v[184:187], v[208:211], v[34:37]
	v_mfma_f32_16x16x32_bf16 v[26:29], v[192:195], v[208:211], v[26:29]
	v_mfma_f32_16x16x32_bf16 v[18:21], v[184:187], v[216:219], v[18:21]
	v_mfma_f32_16x16x32_bf16 v[10:13], v[192:195], v[216:219], v[10:13]
	v_mfma_f32_16x16x32_bf16 v[6:9], v[184:187], v[224:227], v[6:9]
	v_mfma_f32_16x16x32_bf16 v[2:5], v[192:195], v[224:227], v[2:5]
	s_setprio 0
	s_barrier
	s_add_i32 s27, 0, 0x18000
	v_add_u32_e32 v153, s27, v173
	s_add_i32 s29, 0, 0x1c000
	ds_read_b128 v[154:157], v153
	ds_read_b128 v[158:161], v153 offset:1024
	ds_read_b128 v[164:167], v153 offset:2048
	ds_read_b128 v[168:171], v153 offset:3072
	v_add_u32_e32 v153, s29, v173
	ds_read_b128 v[180:183], v153
	ds_read_b128 v[184:187], v153 offset:1024
	ds_read_b128 v[188:191], v153 offset:2048
	ds_read_b128 v[192:195], v153 offset:3072
	s_add_u32 s20, s40, 0x20000
	s_addc_u32 s21, s41, 0
	s_mov_b32 m0, s51
	v_lshl_add_u64 v[236:237], s[20:21], 0, v[136:137]
	ds_read_b128 v[196:199], v177 offset:32768
	ds_read_b128 v[200:203], v177 offset:33792
	ds_read_b128 v[204:207], v177 offset:34816
	ds_read_b128 v[208:211], v177 offset:35840
	ds_read_b128 v[212:215], v177 offset:36864
	ds_read_b128 v[216:219], v177 offset:37888
	ds_read_b128 v[220:223], v177 offset:38912
	ds_read_b128 v[224:227], v177 offset:39936
	global_load_lds_dwordx4 v[236:237], off
	v_lshl_add_u64 v[236:237], s[20:21], 0, v[132:133]
	s_mov_b32 m0, s52
	s_nop 0
	global_load_lds_dwordx4 v[236:237], off
	s_waitcnt vmcnt(8)
	s_waitcnt lgkmcnt(0)
	s_waitcnt lgkmcnt(0)
	v_mfma_f32_16x16x32_bf16 v[126:129], v[154:157], v[196:199], v[126:129]
	v_mfma_f32_16x16x32_bf16 v[122:125], v[164:167], v[196:199], v[122:125]
	v_mfma_f32_16x16x32_bf16 v[118:121], v[154:157], v[204:207], v[118:121]
	v_mfma_f32_16x16x32_bf16 v[110:113], v[164:167], v[204:207], v[110:113]
	s_barrier
	s_setprio 1
	v_mfma_f32_16x16x32_bf16 v[102:105], v[154:157], v[212:215], v[102:105]
	v_mfma_f32_16x16x32_bf16 v[94:97], v[164:167], v[212:215], v[94:97]
	v_mfma_f32_16x16x32_bf16 v[86:89], v[154:157], v[220:223], v[86:89]
	v_mfma_f32_16x16x32_bf16 v[78:81], v[164:167], v[220:223], v[78:81]
	v_mfma_f32_16x16x32_bf16 v[126:129], v[158:161], v[200:203], v[126:129]
	v_mfma_f32_16x16x32_bf16 v[122:125], v[168:171], v[200:203], v[122:125]
	v_mfma_f32_16x16x32_bf16 v[118:121], v[158:161], v[208:211], v[118:121]
	v_mfma_f32_16x16x32_bf16 v[110:113], v[168:171], v[208:211], v[110:113]
	v_mfma_f32_16x16x32_bf16 v[102:105], v[158:161], v[216:219], v[102:105]
	v_mfma_f32_16x16x32_bf16 v[94:97], v[168:171], v[216:219], v[94:97]
	v_mfma_f32_16x16x32_bf16 v[86:89], v[158:161], v[224:227], v[86:89]
	v_mfma_f32_16x16x32_bf16 v[78:81], v[168:171], v[224:227], v[78:81]
	v_mfma_f32_16x16x32_bf16 v[114:117], v[180:183], v[196:199], v[114:117]
	v_mfma_f32_16x16x32_bf16 v[106:109], v[188:191], v[196:199], v[106:109]
	v_mfma_f32_16x16x32_bf16 v[98:101], v[180:183], v[204:207], v[98:101]
	v_mfma_f32_16x16x32_bf16 v[90:93], v[188:191], v[204:207], v[90:93]
	v_mfma_f32_16x16x32_bf16 v[82:85], v[180:183], v[212:215], v[82:85]
	v_mfma_f32_16x16x32_bf16 v[74:77], v[188:191], v[212:215], v[74:77]
	v_mfma_f32_16x16x32_bf16 v[70:73], v[180:183], v[220:223], v[70:73]
	v_mfma_f32_16x16x32_bf16 v[66:69], v[188:191], v[220:223], v[66:69]
	v_mfma_f32_16x16x32_bf16 v[114:117], v[184:187], v[200:203], v[114:117]
	v_mfma_f32_16x16x32_bf16 v[106:109], v[192:195], v[200:203], v[106:109]
	v_mfma_f32_16x16x32_bf16 v[98:101], v[184:187], v[208:211], v[98:101]
	v_mfma_f32_16x16x32_bf16 v[90:93], v[192:195], v[208:211], v[90:93]
	v_mfma_f32_16x16x32_bf16 v[82:85], v[184:187], v[216:219], v[82:85]
	v_mfma_f32_16x16x32_bf16 v[74:77], v[192:195], v[216:219], v[74:77]
	v_mfma_f32_16x16x32_bf16 v[70:73], v[184:187], v[224:227], v[70:73]
	v_mfma_f32_16x16x32_bf16 v[66:69], v[192:195], v[224:227], v[66:69]
	s_setprio 0
	s_barrier
	s_add_i32 s20, s27, s46
	v_lshl_add_u64 v[228:229], v[228:229], 0, s[22:23]
	s_mov_b32 m0, s20
	ds_read_b128 v[196:199], v177 offset:49152
	ds_read_b128 v[200:203], v177 offset:50176
	ds_read_b128 v[204:207], v177 offset:51200
	ds_read_b128 v[208:211], v177 offset:52224
	ds_read_b128 v[212:215], v177 offset:53248
	ds_read_b128 v[216:219], v177 offset:54272
	ds_read_b128 v[220:223], v177 offset:55296
	ds_read_b128 v[224:227], v177 offset:56320
	global_load_lds_dwordx4 v[228:229], off
	s_add_i32 m0, s20, 0x2000
	s_add_u32 s20, s38, 0x20080
	v_lshl_add_u64 v[228:229], v[230:231], 0, s[22:23]
	s_addc_u32 s21, s39, 0
	s_add_i32 s27, s29, s46
	global_load_lds_dwordx4 v[228:229], off
	v_lshl_add_u64 v[228:229], s[20:21], 0, v[134:135]
	s_mov_b32 m0, s27
	s_nop 0
	global_load_lds_dwordx4 v[228:229], off
	v_lshl_add_u64 v[228:229], s[20:21], 0, v[130:131]
	s_add_i32 m0, s27, 0x2000
	s_nop 0
	global_load_lds_dwordx4 v[228:229], off
	v_lshl_add_u64 v[228:229], v[232:233], 0, s[22:23]
	s_mov_b32 m0, s53
	s_nop 0
	global_load_lds_dwordx4 v[228:229], off
	v_lshl_add_u64 v[228:229], v[234:235], 0, s[22:23]
	s_mov_b32 m0, s54
	s_nop 0
	global_load_lds_dwordx4 v[228:229], off
	s_waitcnt vmcnt(8)
	s_waitcnt lgkmcnt(0)
	s_waitcnt lgkmcnt(0)
	v_mfma_f32_16x16x32_bf16 v[62:65], v[154:157], v[196:199], v[62:65]
	v_mfma_f32_16x16x32_bf16 v[58:61], v[164:167], v[196:199], v[58:61]
	v_mfma_f32_16x16x32_bf16 v[54:57], v[154:157], v[204:207], v[54:57]
	v_mfma_f32_16x16x32_bf16 v[46:49], v[164:167], v[204:207], v[46:49]
	s_barrier
	s_setprio 1
	v_mfma_f32_16x16x32_bf16 v[38:41], v[154:157], v[212:215], v[38:41]
	v_mfma_f32_16x16x32_bf16 v[30:33], v[164:167], v[212:215], v[30:33]
	v_mfma_f32_16x16x32_bf16 v[22:25], v[154:157], v[220:223], v[22:25]
	v_mfma_f32_16x16x32_bf16 v[14:17], v[164:167], v[220:223], v[14:17]
	v_mfma_f32_16x16x32_bf16 v[62:65], v[158:161], v[200:203], v[62:65]
	v_mfma_f32_16x16x32_bf16 v[58:61], v[168:171], v[200:203], v[58:61]
	v_mfma_f32_16x16x32_bf16 v[54:57], v[158:161], v[208:211], v[54:57]
	v_mfma_f32_16x16x32_bf16 v[46:49], v[168:171], v[208:211], v[46:49]
	v_mfma_f32_16x16x32_bf16 v[38:41], v[158:161], v[216:219], v[38:41]
	v_mfma_f32_16x16x32_bf16 v[30:33], v[168:171], v[216:219], v[30:33]
	v_mfma_f32_16x16x32_bf16 v[22:25], v[158:161], v[224:227], v[22:25]
	v_mfma_f32_16x16x32_bf16 v[14:17], v[168:171], v[224:227], v[14:17]
	v_mfma_f32_16x16x32_bf16 v[50:53], v[180:183], v[196:199], v[50:53]
	v_mfma_f32_16x16x32_bf16 v[42:45], v[188:191], v[196:199], v[42:45]
	v_mfma_f32_16x16x32_bf16 v[34:37], v[180:183], v[204:207], v[34:37]
	v_mfma_f32_16x16x32_bf16 v[26:29], v[188:191], v[204:207], v[26:29]
	v_mfma_f32_16x16x32_bf16 v[18:21], v[180:183], v[212:215], v[18:21]
	v_mfma_f32_16x16x32_bf16 v[10:13], v[188:191], v[212:215], v[10:13]
	v_mfma_f32_16x16x32_bf16 v[6:9], v[180:183], v[220:223], v[6:9]
	v_mfma_f32_16x16x32_bf16 v[2:5], v[188:191], v[220:223], v[2:5]
	v_mfma_f32_16x16x32_bf16 v[50:53], v[184:187], v[200:203], v[50:53]
	v_mfma_f32_16x16x32_bf16 v[42:45], v[192:195], v[200:203], v[42:45]
	v_mfma_f32_16x16x32_bf16 v[34:37], v[184:187], v[208:211], v[34:37]
	v_mfma_f32_16x16x32_bf16 v[26:29], v[192:195], v[208:211], v[26:29]
	v_mfma_f32_16x16x32_bf16 v[18:21], v[184:187], v[216:219], v[18:21]
	v_mfma_f32_16x16x32_bf16 v[10:13], v[192:195], v[216:219], v[10:13]
	v_mfma_f32_16x16x32_bf16 v[6:9], v[184:187], v[224:227], v[6:9]
	v_mfma_f32_16x16x32_bf16 v[2:5], v[192:195], v[224:227], v[2:5]
	s_setprio 0
	s_barrier
	s_add_i32 s19, s19, 2
	s_add_u32 s36, s36, 0x100
	s_addc_u32 s37, s37, 0
	s_add_u32 s17, s17, 0x100
	s_addc_u32 s18, s18, 0
	s_cmp_gt_u32 s19, 5
	s_cbranch_scc0 .LBB0_1336
	s_and_b64 vcc, exec, s[24:25]
	s_cbranch_vccz .LBB0_1339
	s_barrier

.LBB0_1497:
	ds_read_b128 v[134:137], v214
	ds_read_b128 v[138:141], v214 offset:1024
	ds_read_b128 v[142:145], v214 offset:2048
	ds_read_b128 v[178:181], v214 offset:3072
	ds_read_b128 v[182:185], v215
	ds_read_b128 v[186:189], v215 offset:1024
	ds_read_b128 v[190:193], v215 offset:2048
	ds_read_b128 v[194:197], v215 offset:3072
	s_add_u32 s40, s38, 0x100
	s_addc_u32 s41, s39, 0
	s_add_u32 s0, s15, s38
	s_addc_u32 s1, s16, s39
	s_cmp_eq_u32 s17, 28
	s_cselect_b32 s45, s3, s1
	s_cselect_b32 s1, 0, s40
	s_cselect_b32 s44, s14, s0
	s_cselect_b32 s0, 0, s41
	s_add_u32 s42, s10, s1
	s_addc_u32 s43, s11, s0
	s_mov_b32 m0, s64
	v_lshl_add_u64 v[244:245], v[130:131], 0, s[38:39]
	ds_read_b128 v[198:201], v216
	ds_read_b128 v[202:205], v216 offset:1024
	ds_read_b128 v[206:209], v216 offset:2048
	ds_read_b128 v[224:227], v216 offset:3072
	ds_read_b128 v[228:231], v216 offset:4096
	ds_read_b128 v[232:235], v216 offset:5120
	ds_read_b128 v[236:239], v216 offset:6144
	ds_read_b128 v[240:243], v216 offset:7168
	global_load_lds_dwordx4 v[244:245], off
	v_lshl_add_u64 v[244:245], v[132:133], 0, s[38:39]
	s_mov_b32 m0, s65
	s_nop 0
	global_load_lds_dwordx4 v[244:245], off
	s_waitcnt vmcnt(8)
	s_waitcnt lgkmcnt(0)
	s_waitcnt lgkmcnt(0)
	v_mfma_f32_16x16x32_bf16 v[82:85], v[134:137], v[198:201], v[82:85]
	v_mfma_f32_16x16x32_bf16 v[78:81], v[142:145], v[198:201], v[78:81]
	v_mfma_f32_16x16x32_bf16 v[110:113], v[134:137], v[206:209], v[110:113]
	v_mfma_f32_16x16x32_bf16 v[106:109], v[142:145], v[206:209], v[106:109]
	s_barrier
	s_setprio 1
	v_mfma_f32_16x16x32_bf16 v[118:121], v[134:137], v[228:231], v[118:121]
	v_mfma_f32_16x16x32_bf16 v[114:117], v[142:145], v[228:231], v[114:117]
	v_mfma_f32_16x16x32_bf16 v[126:129], v[134:137], v[236:239], v[126:129]
	v_mfma_f32_16x16x32_bf16 v[122:125], v[142:145], v[236:239], v[122:125]
	v_mfma_f32_16x16x32_bf16 v[82:85], v[138:141], v[202:205], v[82:85]
	v_mfma_f32_16x16x32_bf16 v[78:81], v[178:181], v[202:205], v[78:81]
	v_mfma_f32_16x16x32_bf16 v[110:113], v[138:141], v[224:227], v[110:113]
	v_mfma_f32_16x16x32_bf16 v[106:109], v[178:181], v[224:227], v[106:109]
	v_mfma_f32_16x16x32_bf16 v[118:121], v[138:141], v[232:235], v[118:121]
	v_mfma_f32_16x16x32_bf16 v[114:117], v[178:181], v[232:235], v[114:117]
	v_mfma_f32_16x16x32_bf16 v[126:129], v[138:141], v[240:243], v[126:129]
	v_mfma_f32_16x16x32_bf16 v[122:125], v[178:181], v[240:243], v[122:125]
	v_mfma_f32_16x16x32_bf16 v[22:25], v[182:185], v[198:201], v[22:25]
	v_mfma_f32_16x16x32_bf16 v[26:29], v[190:193], v[198:201], v[26:29]
	v_mfma_f32_16x16x32_bf16 v[42:45], v[182:185], v[206:209], v[42:45]
	v_mfma_f32_16x16x32_bf16 v[46:49], v[190:193], v[206:209], v[46:49]
	v_mfma_f32_16x16x32_bf16 v[62:65], v[182:185], v[228:231], v[62:65]
	v_mfma_f32_16x16x32_bf16 v[70:73], v[190:193], v[228:231], v[70:73]
	v_mfma_f32_16x16x32_bf16 v[90:93], v[182:185], v[236:239], v[90:93]
	v_mfma_f32_16x16x32_bf16 v[94:97], v[190:193], v[236:239], v[94:97]
	v_mfma_f32_16x16x32_bf16 v[22:25], v[186:189], v[202:205], v[22:25]
	v_mfma_f32_16x16x32_bf16 v[26:29], v[194:197], v[202:205], v[26:29]
	v_mfma_f32_16x16x32_bf16 v[42:45], v[186:189], v[224:227], v[42:45]
	v_mfma_f32_16x16x32_bf16 v[46:49], v[194:197], v[224:227], v[46:49]
	v_mfma_f32_16x16x32_bf16 v[62:65], v[186:189], v[232:235], v[62:65]
	v_mfma_f32_16x16x32_bf16 v[70:73], v[194:197], v[232:235], v[70:73]
	v_mfma_f32_16x16x32_bf16 v[90:93], v[186:189], v[240:243], v[90:93]
	v_mfma_f32_16x16x32_bf16 v[94:97], v[194:197], v[240:243], v[94:97]
	s_setprio 0
	s_barrier
	s_mov_b32 m0, s66
	v_lshl_add_u64 v[244:245], s[42:43], 0, v[150:151]
	s_add_u32 s18, s42, 0x80000
	ds_read_b128 v[198:201], v216 offset:16384
	ds_read_b128 v[202:205], v216 offset:17408
	ds_read_b128 v[206:209], v216 offset:18432
	ds_read_b128 v[224:227], v216 offset:19456
	ds_read_b128 v[228:231], v216 offset:20480
	ds_read_b128 v[232:235], v216 offset:21504
	ds_read_b128 v[236:239], v216 offset:22528
	ds_read_b128 v[240:243], v216 offset:23552
	global_load_lds_dwordx4 v[244:245], off
	v_lshl_add_u64 v[246:247], s[42:43], 0, v[146:147]
	s_mov_b32 m0, s67
	s_addc_u32 s19, s43, 0
	global_load_lds_dwordx4 v[246:247], off
	v_lshl_add_u64 v[248:249], s[18:19], 0, v[150:151]
	s_mov_b32 m0, s68
	v_lshl_add_u64 v[250:251], s[44:45], 0, v[148:149]
	global_load_lds_dwordx4 v[248:249], off
	v_lshl_add_u64 v[248:249], s[18:19], 0, v[146:147]
	s_mov_b32 m0, s69
	s_nop 0
	global_load_lds_dwordx4 v[248:249], off
	v_lshl_add_u64 v[248:249], s[44:45], 0, v[152:153]
	s_mov_b32 m0, s9
	s_nop 0
	global_load_lds_dwordx4 v[248:249], off
	s_mov_b32 m0, s55
	s_nop 0
	global_load_lds_dwordx4 v[250:251], off
	s_waitcnt vmcnt(8)
	s_waitcnt lgkmcnt(0)
	s_waitcnt lgkmcnt(0)
	v_mfma_f32_16x16x32_bf16 v[102:105], v[134:137], v[198:201], v[102:105]
	v_mfma_f32_16x16x32_bf16 v[98:101], v[142:145], v[198:201], v[98:101]
	v_mfma_f32_16x16x32_bf16 v[66:69], v[134:137], v[206:209], v[66:69]
	v_mfma_f32_16x16x32_bf16 v[58:61], v[142:145], v[206:209], v[58:61]
	s_barrier
	s_setprio 1
	v_mfma_f32_16x16x32_bf16 v[38:41], v[134:137], v[228:231], v[38:41]
	v_mfma_f32_16x16x32_bf16 v[34:37], v[142:145], v[228:231], v[34:37]
	v_mfma_f32_16x16x32_bf16 v[14:17], v[134:137], v[236:239], v[14:17]
	v_mfma_f32_16x16x32_bf16 v[10:13], v[142:145], v[236:239], v[10:13]
	v_mfma_f32_16x16x32_bf16 v[102:105], v[138:141], v[202:205], v[102:105]
	v_mfma_f32_16x16x32_bf16 v[98:101], v[178:181], v[202:205], v[98:101]
	v_mfma_f32_16x16x32_bf16 v[66:69], v[138:141], v[224:227], v[66:69]
	v_mfma_f32_16x16x32_bf16 v[58:61], v[178:181], v[224:227], v[58:61]
	v_mfma_f32_16x16x32_bf16 v[38:41], v[138:141], v[232:235], v[38:41]
	v_mfma_f32_16x16x32_bf16 v[34:37], v[178:181], v[232:235], v[34:37]
	v_mfma_f32_16x16x32_bf16 v[14:17], v[138:141], v[240:243], v[14:17]
	v_mfma_f32_16x16x32_bf16 v[10:13], v[178:181], v[240:243], v[10:13]
	v_mfma_f32_16x16x32_bf16 v[86:89], v[182:185], v[198:201], v[86:89]
	v_mfma_f32_16x16x32_bf16 v[74:77], v[190:193], v[198:201], v[74:77]
	v_mfma_f32_16x16x32_bf16 v[54:57], v[182:185], v[206:209], v[54:57]
	v_mfma_f32_16x16x32_bf16 v[50:53], v[190:193], v[206:209], v[50:53]
	v_mfma_f32_16x16x32_bf16 v[30:33], v[182:185], v[228:231], v[30:33]
	v_mfma_f32_16x16x32_bf16 v[18:21], v[190:193], v[228:231], v[18:21]
	v_mfma_f32_16x16x32_bf16 v[6:9], v[182:185], v[236:239], v[6:9]
	v_mfma_f32_16x16x32_bf16 v[2:5], v[190:193], v[236:239], v[2:5]
	v_mfma_f32_16x16x32_bf16 v[86:89], v[186:189], v[202:205], v[86:89]
	v_mfma_f32_16x16x32_bf16 v[74:77], v[194:197], v[202:205], v[74:77]
	v_mfma_f32_16x16x32_bf16 v[54:57], v[186:189], v[224:227], v[54:57]
	v_mfma_f32_16x16x32_bf16 v[50:53], v[194:197], v[224:227], v[50:53]
	v_mfma_f32_16x16x32_bf16 v[30:33], v[186:189], v[232:235], v[30:33]
	v_mfma_f32_16x16x32_bf16 v[18:21], v[194:197], v[232:235], v[18:21]
	v_mfma_f32_16x16x32_bf16 v[6:9], v[186:189], v[240:243], v[6:9]
	v_mfma_f32_16x16x32_bf16 v[2:5], v[194:197], v[240:243], v[2:5]
	s_setprio 0
	s_barrier
	s_add_i32 s0, 0, 0x1c000
	v_add_u32_e32 v194, s0, v212
	ds_read_b128 v[134:137], v220
	ds_read_b128 v[138:141], v220 offset:1024
	ds_read_b128 v[142:145], v220 offset:2048
	ds_read_b128 v[178:181], v220 offset:3072
	ds_read_b128 v[182:185], v194
	ds_read_b128 v[186:189], v194 offset:1024
	ds_read_b128 v[190:193], v194 offset:2048
	ds_read_b128 v[194:197], v194 offset:3072
	s_add_u32 s18, s44, 0x80000
	s_addc_u32 s19, s45, 0
	s_mov_b32 m0, s56
	v_lshl_add_u64 v[252:253], s[18:19], 0, v[152:153]
	ds_read_b128 v[198:201], v216 offset:32768
	ds_read_b128 v[202:205], v216 offset:33792
	ds_read_b128 v[206:209], v216 offset:34816
	ds_read_b128 v[224:227], v216 offset:35840
	ds_read_b128 v[228:231], v216 offset:36864
	ds_read_b128 v[232:235], v216 offset:37888
	ds_read_b128 v[236:239], v216 offset:38912
	ds_read_b128 v[240:243], v216 offset:39936
	global_load_lds_dwordx4 v[252:253], off
	v_lshl_add_u64 v[252:253], s[18:19], 0, v[148:149]
	s_mov_b32 m0, s57
	s_nop 0
	global_load_lds_dwordx4 v[252:253], off
	s_waitcnt vmcnt(8)
	s_waitcnt lgkmcnt(0)
	s_waitcnt lgkmcnt(0)
	v_mfma_f32_16x16x32_bf16 v[82:85], v[134:137], v[198:201], v[82:85]
	v_mfma_f32_16x16x32_bf16 v[78:81], v[142:145], v[198:201], v[78:81]
	v_mfma_f32_16x16x32_bf16 v[110:113], v[134:137], v[206:209], v[110:113]
	v_mfma_f32_16x16x32_bf16 v[106:109], v[142:145], v[206:209], v[106:109]
	s_barrier
	s_setprio 1
	v_mfma_f32_16x16x32_bf16 v[118:121], v[134:137], v[228:231], v[118:121]
	v_mfma_f32_16x16x32_bf16 v[114:117], v[142:145], v[228:231], v[114:117]
	v_mfma_f32_16x16x32_bf16 v[126:129], v[134:137], v[236:239], v[126:129]
	v_mfma_f32_16x16x32_bf16 v[122:125], v[142:145], v[236:239], v[122:125]
	v_mfma_f32_16x16x32_bf16 v[82:85], v[138:141], v[202:205], v[82:85]
	v_mfma_f32_16x16x32_bf16 v[78:81], v[178:181], v[202:205], v[78:81]
	v_mfma_f32_16x16x32_bf16 v[110:113], v[138:141], v[224:227], v[110:113]
	v_mfma_f32_16x16x32_bf16 v[106:109], v[178:181], v[224:227], v[106:109]
	v_mfma_f32_16x16x32_bf16 v[118:121], v[138:141], v[232:235], v[118:121]
	v_mfma_f32_16x16x32_bf16 v[114:117], v[178:181], v[232:235], v[114:117]
	v_mfma_f32_16x16x32_bf16 v[126:129], v[138:141], v[240:243], v[126:129]
	v_mfma_f32_16x16x32_bf16 v[122:125], v[178:181], v[240:243], v[122:125]
	v_mfma_f32_16x16x32_bf16 v[22:25], v[182:185], v[198:201], v[22:25]
	v_mfma_f32_16x16x32_bf16 v[26:29], v[190:193], v[198:201], v[26:29]
	v_mfma_f32_16x16x32_bf16 v[42:45], v[182:185], v[206:209], v[42:45]
	v_mfma_f32_16x16x32_bf16 v[46:49], v[190:193], v[206:209], v[46:49]
	v_mfma_f32_16x16x32_bf16 v[62:65], v[182:185], v[228:231], v[62:65]
	v_mfma_f32_16x16x32_bf16 v[70:73], v[190:193], v[228:231], v[70:73]
	v_mfma_f32_16x16x32_bf16 v[90:93], v[182:185], v[236:239], v[90:93]
	v_mfma_f32_16x16x32_bf16 v[94:97], v[190:193], v[236:239], v[94:97]
	v_mfma_f32_16x16x32_bf16 v[22:25], v[186:189], v[202:205], v[22:25]
	v_mfma_f32_16x16x32_bf16 v[26:29], v[194:197], v[202:205], v[26:29]
	v_mfma_f32_16x16x32_bf16 v[42:45], v[186:189], v[224:227], v[42:45]
	v_mfma_f32_16x16x32_bf16 v[46:49], v[194:197], v[224:227], v[46:49]
	v_mfma_f32_16x16x32_bf16 v[62:65], v[186:189], v[232:235], v[62:65]
	v_mfma_f32_16x16x32_bf16 v[70:73], v[194:197], v[232:235], v[70:73]
	v_mfma_f32_16x16x32_bf16 v[90:93], v[186:189], v[240:243], v[90:93]
	v_mfma_f32_16x16x32_bf16 v[94:97], v[194:197], v[240:243], v[94:97]
	s_setprio 0
	s_barrier
	s_add_i32 s1, s72, s54
	v_lshl_add_u64 v[244:245], v[244:245], 0, s[26:27]
	s_mov_b32 m0, s1
	ds_read_b128 v[198:201], v216 offset:49152
	ds_read_b128 v[202:205], v216 offset:50176
	ds_read_b128 v[206:209], v216 offset:51200
	ds_read_b128 v[224:227], v216 offset:52224
	ds_read_b128 v[228:231], v216 offset:53248
	ds_read_b128 v[232:235], v216 offset:54272
	ds_read_b128 v[236:239], v216 offset:55296
	ds_read_b128 v[240:243], v216 offset:56320
	global_load_lds_dwordx4 v[244:245], off
	s_add_i32 m0, s1, 0x2000
	s_add_u32 s18, s42, 0x80080
	v_lshl_add_u64 v[244:245], v[246:247], 0, s[26:27]
	s_addc_u32 s19, s43, 0
	s_add_i32 s0, s0, s54
	global_load_lds_dwordx4 v[244:245], off
	v_lshl_add_u64 v[244:245], s[18:19], 0, v[150:151]
	s_mov_b32 m0, s0
	s_nop 0
	global_load_lds_dwordx4 v[244:245], off
	v_lshl_add_u64 v[244:245], s[18:19], 0, v[146:147]
	s_add_i32 m0, s0, 0x2000
	s_nop 0
	global_load_lds_dwordx4 v[244:245], off
	v_lshl_add_u64 v[244:245], v[248:249], 0, s[26:27]
	s_mov_b32 m0, s61
	s_nop 0
	global_load_lds_dwordx4 v[244:245], off
	v_lshl_add_u64 v[244:245], v[250:251], 0, s[26:27]
	s_mov_b32 m0, s62
	s_nop 0
	global_load_lds_dwordx4 v[244:245], off
	s_waitcnt vmcnt(8)
	s_waitcnt lgkmcnt(0)
	s_waitcnt lgkmcnt(0)
	v_mfma_f32_16x16x32_bf16 v[102:105], v[134:137], v[198:201], v[102:105]
	v_mfma_f32_16x16x32_bf16 v[98:101], v[142:145], v[198:201], v[98:101]
	v_mfma_f32_16x16x32_bf16 v[66:69], v[134:137], v[206:209], v[66:69]
	v_mfma_f32_16x16x32_bf16 v[58:61], v[142:145], v[206:209], v[58:61]
	s_barrier
	s_setprio 1
	v_mfma_f32_16x16x32_bf16 v[38:41], v[134:137], v[228:231], v[38:41]
	v_mfma_f32_16x16x32_bf16 v[34:37], v[142:145], v[228:231], v[34:37]
	v_mfma_f32_16x16x32_bf16 v[14:17], v[134:137], v[236:239], v[14:17]
	v_mfma_f32_16x16x32_bf16 v[10:13], v[142:145], v[236:239], v[10:13]
	v_mfma_f32_16x16x32_bf16 v[102:105], v[138:141], v[202:205], v[102:105]
	v_mfma_f32_16x16x32_bf16 v[98:101], v[178:181], v[202:205], v[98:101]
	v_mfma_f32_16x16x32_bf16 v[66:69], v[138:141], v[224:227], v[66:69]
	v_mfma_f32_16x16x32_bf16 v[58:61], v[178:181], v[224:227], v[58:61]
	v_mfma_f32_16x16x32_bf16 v[38:41], v[138:141], v[232:235], v[38:41]
	v_mfma_f32_16x16x32_bf16 v[34:37], v[178:181], v[232:235], v[34:37]
	v_mfma_f32_16x16x32_bf16 v[14:17], v[138:141], v[240:243], v[14:17]
	v_mfma_f32_16x16x32_bf16 v[10:13], v[178:181], v[240:243], v[10:13]
	v_mfma_f32_16x16x32_bf16 v[86:89], v[182:185], v[198:201], v[86:89]
	v_mfma_f32_16x16x32_bf16 v[74:77], v[190:193], v[198:201], v[74:77]
	v_mfma_f32_16x16x32_bf16 v[54:57], v[182:185], v[206:209], v[54:57]
	v_mfma_f32_16x16x32_bf16 v[50:53], v[190:193], v[206:209], v[50:53]
	v_mfma_f32_16x16x32_bf16 v[30:33], v[182:185], v[228:231], v[30:33]
	v_mfma_f32_16x16x32_bf16 v[18:21], v[190:193], v[228:231], v[18:21]
	v_mfma_f32_16x16x32_bf16 v[6:9], v[182:185], v[236:239], v[6:9]
	v_mfma_f32_16x16x32_bf16 v[2:5], v[190:193], v[236:239], v[2:5]
	v_mfma_f32_16x16x32_bf16 v[86:89], v[186:189], v[202:205], v[86:89]
	v_mfma_f32_16x16x32_bf16 v[74:77], v[194:197], v[202:205], v[74:77]
	v_mfma_f32_16x16x32_bf16 v[54:57], v[186:189], v[224:227], v[54:57]
	v_mfma_f32_16x16x32_bf16 v[50:53], v[194:197], v[224:227], v[50:53]
	v_mfma_f32_16x16x32_bf16 v[30:33], v[186:189], v[232:235], v[30:33]
	v_mfma_f32_16x16x32_bf16 v[18:21], v[194:197], v[232:235], v[18:21]
	v_mfma_f32_16x16x32_bf16 v[6:9], v[186:189], v[240:243], v[6:9]
	v_mfma_f32_16x16x32_bf16 v[2:5], v[194:197], v[240:243], v[2:5]
	s_setprio 0
	s_barrier
	s_add_i32 s17, s17, 2
	s_cmp_gt_u32 s17, 29
	s_mov_b64 s[38:39], s[40:41]
	s_cbranch_scc0 .LBB0_1497
	s_and_b64 vcc, exec, s[28:29]
	s_cbranch_vccz .LBB0_1500
	s_barrier

.LBB0_1604:
	ds_read_b128 v[154:157], v151
	ds_read_b128 v[158:161], v151 offset:1024
	ds_read_b128 v[164:167], v151 offset:2048
	ds_read_b128 v[168:171], v151 offset:3072
	ds_read_b128 v[172:175], v152
	ds_read_b128 v[176:179], v152 offset:1024
	ds_read_b128 v[180:183], v152 offset:2048
	ds_read_b128 v[184:187], v152 offset:3072
	s_add_u32 s0, s34, 0xfff80080
	s_addc_u32 s1, s35, -1
	s_cmp_eq_u32 s53, 28
	s_cselect_b32 s39, s16, s1
	s_cselect_b32 s38, s17, s0
	s_cselect_b32 s37, s18, s25
	s_cselect_b32 s36, s19, s23
	v_lshl_add_u64 v[146:147], s[34:35], 0, v[138:139]
	s_add_i32 m0, s31, 0xc000
	ds_read_b128 v[188:191], v153
	ds_read_b128 v[192:195], v153 offset:1024
	ds_read_b128 v[196:199], v153 offset:2048
	ds_read_b128 v[200:203], v153 offset:3072
	ds_read_b128 v[204:207], v153 offset:4096
	ds_read_b128 v[208:211], v153 offset:5120
	ds_read_b128 v[212:215], v153 offset:6144
	ds_read_b128 v[216:219], v153 offset:7168
	global_load_lds_dwordx4 v[146:147], off
	v_lshl_add_u64 v[146:147], s[34:35], 0, v[140:141]
	s_add_i32 m0, s31, 0xe000
	s_nop 0
	global_load_lds_dwordx4 v[146:147], off
	s_waitcnt vmcnt(8)
	s_waitcnt lgkmcnt(0)
	s_waitcnt lgkmcnt(0)
	v_mfma_f32_16x16x32_bf16 v[126:129], v[154:157], v[188:191], v[126:129]
	v_mfma_f32_16x16x32_bf16 v[122:125], v[164:167], v[188:191], v[122:125]
	v_mfma_f32_16x16x32_bf16 v[110:113], v[154:157], v[196:199], v[110:113]
	v_mfma_f32_16x16x32_bf16 v[106:109], v[164:167], v[196:199], v[106:109]
	s_barrier
	s_setprio 1
	v_mfma_f32_16x16x32_bf16 v[94:97], v[154:157], v[204:207], v[94:97]
	v_mfma_f32_16x16x32_bf16 v[90:93], v[164:167], v[204:207], v[90:93]
	v_mfma_f32_16x16x32_bf16 v[78:81], v[154:157], v[212:215], v[78:81]
	v_mfma_f32_16x16x32_bf16 v[74:77], v[164:167], v[212:215], v[74:77]
	v_mfma_f32_16x16x32_bf16 v[126:129], v[158:161], v[192:195], v[126:129]
	v_mfma_f32_16x16x32_bf16 v[122:125], v[168:171], v[192:195], v[122:125]
	v_mfma_f32_16x16x32_bf16 v[110:113], v[158:161], v[200:203], v[110:113]
	v_mfma_f32_16x16x32_bf16 v[106:109], v[168:171], v[200:203], v[106:109]
	v_mfma_f32_16x16x32_bf16 v[94:97], v[158:161], v[208:211], v[94:97]
	v_mfma_f32_16x16x32_bf16 v[90:93], v[168:171], v[208:211], v[90:93]
	v_mfma_f32_16x16x32_bf16 v[78:81], v[158:161], v[216:219], v[78:81]
	v_mfma_f32_16x16x32_bf16 v[74:77], v[168:171], v[216:219], v[74:77]
	v_mfma_f32_16x16x32_bf16 v[118:121], v[172:175], v[188:191], v[118:121]
	v_mfma_f32_16x16x32_bf16 v[114:117], v[180:183], v[188:191], v[114:117]
	v_mfma_f32_16x16x32_bf16 v[102:105], v[172:175], v[196:199], v[102:105]
	v_mfma_f32_16x16x32_bf16 v[98:101], v[180:183], v[196:199], v[98:101]
	v_mfma_f32_16x16x32_bf16 v[86:89], v[172:175], v[204:207], v[86:89]
	v_mfma_f32_16x16x32_bf16 v[82:85], v[180:183], v[204:207], v[82:85]
	v_mfma_f32_16x16x32_bf16 v[70:73], v[172:175], v[212:215], v[70:73]
	v_mfma_f32_16x16x32_bf16 v[66:69], v[180:183], v[212:215], v[66:69]
	v_mfma_f32_16x16x32_bf16 v[118:121], v[176:179], v[192:195], v[118:121]
	v_mfma_f32_16x16x32_bf16 v[114:117], v[184:187], v[192:195], v[114:117]
	v_mfma_f32_16x16x32_bf16 v[102:105], v[176:179], v[200:203], v[102:105]
	v_mfma_f32_16x16x32_bf16 v[98:101], v[184:187], v[200:203], v[98:101]
	v_mfma_f32_16x16x32_bf16 v[86:89], v[176:179], v[208:211], v[86:89]
	v_mfma_f32_16x16x32_bf16 v[82:85], v[184:187], v[208:211], v[82:85]
	v_mfma_f32_16x16x32_bf16 v[70:73], v[176:179], v[216:219], v[70:73]
	v_mfma_f32_16x16x32_bf16 v[66:69], v[184:187], v[216:219], v[66:69]
	s_setprio 0
	s_barrier
	s_add_i32 s0, s15, s44
	v_lshl_add_u64 v[146:147], s[36:37], 0, v[134:135]
	s_mov_b32 m0, s0
	ds_read_b128 v[188:191], v153 offset:16384
	ds_read_b128 v[192:195], v153 offset:17408
	ds_read_b128 v[196:199], v153 offset:18432
	ds_read_b128 v[200:203], v153 offset:19456
	ds_read_b128 v[204:207], v153 offset:20480
	ds_read_b128 v[208:211], v153 offset:21504
	ds_read_b128 v[212:215], v153 offset:22528
	ds_read_b128 v[216:219], v153 offset:23552
	global_load_lds_dwordx4 v[146:147], off
	s_add_i32 m0, s0, 0x2000
	s_add_u32 s54, s36, 0x80000
	v_lshl_add_u64 v[220:221], s[36:37], 0, v[130:131]
	s_addc_u32 s55, s37, 0
	s_add_i32 s0, s51, s44
	global_load_lds_dwordx4 v[220:221], off
	v_lshl_add_u64 v[222:223], s[54:55], 0, v[134:135]
	s_mov_b32 m0, s0
	v_lshl_add_u64 v[224:225], s[38:39], 0, v[132:133]
	global_load_lds_dwordx4 v[222:223], off
	v_lshl_add_u64 v[222:223], s[54:55], 0, v[130:131]
	s_add_i32 m0, s0, 0x2000
	s_nop 0
	global_load_lds_dwordx4 v[222:223], off
	v_lshl_add_u64 v[222:223], s[38:39], 0, v[136:137]
	s_mov_b32 m0, s31
	s_nop 0
	global_load_lds_dwordx4 v[222:223], off
	s_mov_b32 m0, s47
	s_nop 0
	global_load_lds_dwordx4 v[224:225], off
	s_waitcnt vmcnt(8)
	s_waitcnt lgkmcnt(0)
	s_waitcnt lgkmcnt(0)
	v_mfma_f32_16x16x32_bf16 v[62:65], v[154:157], v[188:191], v[62:65]
	v_mfma_f32_16x16x32_bf16 v[58:61], v[164:167], v[188:191], v[58:61]
	v_mfma_f32_16x16x32_bf16 v[46:49], v[154:157], v[196:199], v[46:49]
	v_mfma_f32_16x16x32_bf16 v[42:45], v[164:167], v[196:199], v[42:45]
	s_barrier
	s_setprio 1
	v_mfma_f32_16x16x32_bf16 v[30:33], v[154:157], v[204:207], v[30:33]
	v_mfma_f32_16x16x32_bf16 v[26:29], v[164:167], v[204:207], v[26:29]
	v_mfma_f32_16x16x32_bf16 v[14:17], v[154:157], v[212:215], v[14:17]
	v_mfma_f32_16x16x32_bf16 v[10:13], v[164:167], v[212:215], v[10:13]
	v_mfma_f32_16x16x32_bf16 v[62:65], v[158:161], v[192:195], v[62:65]
	v_mfma_f32_16x16x32_bf16 v[58:61], v[168:171], v[192:195], v[58:61]
	v_mfma_f32_16x16x32_bf16 v[46:49], v[158:161], v[200:203], v[46:49]
	v_mfma_f32_16x16x32_bf16 v[42:45], v[168:171], v[200:203], v[42:45]
	v_mfma_f32_16x16x32_bf16 v[30:33], v[158:161], v[208:211], v[30:33]
	v_mfma_f32_16x16x32_bf16 v[26:29], v[168:171], v[208:211], v[26:29]
	v_mfma_f32_16x16x32_bf16 v[14:17], v[158:161], v[216:219], v[14:17]
	v_mfma_f32_16x16x32_bf16 v[10:13], v[168:171], v[216:219], v[10:13]
	v_mfma_f32_16x16x32_bf16 v[54:57], v[172:175], v[188:191], v[54:57]
	v_mfma_f32_16x16x32_bf16 v[50:53], v[180:183], v[188:191], v[50:53]
	v_mfma_f32_16x16x32_bf16 v[38:41], v[172:175], v[196:199], v[38:41]
	v_mfma_f32_16x16x32_bf16 v[34:37], v[180:183], v[196:199], v[34:37]
	v_mfma_f32_16x16x32_bf16 v[22:25], v[172:175], v[204:207], v[22:25]
	v_mfma_f32_16x16x32_bf16 v[18:21], v[180:183], v[204:207], v[18:21]
	v_mfma_f32_16x16x32_bf16 v[6:9], v[172:175], v[212:215], v[6:9]
	v_mfma_f32_16x16x32_bf16 v[2:5], v[180:183], v[212:215], v[2:5]
	v_mfma_f32_16x16x32_bf16 v[54:57], v[176:179], v[192:195], v[54:57]
	v_mfma_f32_16x16x32_bf16 v[50:53], v[184:187], v[192:195], v[50:53]
	v_mfma_f32_16x16x32_bf16 v[38:41], v[176:179], v[200:203], v[38:41]
	v_mfma_f32_16x16x32_bf16 v[34:37], v[184:187], v[200:203], v[34:37]
	v_mfma_f32_16x16x32_bf16 v[22:25], v[176:179], v[208:211], v[22:25]
	v_mfma_f32_16x16x32_bf16 v[18:21], v[184:187], v[208:211], v[18:21]
	v_mfma_f32_16x16x32_bf16 v[6:9], v[176:179], v[216:219], v[6:9]
	v_mfma_f32_16x16x32_bf16 v[2:5], v[184:187], v[216:219], v[2:5]
	s_setprio 0
	s_barrier
	s_add_i32 s0, 0, 0x18000
	v_add_u32_e32 v163, s0, v149
	s_add_i32 s1, 0, 0x1c000
	ds_read_b128 v[154:157], v163
	ds_read_b128 v[158:161], v163 offset:1024
	ds_read_b128 v[164:167], v163 offset:2048
	ds_read_b128 v[168:171], v163 offset:3072
	v_add_u32_e32 v163, s1, v149
	ds_read_b128 v[172:175], v163
	ds_read_b128 v[176:179], v163 offset:1024
	ds_read_b128 v[180:183], v163 offset:2048
	ds_read_b128 v[184:187], v163 offset:3072
	s_add_u32 s38, s38, 0x80000
	s_addc_u32 s39, s39, 0
	s_mov_b32 m0, s48
	v_lshl_add_u64 v[226:227], s[38:39], 0, v[136:137]
	ds_read_b128 v[188:191], v153 offset:32768
	ds_read_b128 v[192:195], v153 offset:33792
	ds_read_b128 v[196:199], v153 offset:34816
	ds_read_b128 v[200:203], v153 offset:35840
	ds_read_b128 v[204:207], v153 offset:36864
	ds_read_b128 v[208:211], v153 offset:37888
	ds_read_b128 v[212:215], v153 offset:38912
	ds_read_b128 v[216:219], v153 offset:39936
	global_load_lds_dwordx4 v[226:227], off
	v_lshl_add_u64 v[226:227], s[38:39], 0, v[132:133]
	s_mov_b32 m0, s49
	s_nop 0
	global_load_lds_dwordx4 v[226:227], off
	s_waitcnt vmcnt(8)
	s_waitcnt lgkmcnt(0)
	s_waitcnt lgkmcnt(0)
	v_mfma_f32_16x16x32_bf16 v[126:129], v[154:157], v[188:191], v[126:129]
	v_mfma_f32_16x16x32_bf16 v[122:125], v[164:167], v[188:191], v[122:125]
	v_mfma_f32_16x16x32_bf16 v[110:113], v[154:157], v[196:199], v[110:113]
	v_mfma_f32_16x16x32_bf16 v[106:109], v[164:167], v[196:199], v[106:109]
	s_barrier
	s_setprio 1
	v_mfma_f32_16x16x32_bf16 v[94:97], v[154:157], v[204:207], v[94:97]
	v_mfma_f32_16x16x32_bf16 v[90:93], v[164:167], v[204:207], v[90:93]
	v_mfma_f32_16x16x32_bf16 v[78:81], v[154:157], v[212:215], v[78:81]
	v_mfma_f32_16x16x32_bf16 v[74:77], v[164:167], v[212:215], v[74:77]
	v_mfma_f32_16x16x32_bf16 v[126:129], v[158:161], v[192:195], v[126:129]
	v_mfma_f32_16x16x32_bf16 v[122:125], v[168:171], v[192:195], v[122:125]
	v_mfma_f32_16x16x32_bf16 v[110:113], v[158:161], v[200:203], v[110:113]
	v_mfma_f32_16x16x32_bf16 v[106:109], v[168:171], v[200:203], v[106:109]
	v_mfma_f32_16x16x32_bf16 v[94:97], v[158:161], v[208:211], v[94:97]
	v_mfma_f32_16x16x32_bf16 v[90:93], v[168:171], v[208:211], v[90:93]
	v_mfma_f32_16x16x32_bf16 v[78:81], v[158:161], v[216:219], v[78:81]
	v_mfma_f32_16x16x32_bf16 v[74:77], v[168:171], v[216:219], v[74:77]
	v_mfma_f32_16x16x32_bf16 v[118:121], v[172:175], v[188:191], v[118:121]
	v_mfma_f32_16x16x32_bf16 v[114:117], v[180:183], v[188:191], v[114:117]
	v_mfma_f32_16x16x32_bf16 v[102:105], v[172:175], v[196:199], v[102:105]
	v_mfma_f32_16x16x32_bf16 v[98:101], v[180:183], v[196:199], v[98:101]
	v_mfma_f32_16x16x32_bf16 v[86:89], v[172:175], v[204:207], v[86:89]
	v_mfma_f32_16x16x32_bf16 v[82:85], v[180:183], v[204:207], v[82:85]
	v_mfma_f32_16x16x32_bf16 v[70:73], v[172:175], v[212:215], v[70:73]
	v_mfma_f32_16x16x32_bf16 v[66:69], v[180:183], v[212:215], v[66:69]
	v_mfma_f32_16x16x32_bf16 v[118:121], v[176:179], v[192:195], v[118:121]
	v_mfma_f32_16x16x32_bf16 v[114:117], v[184:187], v[192:195], v[114:117]
	v_mfma_f32_16x16x32_bf16 v[102:105], v[176:179], v[200:203], v[102:105]
	v_mfma_f32_16x16x32_bf16 v[98:101], v[184:187], v[200:203], v[98:101]
	v_mfma_f32_16x16x32_bf16 v[86:89], v[176:179], v[208:211], v[86:89]
	v_mfma_f32_16x16x32_bf16 v[82:85], v[184:187], v[208:211], v[82:85]
	v_mfma_f32_16x16x32_bf16 v[70:73], v[176:179], v[216:219], v[70:73]
	v_mfma_f32_16x16x32_bf16 v[66:69], v[184:187], v[216:219], v[66:69]
	s_setprio 0
	s_barrier
	s_add_i32 s0, s0, s44
	v_lshl_add_u64 v[146:147], v[146:147], 0, s[10:11]
	s_mov_b32 m0, s0
	ds_read_b128 v[188:191], v153 offset:49152
	ds_read_b128 v[192:195], v153 offset:50176
	ds_read_b128 v[196:199], v153 offset:51200
	ds_read_b128 v[200:203], v153 offset:52224
	ds_read_b128 v[204:207], v153 offset:53248
	ds_read_b128 v[208:211], v153 offset:54272
	ds_read_b128 v[212:215], v153 offset:55296
	ds_read_b128 v[216:219], v153 offset:56320
	global_load_lds_dwordx4 v[146:147], off
	s_add_i32 m0, s0, 0x2000
	s_add_u32 s36, s36, 0x80080
	v_lshl_add_u64 v[146:147], v[220:221], 0, s[10:11]
	s_addc_u32 s37, s37, 0
	s_add_i32 s0, s1, s44
	global_load_lds_dwordx4 v[146:147], off
	v_lshl_add_u64 v[146:147], s[36:37], 0, v[134:135]
	s_mov_b32 m0, s0
	s_nop 0
	global_load_lds_dwordx4 v[146:147], off
	v_lshl_add_u64 v[146:147], s[36:37], 0, v[130:131]
	s_add_i32 m0, s0, 0x2000
	s_nop 0
	global_load_lds_dwordx4 v[146:147], off
	v_lshl_add_u64 v[146:147], v[222:223], 0, s[10:11]
	s_mov_b32 m0, s20
	s_nop 0
	global_load_lds_dwordx4 v[146:147], off
	v_lshl_add_u64 v[146:147], v[224:225], 0, s[10:11]
	s_mov_b32 m0, s21
	s_nop 0
	global_load_lds_dwordx4 v[146:147], off
	s_waitcnt vmcnt(8)
	s_waitcnt lgkmcnt(0)
	s_waitcnt lgkmcnt(0)
	v_mfma_f32_16x16x32_bf16 v[62:65], v[154:157], v[188:191], v[62:65]
	v_mfma_f32_16x16x32_bf16 v[58:61], v[164:167], v[188:191], v[58:61]
	v_mfma_f32_16x16x32_bf16 v[46:49], v[154:157], v[196:199], v[46:49]
	v_mfma_f32_16x16x32_bf16 v[42:45], v[164:167], v[196:199], v[42:45]
	s_barrier
	s_setprio 1
	v_mfma_f32_16x16x32_bf16 v[30:33], v[154:157], v[204:207], v[30:33]
	v_mfma_f32_16x16x32_bf16 v[26:29], v[164:167], v[204:207], v[26:29]
	v_mfma_f32_16x16x32_bf16 v[14:17], v[154:157], v[212:215], v[14:17]
	v_mfma_f32_16x16x32_bf16 v[10:13], v[164:167], v[212:215], v[10:13]
	v_mfma_f32_16x16x32_bf16 v[62:65], v[158:161], v[192:195], v[62:65]
	v_mfma_f32_16x16x32_bf16 v[58:61], v[168:171], v[192:195], v[58:61]
	v_mfma_f32_16x16x32_bf16 v[46:49], v[158:161], v[200:203], v[46:49]
	v_mfma_f32_16x16x32_bf16 v[42:45], v[168:171], v[200:203], v[42:45]
	v_mfma_f32_16x16x32_bf16 v[30:33], v[158:161], v[208:211], v[30:33]
	v_mfma_f32_16x16x32_bf16 v[26:29], v[168:171], v[208:211], v[26:29]
	v_mfma_f32_16x16x32_bf16 v[14:17], v[158:161], v[216:219], v[14:17]
	v_mfma_f32_16x16x32_bf16 v[10:13], v[168:171], v[216:219], v[10:13]
	v_mfma_f32_16x16x32_bf16 v[54:57], v[172:175], v[188:191], v[54:57]
	v_mfma_f32_16x16x32_bf16 v[50:53], v[180:183], v[188:191], v[50:53]
	v_mfma_f32_16x16x32_bf16 v[38:41], v[172:175], v[196:199], v[38:41]
	v_mfma_f32_16x16x32_bf16 v[34:37], v[180:183], v[196:199], v[34:37]
	v_mfma_f32_16x16x32_bf16 v[22:25], v[172:175], v[204:207], v[22:25]
	v_mfma_f32_16x16x32_bf16 v[18:21], v[180:183], v[204:207], v[18:21]
	v_mfma_f32_16x16x32_bf16 v[6:9], v[172:175], v[212:215], v[6:9]
	v_mfma_f32_16x16x32_bf16 v[2:5], v[180:183], v[212:215], v[2:5]
	v_mfma_f32_16x16x32_bf16 v[54:57], v[176:179], v[192:195], v[54:57]
	v_mfma_f32_16x16x32_bf16 v[50:53], v[184:187], v[192:195], v[50:53]
	v_mfma_f32_16x16x32_bf16 v[38:41], v[176:179], v[200:203], v[38:41]
	v_mfma_f32_16x16x32_bf16 v[34:37], v[184:187], v[200:203], v[34:37]
	v_mfma_f32_16x16x32_bf16 v[22:25], v[176:179], v[208:211], v[22:25]
	v_mfma_f32_16x16x32_bf16 v[18:21], v[184:187], v[208:211], v[18:21]
	v_mfma_f32_16x16x32_bf16 v[6:9], v[176:179], v[216:219], v[6:9]
	v_mfma_f32_16x16x32_bf16 v[2:5], v[184:187], v[216:219], v[2:5]
	s_setprio 0
	s_barrier
	s_add_i32 s53, s53, 2
	s_add_u32 s34, s34, 0x100
	s_addc_u32 s35, s35, 0
	s_add_u32 s23, s23, 0x100
	s_addc_u32 s25, s25, 0
	s_cmp_gt_u32 s53, 29
	s_cbranch_scc0 .LBB0_1604
	s_and_b64 vcc, exec, s[12:13]
	s_cbranch_vccz .LBB0_1607
	s_barrier

.LBB0_1675:
	ds_read_b128 v[156:159], v191
	ds_read_b128 v[160:163], v191 offset:1024
	ds_read_b128 v[164:167], v191 offset:2048
	ds_read_b128 v[168:171], v191 offset:3072
	ds_read_b128 v[172:175], v192
	ds_read_b128 v[176:179], v192 offset:1024
	ds_read_b128 v[180:183], v192 offset:2048
	ds_read_b128 v[184:187], v192 offset:3072
	s_add_u32 s36, s30, 0xffea0080
	s_addc_u32 s37, s31, -1
	s_cmpk_eq_i32 s29, 0x54
	s_cselect_b32 s39, s25, s37
	s_cselect_b32 s38, s24, s36
	s_cselect_b32 s37, s5, s35
	s_cselect_b32 s36, s4, s34
	s_mov_b32 m0, s57
	v_lshl_add_u64 v[234:235], s[30:31], 0, v[150:151]
	ds_read_b128 v[202:205], v193
	ds_read_b128 v[206:209], v193 offset:1024
	ds_read_b128 v[210:213], v193 offset:2048
	ds_read_b128 v[214:217], v193 offset:3072
	ds_read_b128 v[218:221], v193 offset:4096
	ds_read_b128 v[222:225], v193 offset:5120
	ds_read_b128 v[226:229], v193 offset:6144
	ds_read_b128 v[230:233], v193 offset:7168
	global_load_lds_dwordx4 v[234:235], off
	v_lshl_add_u64 v[234:235], s[30:31], 0, v[152:153]
	s_mov_b32 m0, s58
	s_nop 0
	global_load_lds_dwordx4 v[234:235], off
	s_waitcnt vmcnt(8)
	s_waitcnt lgkmcnt(0)
	s_waitcnt lgkmcnt(0)
	v_mfma_f32_16x16x32_bf16 v[126:129], v[156:159], v[202:205], v[126:129]
	v_mfma_f32_16x16x32_bf16 v[122:125], v[164:167], v[202:205], v[122:125]
	v_mfma_f32_16x16x32_bf16 v[110:113], v[156:159], v[210:213], v[110:113]
	v_mfma_f32_16x16x32_bf16 v[106:109], v[164:167], v[210:213], v[106:109]
	s_barrier
	s_setprio 1
	v_mfma_f32_16x16x32_bf16 v[94:97], v[156:159], v[218:221], v[94:97]
	v_mfma_f32_16x16x32_bf16 v[90:93], v[164:167], v[218:221], v[90:93]
	v_mfma_f32_16x16x32_bf16 v[78:81], v[156:159], v[226:229], v[78:81]
	v_mfma_f32_16x16x32_bf16 v[74:77], v[164:167], v[226:229], v[74:77]
	v_mfma_f32_16x16x32_bf16 v[126:129], v[160:163], v[206:209], v[126:129]
	v_mfma_f32_16x16x32_bf16 v[122:125], v[168:171], v[206:209], v[122:125]
	v_mfma_f32_16x16x32_bf16 v[110:113], v[160:163], v[214:217], v[110:113]
	v_mfma_f32_16x16x32_bf16 v[106:109], v[168:171], v[214:217], v[106:109]
	v_mfma_f32_16x16x32_bf16 v[94:97], v[160:163], v[222:225], v[94:97]
	v_mfma_f32_16x16x32_bf16 v[90:93], v[168:171], v[222:225], v[90:93]
	v_mfma_f32_16x16x32_bf16 v[78:81], v[160:163], v[230:233], v[78:81]
	v_mfma_f32_16x16x32_bf16 v[74:77], v[168:171], v[230:233], v[74:77]
	v_mfma_f32_16x16x32_bf16 v[118:121], v[172:175], v[202:205], v[118:121]
	v_mfma_f32_16x16x32_bf16 v[114:117], v[180:183], v[202:205], v[114:117]
	v_mfma_f32_16x16x32_bf16 v[102:105], v[172:175], v[210:213], v[102:105]
	v_mfma_f32_16x16x32_bf16 v[98:101], v[180:183], v[210:213], v[98:101]
	v_mfma_f32_16x16x32_bf16 v[86:89], v[172:175], v[218:221], v[86:89]
	v_mfma_f32_16x16x32_bf16 v[82:85], v[180:183], v[218:221], v[82:85]
	v_mfma_f32_16x16x32_bf16 v[70:73], v[172:175], v[226:229], v[70:73]
	v_mfma_f32_16x16x32_bf16 v[66:69], v[180:183], v[226:229], v[66:69]
	v_mfma_f32_16x16x32_bf16 v[118:121], v[176:179], v[206:209], v[118:121]
	v_mfma_f32_16x16x32_bf16 v[114:117], v[184:187], v[206:209], v[114:117]
	v_mfma_f32_16x16x32_bf16 v[102:105], v[176:179], v[214:217], v[102:105]
	v_mfma_f32_16x16x32_bf16 v[98:101], v[184:187], v[214:217], v[98:101]
	v_mfma_f32_16x16x32_bf16 v[86:89], v[176:179], v[222:225], v[86:89]
	v_mfma_f32_16x16x32_bf16 v[82:85], v[184:187], v[222:225], v[82:85]
	v_mfma_f32_16x16x32_bf16 v[70:73], v[176:179], v[230:233], v[70:73]
	v_mfma_f32_16x16x32_bf16 v[66:69], v[184:187], v[230:233], v[66:69]
	s_setprio 0
	s_barrier
	s_mov_b32 m0, s59
	v_lshl_add_u64 v[234:235], s[36:37], 0, v[134:135]
	s_add_u32 s40, s36, 0x160000
	ds_read_b128 v[202:205], v193 offset:16384
	ds_read_b128 v[206:209], v193 offset:17408
	ds_read_b128 v[210:213], v193 offset:18432
	ds_read_b128 v[214:217], v193 offset:19456
	ds_read_b128 v[218:221], v193 offset:20480
	ds_read_b128 v[222:225], v193 offset:21504
	ds_read_b128 v[226:229], v193 offset:22528
	ds_read_b128 v[230:233], v193 offset:23552
	global_load_lds_dwordx4 v[234:235], off
	v_lshl_add_u64 v[236:237], s[36:37], 0, v[130:131]
	s_mov_b32 m0, s60
	s_addc_u32 s41, s37, 0
	global_load_lds_dwordx4 v[236:237], off
	v_lshl_add_u64 v[238:239], s[40:41], 0, v[134:135]
	s_mov_b32 m0, s61
	v_lshl_add_u64 v[240:241], s[38:39], 0, v[132:133]
	global_load_lds_dwordx4 v[238:239], off
	v_lshl_add_u64 v[238:239], s[40:41], 0, v[130:131]
	s_mov_b32 m0, s62
	s_nop 0
	global_load_lds_dwordx4 v[238:239], off
	v_lshl_add_u64 v[238:239], s[38:39], 0, v[136:137]
	s_mov_b32 m0, s48
	s_nop 0
	global_load_lds_dwordx4 v[238:239], off
	s_mov_b32 m0, s49
	s_nop 0
	global_load_lds_dwordx4 v[240:241], off
	s_waitcnt vmcnt(8)
	s_waitcnt lgkmcnt(0)
	s_waitcnt lgkmcnt(0)
	v_mfma_f32_16x16x32_bf16 v[62:65], v[156:159], v[202:205], v[62:65]
	v_mfma_f32_16x16x32_bf16 v[58:61], v[164:167], v[202:205], v[58:61]
	v_mfma_f32_16x16x32_bf16 v[46:49], v[156:159], v[210:213], v[46:49]
	v_mfma_f32_16x16x32_bf16 v[42:45], v[164:167], v[210:213], v[42:45]
	s_barrier
	s_setprio 1
	v_mfma_f32_16x16x32_bf16 v[30:33], v[156:159], v[218:221], v[30:33]
	v_mfma_f32_16x16x32_bf16 v[26:29], v[164:167], v[218:221], v[26:29]
	v_mfma_f32_16x16x32_bf16 v[14:17], v[156:159], v[226:229], v[14:17]
	v_mfma_f32_16x16x32_bf16 v[10:13], v[164:167], v[226:229], v[10:13]
	v_mfma_f32_16x16x32_bf16 v[62:65], v[160:163], v[206:209], v[62:65]
	v_mfma_f32_16x16x32_bf16 v[58:61], v[168:171], v[206:209], v[58:61]
	v_mfma_f32_16x16x32_bf16 v[46:49], v[160:163], v[214:217], v[46:49]
	v_mfma_f32_16x16x32_bf16 v[42:45], v[168:171], v[214:217], v[42:45]
	v_mfma_f32_16x16x32_bf16 v[30:33], v[160:163], v[222:225], v[30:33]
	v_mfma_f32_16x16x32_bf16 v[26:29], v[168:171], v[222:225], v[26:29]
	v_mfma_f32_16x16x32_bf16 v[14:17], v[160:163], v[230:233], v[14:17]
	v_mfma_f32_16x16x32_bf16 v[10:13], v[168:171], v[230:233], v[10:13]
	v_mfma_f32_16x16x32_bf16 v[54:57], v[172:175], v[202:205], v[54:57]
	v_mfma_f32_16x16x32_bf16 v[50:53], v[180:183], v[202:205], v[50:53]
	v_mfma_f32_16x16x32_bf16 v[38:41], v[172:175], v[210:213], v[38:41]
	v_mfma_f32_16x16x32_bf16 v[34:37], v[180:183], v[210:213], v[34:37]
	v_mfma_f32_16x16x32_bf16 v[22:25], v[172:175], v[218:221], v[22:25]
	v_mfma_f32_16x16x32_bf16 v[18:21], v[180:183], v[218:221], v[18:21]
	v_mfma_f32_16x16x32_bf16 v[6:9], v[172:175], v[226:229], v[6:9]
	v_mfma_f32_16x16x32_bf16 v[2:5], v[180:183], v[226:229], v[2:5]
	v_mfma_f32_16x16x32_bf16 v[54:57], v[176:179], v[206:209], v[54:57]
	v_mfma_f32_16x16x32_bf16 v[50:53], v[184:187], v[206:209], v[50:53]
	v_mfma_f32_16x16x32_bf16 v[38:41], v[176:179], v[214:217], v[38:41]
	v_mfma_f32_16x16x32_bf16 v[34:37], v[184:187], v[214:217], v[34:37]
	v_mfma_f32_16x16x32_bf16 v[22:25], v[176:179], v[222:225], v[22:25]
	v_mfma_f32_16x16x32_bf16 v[18:21], v[184:187], v[222:225], v[18:21]
	v_mfma_f32_16x16x32_bf16 v[6:9], v[176:179], v[230:233], v[6:9]
	v_mfma_f32_16x16x32_bf16 v[2:5], v[184:187], v[230:233], v[2:5]
	s_setprio 0
	s_barrier
	ds_read_b128 v[156:159], v197
	ds_read_b128 v[160:163], v197 offset:1024
	ds_read_b128 v[164:167], v197 offset:2048
	ds_read_b128 v[168:171], v197 offset:3072
	ds_read_b128 v[172:175], v198
	ds_read_b128 v[176:179], v198 offset:1024
	ds_read_b128 v[180:183], v198 offset:2048
	ds_read_b128 v[184:187], v198 offset:3072
	s_add_u32 s38, s38, 0x160000
	s_addc_u32 s39, s39, 0
	s_mov_b32 m0, s50
	v_lshl_add_u64 v[242:243], s[38:39], 0, v[136:137]
	ds_read_b128 v[202:205], v193 offset:32768
	ds_read_b128 v[206:209], v193 offset:33792
	ds_read_b128 v[210:213], v193 offset:34816
	ds_read_b128 v[214:217], v193 offset:35840
	ds_read_b128 v[218:221], v193 offset:36864
	ds_read_b128 v[222:225], v193 offset:37888
	ds_read_b128 v[226:229], v193 offset:38912
	ds_read_b128 v[230:233], v193 offset:39936
	global_load_lds_dwordx4 v[242:243], off
	v_lshl_add_u64 v[242:243], s[38:39], 0, v[132:133]
	s_mov_b32 m0, s51
	s_nop 0
	global_load_lds_dwordx4 v[242:243], off
	s_waitcnt vmcnt(8)
	s_waitcnt lgkmcnt(0)
	s_waitcnt lgkmcnt(0)
	v_mfma_f32_16x16x32_bf16 v[126:129], v[156:159], v[202:205], v[126:129]
	v_mfma_f32_16x16x32_bf16 v[122:125], v[164:167], v[202:205], v[122:125]
	v_mfma_f32_16x16x32_bf16 v[110:113], v[156:159], v[210:213], v[110:113]
	v_mfma_f32_16x16x32_bf16 v[106:109], v[164:167], v[210:213], v[106:109]
	s_barrier
	s_setprio 1
	v_mfma_f32_16x16x32_bf16 v[94:97], v[156:159], v[218:221], v[94:97]
	v_mfma_f32_16x16x32_bf16 v[90:93], v[164:167], v[218:221], v[90:93]
	v_mfma_f32_16x16x32_bf16 v[78:81], v[156:159], v[226:229], v[78:81]
	v_mfma_f32_16x16x32_bf16 v[74:77], v[164:167], v[226:229], v[74:77]
	v_mfma_f32_16x16x32_bf16 v[126:129], v[160:163], v[206:209], v[126:129]
	v_mfma_f32_16x16x32_bf16 v[122:125], v[168:171], v[206:209], v[122:125]
	v_mfma_f32_16x16x32_bf16 v[110:113], v[160:163], v[214:217], v[110:113]
	v_mfma_f32_16x16x32_bf16 v[106:109], v[168:171], v[214:217], v[106:109]
	v_mfma_f32_16x16x32_bf16 v[94:97], v[160:163], v[222:225], v[94:97]
	v_mfma_f32_16x16x32_bf16 v[90:93], v[168:171], v[222:225], v[90:93]
	v_mfma_f32_16x16x32_bf16 v[78:81], v[160:163], v[230:233], v[78:81]
	v_mfma_f32_16x16x32_bf16 v[74:77], v[168:171], v[230:233], v[74:77]
	v_mfma_f32_16x16x32_bf16 v[118:121], v[172:175], v[202:205], v[118:121]
	v_mfma_f32_16x16x32_bf16 v[114:117], v[180:183], v[202:205], v[114:117]
	v_mfma_f32_16x16x32_bf16 v[102:105], v[172:175], v[210:213], v[102:105]
	v_mfma_f32_16x16x32_bf16 v[98:101], v[180:183], v[210:213], v[98:101]
	v_mfma_f32_16x16x32_bf16 v[86:89], v[172:175], v[218:221], v[86:89]
	v_mfma_f32_16x16x32_bf16 v[82:85], v[180:183], v[218:221], v[82:85]
	v_mfma_f32_16x16x32_bf16 v[70:73], v[172:175], v[226:229], v[70:73]
	v_mfma_f32_16x16x32_bf16 v[66:69], v[180:183], v[226:229], v[66:69]
	v_mfma_f32_16x16x32_bf16 v[118:121], v[176:179], v[206:209], v[118:121]
	v_mfma_f32_16x16x32_bf16 v[114:117], v[184:187], v[206:209], v[114:117]
	v_mfma_f32_16x16x32_bf16 v[102:105], v[176:179], v[214:217], v[102:105]
	v_mfma_f32_16x16x32_bf16 v[98:101], v[184:187], v[214:217], v[98:101]
	v_mfma_f32_16x16x32_bf16 v[86:89], v[176:179], v[222:225], v[86:89]
	v_mfma_f32_16x16x32_bf16 v[82:85], v[184:187], v[222:225], v[82:85]
	v_mfma_f32_16x16x32_bf16 v[70:73], v[176:179], v[230:233], v[70:73]
	v_mfma_f32_16x16x32_bf16 v[66:69], v[184:187], v[230:233], v[66:69]
	s_setprio 0
	s_barrier
	s_mov_b32 m0, s64
	v_lshl_add_u64 v[234:235], v[234:235], 0, s[12:13]
	s_add_u32 s36, s36, 0x160080
	ds_read_b128 v[202:205], v193 offset:49152
	ds_read_b128 v[206:209], v193 offset:50176
	ds_read_b128 v[210:213], v193 offset:51200
	ds_read_b128 v[214:217], v193 offset:52224
	ds_read_b128 v[218:221], v193 offset:53248
	ds_read_b128 v[222:225], v193 offset:54272
	ds_read_b128 v[226:229], v193 offset:55296
	ds_read_b128 v[230:233], v193 offset:56320
	global_load_lds_dwordx4 v[234:235], off
	v_lshl_add_u64 v[234:235], v[236:237], 0, s[12:13]
	s_mov_b32 m0, s65
	s_addc_u32 s37, s37, 0
	s_add_i32 s38, s63, s47
	global_load_lds_dwordx4 v[234:235], off
	v_lshl_add_u64 v[234:235], s[36:37], 0, v[134:135]
	s_mov_b32 m0, s38
	s_nop 0
	global_load_lds_dwordx4 v[234:235], off
	v_lshl_add_u64 v[234:235], s[36:37], 0, v[130:131]
	s_add_i32 m0, s38, 0x2000
	s_nop 0
	global_load_lds_dwordx4 v[234:235], off
	v_lshl_add_u64 v[234:235], v[238:239], 0, s[12:13]
	s_mov_b32 m0, s55
	s_nop 0
	global_load_lds_dwordx4 v[234:235], off
	v_lshl_add_u64 v[234:235], v[240:241], 0, s[12:13]
	s_mov_b32 m0, s56
	s_nop 0
	global_load_lds_dwordx4 v[234:235], off
	s_waitcnt vmcnt(8)
	s_waitcnt lgkmcnt(0)
	s_waitcnt lgkmcnt(0)
	v_mfma_f32_16x16x32_bf16 v[62:65], v[156:159], v[202:205], v[62:65]
	v_mfma_f32_16x16x32_bf16 v[58:61], v[164:167], v[202:205], v[58:61]
	v_mfma_f32_16x16x32_bf16 v[46:49], v[156:159], v[210:213], v[46:49]
	v_mfma_f32_16x16x32_bf16 v[42:45], v[164:167], v[210:213], v[42:45]
	s_barrier
	s_setprio 1
	v_mfma_f32_16x16x32_bf16 v[30:33], v[156:159], v[218:221], v[30:33]
	v_mfma_f32_16x16x32_bf16 v[26:29], v[164:167], v[218:221], v[26:29]
	v_mfma_f32_16x16x32_bf16 v[14:17], v[156:159], v[226:229], v[14:17]
	v_mfma_f32_16x16x32_bf16 v[10:13], v[164:167], v[226:229], v[10:13]
	v_mfma_f32_16x16x32_bf16 v[62:65], v[160:163], v[206:209], v[62:65]
	v_mfma_f32_16x16x32_bf16 v[58:61], v[168:171], v[206:209], v[58:61]
	v_mfma_f32_16x16x32_bf16 v[46:49], v[160:163], v[214:217], v[46:49]
	v_mfma_f32_16x16x32_bf16 v[42:45], v[168:171], v[214:217], v[42:45]
	v_mfma_f32_16x16x32_bf16 v[30:33], v[160:163], v[222:225], v[30:33]
	v_mfma_f32_16x16x32_bf16 v[26:29], v[168:171], v[222:225], v[26:29]
	v_mfma_f32_16x16x32_bf16 v[14:17], v[160:163], v[230:233], v[14:17]
	v_mfma_f32_16x16x32_bf16 v[10:13], v[168:171], v[230:233], v[10:13]
	v_mfma_f32_16x16x32_bf16 v[54:57], v[172:175], v[202:205], v[54:57]
	v_mfma_f32_16x16x32_bf16 v[50:53], v[180:183], v[202:205], v[50:53]
	v_mfma_f32_16x16x32_bf16 v[38:41], v[172:175], v[210:213], v[38:41]
	v_mfma_f32_16x16x32_bf16 v[34:37], v[180:183], v[210:213], v[34:37]
	v_mfma_f32_16x16x32_bf16 v[22:25], v[172:175], v[218:221], v[22:25]
	v_mfma_f32_16x16x32_bf16 v[18:21], v[180:183], v[218:221], v[18:21]
	v_mfma_f32_16x16x32_bf16 v[6:9], v[172:175], v[226:229], v[6:9]
	v_mfma_f32_16x16x32_bf16 v[2:5], v[180:183], v[226:229], v[2:5]
	v_mfma_f32_16x16x32_bf16 v[54:57], v[176:179], v[206:209], v[54:57]
	v_mfma_f32_16x16x32_bf16 v[50:53], v[184:187], v[206:209], v[50:53]
	v_mfma_f32_16x16x32_bf16 v[38:41], v[176:179], v[214:217], v[38:41]
	v_mfma_f32_16x16x32_bf16 v[34:37], v[184:187], v[214:217], v[34:37]
	v_mfma_f32_16x16x32_bf16 v[22:25], v[176:179], v[222:225], v[22:25]
	v_mfma_f32_16x16x32_bf16 v[18:21], v[184:187], v[222:225], v[18:21]
	v_mfma_f32_16x16x32_bf16 v[6:9], v[176:179], v[230:233], v[6:9]
	v_mfma_f32_16x16x32_bf16 v[2:5], v[184:187], v[230:233], v[2:5]
	s_setprio 0
	s_barrier
	s_add_i32 s29, s29, 2
	s_add_u32 s30, s30, 0x100
	s_addc_u32 s31, s31, 0
	s_add_u32 s34, s34, 0x100
	s_addc_u32 s35, s35, 0
	s_cmpk_gt_u32 s29, 0x55
	s_cbranch_scc0 .LBB0_1675
	s_and_b64 vcc, exec, s[14:15]
	s_cbranch_vccz .LBB0_1678
	s_barrier
